# hand-written scan phase; batched residual epilogues; split-K partials+group reduce instead of atomics
# speedup vs baseline: 1.0745x; 1.0685x over previous
.LBB0_31:
	s_or_b64 exec, exec, s[4:5]
	s_ashr_i32 s0, s23, 13
	s_mulk_i32 s0, 0x1800
	s_ashr_i32 s1, s0, 31
	s_lshl_b64 s[0:1], s[0:1], 2
	s_add_u32 s0, s16, s0
	s_addc_u32 s1, s17, s1
	v_lshlrev_b32_e32 v160, 2, v146
	v_lshl_or_b32 v160, v145, 5, v160
	v_lshl_or_b32 v160, s22, 8, v160
	v_lshlrev_b32_e32 v237, 2, v160
	v_add_u32_e32 v236, s23, v147
	v_lshl_add_u32 v238, v236, 12, v237
	global_load_dwordx4 v[128:131], v237, s[0:1]
	global_load_dwordx4 v[132:135], v237, s[0:1] offset:64
	global_load_dwordx4 v[136:139], v237, s[0:1] offset:512
	global_load_dwordx4 v[140:143], v237, s[0:1] offset:576
	v_mov_b32_e32 v160, v238
	global_load_dwordx4 v[144:147], v160, s[58:59]
	global_load_dwordx4 v[148:151], v160, s[58:59] offset:64
	global_load_dwordx4 v[152:155], v160, s[58:59] offset:512
	global_load_dwordx4 v[156:159], v160, s[58:59] offset:576
	v_add_u32_e32 v160, 0x10000, v238
	global_load_dwordx4 v[164:167], v160, s[58:59]
	global_load_dwordx4 v[168:171], v160, s[58:59] offset:64
	global_load_dwordx4 v[172:175], v160, s[58:59] offset:512
	global_load_dwordx4 v[198:201], v160, s[58:59] offset:576
	v_add_u32_e32 v160, 0x20000, v238
	global_load_dwordx4 v[202:205], v160, s[58:59]
	global_load_dwordx4 v[206:209], v160, s[58:59] offset:64
	global_load_dwordx4 v[210:213], v160, s[58:59] offset:512
	global_load_dwordx4 v[214:217], v160, s[58:59] offset:576
	v_add_u32_e32 v160, 0x30000, v238
	global_load_dwordx4 v[218:221], v160, s[58:59]
	global_load_dwordx4 v[222:225], v160, s[58:59] offset:64
	global_load_dwordx4 v[226:229], v160, s[58:59] offset:512
	global_load_dwordx4 v[232:235], v160, s[58:59] offset:576
	v_mov_b32_e32 v252, 0x358637bd
	v_mov_b32_e32 v250, v246
	v_not_b32_e32 v246, 31
	v_mov_b32_e32 v251, 0x7fc00000
	s_waitcnt vmcnt(0)
	v_mov_b32_e32 v160, v238
	v_add_u32_e32 v236, 0x80000, v238
	v_pk_fma_f32 v[124:125], v[124:125], v[128:129], v[144:145]
	v_pk_fma_f32 v[126:127], v[126:127], v[130:131], v[146:147]
	global_store_dwordx4 v160, v[124:127], s[44:45]
	global_load_dwordx4 v[144:147], v236, s[58:59]
	v_pk_fma_f32 v[116:117], v[116:117], v[132:133], v[148:149]
	v_pk_fma_f32 v[118:119], v[118:119], v[134:135], v[150:151]
	global_store_dwordx4 v160, v[116:119], s[44:45] offset:64
	global_load_dwordx4 v[148:151], v236, s[58:59] offset:64
	v_pk_fma_f32 v[120:121], v[120:121], v[136:137], v[152:153]
	v_pk_fma_f32 v[122:123], v[122:123], v[138:139], v[154:155]
	global_store_dwordx4 v160, v[120:123], s[44:45] offset:512
	global_load_dwordx4 v[152:155], v236, s[58:59] offset:512
	v_pk_fma_f32 v[112:113], v[112:113], v[140:141], v[156:157]
	v_pk_fma_f32 v[114:115], v[114:115], v[142:143], v[158:159]
	global_store_dwordx4 v160, v[112:115], s[44:45] offset:576
	global_load_dwordx4 v[156:159], v236, s[58:59] offset:576
	v_add_u32_e32 v160, 0x10000, v238
	v_add_u32_e32 v236, 0x90000, v238
	v_pk_fma_f32 v[108:109], v[108:109], v[128:129], v[164:165]
	v_pk_fma_f32 v[110:111], v[110:111], v[130:131], v[166:167]
	global_store_dwordx4 v160, v[108:111], s[44:45]
	global_load_dwordx4 v[164:167], v236, s[58:59]
	v_pk_fma_f32 v[100:101], v[100:101], v[132:133], v[168:169]
	v_pk_fma_f32 v[102:103], v[102:103], v[134:135], v[170:171]
	global_store_dwordx4 v160, v[100:103], s[44:45] offset:64
	global_load_dwordx4 v[168:171], v236, s[58:59] offset:64
	v_pk_fma_f32 v[104:105], v[104:105], v[136:137], v[172:173]
	v_pk_fma_f32 v[106:107], v[106:107], v[138:139], v[174:175]
	global_store_dwordx4 v160, v[104:107], s[44:45] offset:512
	global_load_dwordx4 v[172:175], v236, s[58:59] offset:512
	v_pk_fma_f32 v[96:97], v[96:97], v[140:141], v[198:199]
	v_pk_fma_f32 v[98:99], v[98:99], v[142:143], v[200:201]
	global_store_dwordx4 v160, v[96:99], s[44:45] offset:576
	global_load_dwordx4 v[198:201], v236, s[58:59] offset:576
	v_add_u32_e32 v160, 0x20000, v238
	v_add_u32_e32 v236, 0xa0000, v238
	v_pk_fma_f32 v[92:93], v[92:93], v[128:129], v[202:203]
	v_pk_fma_f32 v[94:95], v[94:95], v[130:131], v[204:205]
	global_store_dwordx4 v160, v[92:95], s[44:45]
	global_load_dwordx4 v[202:205], v236, s[58:59]
	v_pk_fma_f32 v[84:85], v[84:85], v[132:133], v[206:207]
	v_pk_fma_f32 v[86:87], v[86:87], v[134:135], v[208:209]
	global_store_dwordx4 v160, v[84:87], s[44:45] offset:64
	global_load_dwordx4 v[206:209], v236, s[58:59] offset:64
	v_pk_fma_f32 v[88:89], v[88:89], v[136:137], v[210:211]
	v_pk_fma_f32 v[90:91], v[90:91], v[138:139], v[212:213]
	global_store_dwordx4 v160, v[88:91], s[44:45] offset:512
	global_load_dwordx4 v[210:213], v236, s[58:59] offset:512
	v_pk_fma_f32 v[80:81], v[80:81], v[140:141], v[214:215]
	v_pk_fma_f32 v[82:83], v[82:83], v[142:143], v[216:217]
	global_store_dwordx4 v160, v[80:83], s[44:45] offset:576
	global_load_dwordx4 v[214:217], v236, s[58:59] offset:576
	v_add_u32_e32 v160, 0x30000, v238
	v_add_u32_e32 v236, 0xb0000, v238
	v_pk_fma_f32 v[76:77], v[76:77], v[128:129], v[218:219]
	v_pk_fma_f32 v[78:79], v[78:79], v[130:131], v[220:221]
	global_store_dwordx4 v160, v[76:79], s[44:45]
	global_load_dwordx4 v[218:221], v236, s[58:59]
	v_pk_fma_f32 v[68:69], v[68:69], v[132:133], v[222:223]
	v_pk_fma_f32 v[70:71], v[70:71], v[134:135], v[224:225]
	global_store_dwordx4 v160, v[68:71], s[44:45] offset:64
	global_load_dwordx4 v[222:225], v236, s[58:59] offset:64
	v_pk_fma_f32 v[72:73], v[72:73], v[136:137], v[226:227]
	v_pk_fma_f32 v[74:75], v[74:75], v[138:139], v[228:229]
	global_store_dwordx4 v160, v[72:75], s[44:45] offset:512
	global_load_dwordx4 v[226:229], v236, s[58:59] offset:512
	v_pk_fma_f32 v[60:61], v[60:61], v[140:141], v[232:233]
	v_pk_fma_f32 v[62:63], v[62:63], v[142:143], v[234:235]
	global_store_dwordx4 v160, v[60:63], s[44:45] offset:576
	global_load_dwordx4 v[232:235], v236, s[58:59] offset:576
	v_add_u32_e32 v236, 0x80000, v238
	s_waitcnt vmcnt(30)
	v_pk_fma_f32 v[64:65], v[64:65], v[128:129], v[144:145]
	v_pk_fma_f32 v[66:67], v[66:67], v[130:131], v[146:147]
	global_store_dwordx4 v236, v[64:67], s[44:45]
	s_waitcnt vmcnt(29)
	v_pk_fma_f32 v[52:53], v[52:53], v[132:133], v[148:149]
	v_pk_fma_f32 v[54:55], v[54:55], v[134:135], v[150:151]
	global_store_dwordx4 v236, v[52:55], s[44:45] offset:64
	s_waitcnt vmcnt(28)
	v_pk_fma_f32 v[56:57], v[56:57], v[136:137], v[152:153]
	v_pk_fma_f32 v[58:59], v[58:59], v[138:139], v[154:155]
	global_store_dwordx4 v236, v[56:59], s[44:45] offset:512
	s_waitcnt vmcnt(27)
	v_pk_fma_f32 v[48:49], v[48:49], v[140:141], v[156:157]
	v_pk_fma_f32 v[50:51], v[50:51], v[142:143], v[158:159]
	global_store_dwordx4 v236, v[48:51], s[44:45] offset:576
	v_add_u32_e32 v236, 0x90000, v238
	s_waitcnt vmcnt(26)
	v_pk_fma_f32 v[44:45], v[44:45], v[128:129], v[164:165]
	v_pk_fma_f32 v[46:47], v[46:47], v[130:131], v[166:167]
	global_store_dwordx4 v236, v[44:47], s[44:45]
	s_waitcnt vmcnt(25)
	v_pk_fma_f32 v[36:37], v[36:37], v[132:133], v[168:169]
	v_pk_fma_f32 v[38:39], v[38:39], v[134:135], v[170:171]
	global_store_dwordx4 v236, v[36:39], s[44:45] offset:64
	s_waitcnt vmcnt(24)
	v_pk_fma_f32 v[40:41], v[40:41], v[136:137], v[172:173]
	v_pk_fma_f32 v[42:43], v[42:43], v[138:139], v[174:175]
	global_store_dwordx4 v236, v[40:43], s[44:45] offset:512
	s_waitcnt vmcnt(23)
	v_pk_fma_f32 v[32:33], v[32:33], v[140:141], v[198:199]
	v_pk_fma_f32 v[34:35], v[34:35], v[142:143], v[200:201]
	global_store_dwordx4 v236, v[32:35], s[44:45] offset:576
	v_add_u32_e32 v236, 0xa0000, v238
	s_waitcnt vmcnt(22)
	v_pk_fma_f32 v[28:29], v[28:29], v[128:129], v[202:203]
	v_pk_fma_f32 v[30:31], v[30:31], v[130:131], v[204:205]
	global_store_dwordx4 v236, v[28:31], s[44:45]
	s_waitcnt vmcnt(21)
	v_pk_fma_f32 v[20:21], v[20:21], v[132:133], v[206:207]
	v_pk_fma_f32 v[22:23], v[22:23], v[134:135], v[208:209]
	global_store_dwordx4 v236, v[20:23], s[44:45] offset:64
	s_waitcnt vmcnt(20)
	v_pk_fma_f32 v[24:25], v[24:25], v[136:137], v[210:211]
	v_pk_fma_f32 v[26:27], v[26:27], v[138:139], v[212:213]
	global_store_dwordx4 v236, v[24:27], s[44:45] offset:512
	s_waitcnt vmcnt(19)
	v_pk_fma_f32 v[16:17], v[16:17], v[140:141], v[214:215]
	v_pk_fma_f32 v[18:19], v[18:19], v[142:143], v[216:217]
	global_store_dwordx4 v236, v[16:19], s[44:45] offset:576
	v_add_u32_e32 v236, 0xb0000, v238
	s_waitcnt vmcnt(18)
	v_pk_fma_f32 v[12:13], v[12:13], v[128:129], v[218:219]
	v_pk_fma_f32 v[14:15], v[14:15], v[130:131], v[220:221]
	global_store_dwordx4 v236, v[12:15], s[44:45]
	s_waitcnt vmcnt(17)
	v_pk_fma_f32 v[4:5], v[4:5], v[132:133], v[222:223]
	v_pk_fma_f32 v[6:7], v[6:7], v[134:135], v[224:225]
	global_store_dwordx4 v236, v[4:7], s[44:45] offset:64
	s_waitcnt vmcnt(16)
	v_pk_fma_f32 v[8:9], v[8:9], v[136:137], v[226:227]
	v_pk_fma_f32 v[10:11], v[10:11], v[138:139], v[228:229]
	global_store_dwordx4 v236, v[8:11], s[44:45] offset:512
	s_waitcnt vmcnt(15)
	v_pk_fma_f32 v[0:1], v[0:1], v[140:141], v[232:233]
	v_pk_fma_f32 v[2:3], v[2:3], v[142:143], v[234:235]
	global_store_dwordx4 v236, v[0:3], s[44:45] offset:576
	s_add_i32 s15, s15, s14
	s_cmpk_gt_i32 s15, 0xff
	s_waitcnt vmcnt(0)
	s_cbranch_scc1 .LBB0_42

.LBB0_63:
	s_or_b64 exec, exec, s[8:9]
	s_ashr_i32 s0, s6, 13
	s_mulk_i32 s0, 0x1800
	s_ashr_i32 s1, s0, 31
	s_lshl_b64 s[0:1], s[0:1], 2
	s_add_u32 s0, s18, s0
	s_addc_u32 s1, s19, s1
	v_lshlrev_b32_e32 v20, 5, v145
	v_lshlrev_b32_e32 v21, 2, v146
	v_or3_b32 v20, v20, v21, s4
	v_lshlrev_b32_e32 v30, 2, v20
	v_add_u32_e32 v21, s6, v147
	v_lshl_add_u32 v31, v21, 12, v30
	global_load_dwordx4 v[26:29], v30, s[0:1]
	global_load_dwordx4 v[138:141], v30, s[0:1] offset:64
	global_load_dwordx4 v[142:145], v30, s[0:1] offset:512
	global_load_dwordx4 v[146:149], v30, s[0:1] offset:576
	v_mov_b32_e32 v20, v31
	global_load_dwordx4 v[150:153], v20, s[58:59]
	global_load_dwordx4 v[154:157], v20, s[58:59] offset:64
	global_load_dwordx4 v[164:167], v20, s[58:59] offset:512
	global_load_dwordx4 v[168:171], v20, s[58:59] offset:576
	v_add_u32_e32 v20, 0x10000, v31
	global_load_dwordx4 v[172:175], v20, s[58:59]
	global_load_dwordx4 v[198:201], v20, s[58:59] offset:64
	global_load_dwordx4 v[202:205], v20, s[58:59] offset:512
	global_load_dwordx4 v[206:209], v20, s[58:59] offset:576
	v_add_u32_e32 v20, 0x20000, v31
	global_load_dwordx4 v[210:213], v20, s[58:59]
	global_load_dwordx4 v[214:217], v20, s[58:59] offset:64
	global_load_dwordx4 v[218:221], v20, s[58:59] offset:512
	global_load_dwordx4 v[222:225], v20, s[58:59] offset:576
	v_add_u32_e32 v20, 0x30000, v31
	global_load_dwordx4 v[226:229], v20, s[58:59]
	global_load_dwordx4 v[232:235], v20, s[58:59] offset:64
	global_load_dwordx4 v[236:239], v20, s[58:59] offset:512
	global_load_dwordx4 v[240:243], v20, s[58:59] offset:576
	v_mov_b32_e32 v252, 0x358637bd
	v_mov_b32_e32 v250, v246
	v_not_b32_e32 v246, 31
	v_mov_b32_e32 v251, 0x7fc00000
	s_waitcnt vmcnt(0)
	v_mov_b32_e32 v20, v31
	v_add_u32_e32 v21, 0x80000, v31
	v_pk_fma_f32 v[134:135], v[134:135], v[26:27], v[150:151]
	v_pk_fma_f32 v[136:137], v[136:137], v[28:29], v[152:153]
	global_store_dwordx4 v20, v[134:137], s[58:59]
	global_load_dwordx4 v[150:153], v21, s[58:59]
	v_pk_fma_f32 v[22:23], v[22:23], v[138:139], v[154:155]
	v_pk_fma_f32 v[24:25], v[24:25], v[140:141], v[156:157]
	global_store_dwordx4 v20, v[22:25], s[58:59] offset:64
	global_load_dwordx4 v[154:157], v21, s[58:59] offset:64
	v_pk_fma_f32 v[4:5], v[4:5], v[142:143], v[164:165]
	v_pk_fma_f32 v[6:7], v[6:7], v[144:145], v[166:167]
	global_store_dwordx4 v20, v[4:7], s[58:59] offset:512
	global_load_dwordx4 v[164:167], v21, s[58:59] offset:512
	v_pk_fma_f32 v[130:131], v[130:131], v[146:147], v[168:169]
	v_pk_fma_f32 v[132:133], v[132:133], v[148:149], v[170:171]
	global_store_dwordx4 v20, v[130:133], s[58:59] offset:576
	global_load_dwordx4 v[168:171], v21, s[58:59] offset:576
	v_add_u32_e32 v20, 0x10000, v31
	v_add_u32_e32 v21, 0x90000, v31
	v_pk_fma_f32 v[126:127], v[126:127], v[26:27], v[172:173]
	v_pk_fma_f32 v[128:129], v[128:129], v[28:29], v[174:175]
	global_store_dwordx4 v20, v[126:129], s[58:59]
	global_load_dwordx4 v[172:175], v21, s[58:59]
	v_pk_fma_f32 v[118:119], v[118:119], v[138:139], v[198:199]
	v_pk_fma_f32 v[120:121], v[120:121], v[140:141], v[200:201]
	global_store_dwordx4 v20, v[118:121], s[58:59] offset:64
	global_load_dwordx4 v[198:201], v21, s[58:59] offset:64
	v_pk_fma_f32 v[122:123], v[122:123], v[142:143], v[202:203]
	v_pk_fma_f32 v[124:125], v[124:125], v[144:145], v[204:205]
	global_store_dwordx4 v20, v[122:125], s[58:59] offset:512
	global_load_dwordx4 v[202:205], v21, s[58:59] offset:512
	v_pk_fma_f32 v[114:115], v[114:115], v[146:147], v[206:207]
	v_pk_fma_f32 v[116:117], v[116:117], v[148:149], v[208:209]
	global_store_dwordx4 v20, v[114:117], s[58:59] offset:576
	global_load_dwordx4 v[206:209], v21, s[58:59] offset:576
	v_add_u32_e32 v20, 0x20000, v31
	v_add_u32_e32 v21, 0xa0000, v31
	v_pk_fma_f32 v[98:99], v[98:99], v[26:27], v[210:211]
	v_pk_fma_f32 v[100:101], v[100:101], v[28:29], v[212:213]
	global_store_dwordx4 v20, v[98:101], s[58:59]
	global_load_dwordx4 v[210:213], v21, s[58:59]
	v_pk_fma_f32 v[102:103], v[102:103], v[138:139], v[214:215]
	v_pk_fma_f32 v[104:105], v[104:105], v[140:141], v[216:217]
	global_store_dwordx4 v20, v[102:105], s[58:59] offset:64
	global_load_dwordx4 v[214:217], v21, s[58:59] offset:64
	v_pk_fma_f32 v[106:107], v[106:107], v[142:143], v[218:219]
	v_pk_fma_f32 v[108:109], v[108:109], v[144:145], v[220:221]
	global_store_dwordx4 v20, v[106:109], s[58:59] offset:512
	global_load_dwordx4 v[218:221], v21, s[58:59] offset:512
	v_pk_fma_f32 v[110:111], v[110:111], v[146:147], v[222:223]
	v_pk_fma_f32 v[112:113], v[112:113], v[148:149], v[224:225]
	global_store_dwordx4 v20, v[110:113], s[58:59] offset:576
	global_load_dwordx4 v[222:225], v21, s[58:59] offset:576
	v_add_u32_e32 v20, 0x30000, v31
	v_add_u32_e32 v21, 0xb0000, v31
	v_pk_fma_f32 v[84:85], v[84:85], v[26:27], v[226:227]
	v_pk_fma_f32 v[86:87], v[86:87], v[28:29], v[228:229]
	global_store_dwordx4 v20, v[84:87], s[58:59]
	global_load_dwordx4 v[226:229], v21, s[58:59]
	v_pk_fma_f32 v[80:81], v[80:81], v[138:139], v[232:233]
	v_pk_fma_f32 v[82:83], v[82:83], v[140:141], v[234:235]
	global_store_dwordx4 v20, v[80:83], s[58:59] offset:64
	global_load_dwordx4 v[232:235], v21, s[58:59] offset:64
	v_pk_fma_f32 v[92:93], v[92:93], v[142:143], v[236:237]
	v_pk_fma_f32 v[94:95], v[94:95], v[144:145], v[238:239]
	global_store_dwordx4 v20, v[92:95], s[58:59] offset:512
	global_load_dwordx4 v[236:239], v21, s[58:59] offset:512
	v_pk_fma_f32 v[88:89], v[88:89], v[146:147], v[240:241]
	v_pk_fma_f32 v[90:91], v[90:91], v[148:149], v[242:243]
	global_store_dwordx4 v20, v[88:91], s[58:59] offset:576
	global_load_dwordx4 v[240:243], v21, s[58:59] offset:576
	v_add_u32_e32 v21, 0x80000, v31
	s_waitcnt vmcnt(30)
	v_pk_fma_f32 v[68:69], v[68:69], v[26:27], v[150:151]
	v_pk_fma_f32 v[70:71], v[70:71], v[28:29], v[152:153]
	global_store_dwordx4 v21, v[68:71], s[58:59]
	s_waitcnt vmcnt(29)
	v_pk_fma_f32 v[64:65], v[64:65], v[138:139], v[154:155]
	v_pk_fma_f32 v[66:67], v[66:67], v[140:141], v[156:157]
	global_store_dwordx4 v21, v[64:67], s[58:59] offset:64
	s_waitcnt vmcnt(28)
	v_pk_fma_f32 v[76:77], v[76:77], v[142:143], v[164:165]
	v_pk_fma_f32 v[78:79], v[78:79], v[144:145], v[166:167]
	global_store_dwordx4 v21, v[76:79], s[58:59] offset:512
	s_waitcnt vmcnt(27)
	v_pk_fma_f32 v[72:73], v[72:73], v[146:147], v[168:169]
	v_pk_fma_f32 v[74:75], v[74:75], v[148:149], v[170:171]
	global_store_dwordx4 v21, v[72:75], s[58:59] offset:576
	v_add_u32_e32 v21, 0x90000, v31
	s_waitcnt vmcnt(26)
	v_pk_fma_f32 v[52:53], v[52:53], v[26:27], v[172:173]
	v_pk_fma_f32 v[54:55], v[54:55], v[28:29], v[174:175]
	global_store_dwordx4 v21, v[52:55], s[58:59]
	s_waitcnt vmcnt(25)
	v_pk_fma_f32 v[48:49], v[48:49], v[138:139], v[198:199]
	v_pk_fma_f32 v[50:51], v[50:51], v[140:141], v[200:201]
	global_store_dwordx4 v21, v[48:51], s[58:59] offset:64
	s_waitcnt vmcnt(24)
	v_pk_fma_f32 v[60:61], v[60:61], v[142:143], v[202:203]
	v_pk_fma_f32 v[62:63], v[62:63], v[144:145], v[204:205]
	global_store_dwordx4 v21, v[60:63], s[58:59] offset:512
	s_waitcnt vmcnt(23)
	v_pk_fma_f32 v[56:57], v[56:57], v[146:147], v[206:207]
	v_pk_fma_f32 v[58:59], v[58:59], v[148:149], v[208:209]
	global_store_dwordx4 v21, v[56:59], s[58:59] offset:576
	v_add_u32_e32 v21, 0xa0000, v31
	s_waitcnt vmcnt(22)
	v_pk_fma_f32 v[44:45], v[44:45], v[26:27], v[210:211]
	v_pk_fma_f32 v[46:47], v[46:47], v[28:29], v[212:213]
	global_store_dwordx4 v21, v[44:47], s[58:59]
	s_waitcnt vmcnt(21)
	v_pk_fma_f32 v[40:41], v[40:41], v[138:139], v[214:215]
	v_pk_fma_f32 v[42:43], v[42:43], v[140:141], v[216:217]
	global_store_dwordx4 v21, v[40:43], s[58:59] offset:64
	s_waitcnt vmcnt(20)
	v_pk_fma_f32 v[36:37], v[36:37], v[142:143], v[218:219]
	v_pk_fma_f32 v[38:39], v[38:39], v[144:145], v[220:221]
	global_store_dwordx4 v21, v[36:39], s[58:59] offset:512
	s_waitcnt vmcnt(19)
	v_pk_fma_f32 v[32:33], v[32:33], v[146:147], v[222:223]
	v_pk_fma_f32 v[34:35], v[34:35], v[148:149], v[224:225]
	global_store_dwordx4 v21, v[32:35], s[58:59] offset:576
	v_add_u32_e32 v21, 0xb0000, v31
	s_waitcnt vmcnt(18)
	v_pk_fma_f32 v[16:17], v[16:17], v[26:27], v[226:227]
	v_pk_fma_f32 v[18:19], v[18:19], v[28:29], v[228:229]
	global_store_dwordx4 v21, v[16:19], s[58:59]
	s_waitcnt vmcnt(17)
	v_pk_fma_f32 v[12:13], v[12:13], v[138:139], v[232:233]
	v_pk_fma_f32 v[14:15], v[14:15], v[140:141], v[234:235]
	global_store_dwordx4 v21, v[12:15], s[58:59] offset:64
	s_waitcnt vmcnt(16)
	v_pk_fma_f32 v[8:9], v[8:9], v[142:143], v[236:237]
	v_pk_fma_f32 v[10:11], v[10:11], v[144:145], v[238:239]
	global_store_dwordx4 v21, v[8:11], s[58:59] offset:512
	s_waitcnt vmcnt(15)
	v_pk_fma_f32 v[0:1], v[0:1], v[146:147], v[240:241]
	v_pk_fma_f32 v[2:3], v[2:3], v[148:149], v[242:243]
	global_store_dwordx4 v21, v[0:3], s[58:59] offset:576
	s_add_i32 s17, s17, s16
	s_cmpk_gt_i32 s17, 0xff
	s_waitcnt vmcnt(0)
	s_cbranch_scc1 .LBB0_74

.LBB0_192:
	s_or_b64 exec, exec, s[4:5]
	s_cmpk_gt_i32 s20, 0x3fff
	s_cselect_b32 s9, s19, s59
	s_cselect_b32 s8, s18, s58
	s_min_i32 s0, s20, 0x4000
	s_ashr_i32 s0, s0, 13
	s_mulk_i32 s0, 0x1800
	s_ashr_i32 s1, s0, 31
	s_lshl_b64 s[0:1], s[0:1], 2
	s_add_u32 s0, s14, s0
	s_addc_u32 s1, s15, s1
	v_lshlrev_b32_e32 v160, 2, v146
	v_lshl_or_b32 v160, v145, 5, v160
	v_lshl_or_b32 v160, s21, 8, v160
	v_lshlrev_b32_e32 v237, 2, v160
	v_add_u32_e32 v236, s20, v147
	v_lshl_add_u32 v238, v236, 12, v237
	global_load_dwordx4 v[128:131], v237, s[0:1]
	global_load_dwordx4 v[132:135], v237, s[0:1] offset:64
	global_load_dwordx4 v[136:139], v237, s[0:1] offset:512
	global_load_dwordx4 v[140:143], v237, s[0:1] offset:576
	s_movk_i32 s39, 0x4000
	s_movk_i32 s42, 0xc00
	s_movk_i32 s68, 0x1020
	v_mov_b32_e32 v252, 0x358637bd
	v_mov_b32_e32 v250, v246
	v_mov_b32_e32 v246, v162
	v_mov_b32_e32 v251, 0x7fc00000
	v_mov_b32_e32 v162, v230
	v_mov_b32_e32 v230, 0x33b4000
	s_and_b64 vcc, exec, s[6:7]
	s_cbranch_vccz .Lres_split_p9
	v_mov_b32_e32 v160, v238
	global_load_dwordx4 v[144:147], v160, s[8:9]
	global_load_dwordx4 v[148:151], v160, s[8:9] offset:64
	global_load_dwordx4 v[152:155], v160, s[8:9] offset:512
	global_load_dwordx4 v[156:159], v160, s[8:9] offset:576
	v_add_u32_e32 v160, 0x10000, v238
	global_load_dwordx4 v[164:167], v160, s[8:9]
	global_load_dwordx4 v[168:171], v160, s[8:9] offset:64
	global_load_dwordx4 v[172:175], v160, s[8:9] offset:512
	global_load_dwordx4 v[198:201], v160, s[8:9] offset:576
	v_add_u32_e32 v160, 0x20000, v238
	global_load_dwordx4 v[202:205], v160, s[8:9]
	global_load_dwordx4 v[206:209], v160, s[8:9] offset:64
	global_load_dwordx4 v[210:213], v160, s[8:9] offset:512
	global_load_dwordx4 v[214:217], v160, s[8:9] offset:576
	v_add_u32_e32 v160, 0x30000, v238
	global_load_dwordx4 v[218:221], v160, s[8:9]
	global_load_dwordx4 v[222:225], v160, s[8:9] offset:64
	global_load_dwordx4 v[226:229], v160, s[8:9] offset:512
	global_load_dwordx4 v[232:235], v160, s[8:9] offset:576
	s_waitcnt vmcnt(0)
	v_mov_b32_e32 v160, v238
	v_add_u32_e32 v236, 0x80000, v238
	v_pk_fma_f32 v[124:125], v[124:125], v[128:129], v[144:145]
	v_pk_fma_f32 v[126:127], v[126:127], v[130:131], v[146:147]
	global_store_dwordx4 v160, v[124:127], s[8:9]
	global_load_dwordx4 v[144:147], v236, s[8:9]
	v_pk_fma_f32 v[120:121], v[120:121], v[132:133], v[148:149]
	v_pk_fma_f32 v[122:123], v[122:123], v[134:135], v[150:151]
	global_store_dwordx4 v160, v[120:123], s[8:9] offset:64
	global_load_dwordx4 v[148:151], v236, s[8:9] offset:64
	v_pk_fma_f32 v[116:117], v[116:117], v[136:137], v[152:153]
	v_pk_fma_f32 v[118:119], v[118:119], v[138:139], v[154:155]
	global_store_dwordx4 v160, v[116:119], s[8:9] offset:512
	global_load_dwordx4 v[152:155], v236, s[8:9] offset:512
	v_pk_fma_f32 v[112:113], v[112:113], v[140:141], v[156:157]
	v_pk_fma_f32 v[114:115], v[114:115], v[142:143], v[158:159]
	global_store_dwordx4 v160, v[112:115], s[8:9] offset:576
	global_load_dwordx4 v[156:159], v236, s[8:9] offset:576
	v_add_u32_e32 v160, 0x10000, v238
	v_add_u32_e32 v236, 0x90000, v238
	v_pk_fma_f32 v[108:109], v[108:109], v[128:129], v[164:165]
	v_pk_fma_f32 v[110:111], v[110:111], v[130:131], v[166:167]
	global_store_dwordx4 v160, v[108:111], s[8:9]
	global_load_dwordx4 v[164:167], v236, s[8:9]
	v_pk_fma_f32 v[104:105], v[104:105], v[132:133], v[168:169]
	v_pk_fma_f32 v[106:107], v[106:107], v[134:135], v[170:171]
	global_store_dwordx4 v160, v[104:107], s[8:9] offset:64
	global_load_dwordx4 v[168:171], v236, s[8:9] offset:64
	v_pk_fma_f32 v[100:101], v[100:101], v[136:137], v[172:173]
	v_pk_fma_f32 v[102:103], v[102:103], v[138:139], v[174:175]
	global_store_dwordx4 v160, v[100:103], s[8:9] offset:512
	global_load_dwordx4 v[172:175], v236, s[8:9] offset:512
	v_pk_fma_f32 v[96:97], v[96:97], v[140:141], v[198:199]
	v_pk_fma_f32 v[98:99], v[98:99], v[142:143], v[200:201]
	global_store_dwordx4 v160, v[96:99], s[8:9] offset:576
	global_load_dwordx4 v[198:201], v236, s[8:9] offset:576
	v_add_u32_e32 v160, 0x20000, v238
	v_add_u32_e32 v236, 0xa0000, v238
	v_pk_fma_f32 v[92:93], v[92:93], v[128:129], v[202:203]
	v_pk_fma_f32 v[94:95], v[94:95], v[130:131], v[204:205]
	global_store_dwordx4 v160, v[92:95], s[8:9]
	global_load_dwordx4 v[202:205], v236, s[8:9]
	v_pk_fma_f32 v[88:89], v[88:89], v[132:133], v[206:207]
	v_pk_fma_f32 v[90:91], v[90:91], v[134:135], v[208:209]
	global_store_dwordx4 v160, v[88:91], s[8:9] offset:64
	global_load_dwordx4 v[206:209], v236, s[8:9] offset:64
	v_pk_fma_f32 v[84:85], v[84:85], v[136:137], v[210:211]
	v_pk_fma_f32 v[86:87], v[86:87], v[138:139], v[212:213]
	global_store_dwordx4 v160, v[84:87], s[8:9] offset:512
	global_load_dwordx4 v[210:213], v236, s[8:9] offset:512
	v_pk_fma_f32 v[80:81], v[80:81], v[140:141], v[214:215]
	v_pk_fma_f32 v[82:83], v[82:83], v[142:143], v[216:217]
	global_store_dwordx4 v160, v[80:83], s[8:9] offset:576
	global_load_dwordx4 v[214:217], v236, s[8:9] offset:576
	v_add_u32_e32 v160, 0x30000, v238
	v_add_u32_e32 v236, 0xb0000, v238
	v_pk_fma_f32 v[76:77], v[76:77], v[128:129], v[218:219]
	v_pk_fma_f32 v[78:79], v[78:79], v[130:131], v[220:221]
	global_store_dwordx4 v160, v[76:79], s[8:9]
	global_load_dwordx4 v[218:221], v236, s[8:9]
	v_pk_fma_f32 v[72:73], v[72:73], v[132:133], v[222:223]
	v_pk_fma_f32 v[74:75], v[74:75], v[134:135], v[224:225]
	global_store_dwordx4 v160, v[72:75], s[8:9] offset:64
	global_load_dwordx4 v[222:225], v236, s[8:9] offset:64
	v_pk_fma_f32 v[68:69], v[68:69], v[136:137], v[226:227]
	v_pk_fma_f32 v[70:71], v[70:71], v[138:139], v[228:229]
	global_store_dwordx4 v160, v[68:71], s[8:9] offset:512
	global_load_dwordx4 v[226:229], v236, s[8:9] offset:512
	v_pk_fma_f32 v[64:65], v[64:65], v[140:141], v[232:233]
	v_pk_fma_f32 v[66:67], v[66:67], v[142:143], v[234:235]
	global_store_dwordx4 v160, v[64:67], s[8:9] offset:576
	global_load_dwordx4 v[232:235], v236, s[8:9] offset:576
	v_add_u32_e32 v236, 0x80000, v238
	s_waitcnt vmcnt(30)
	v_pk_fma_f32 v[60:61], v[60:61], v[128:129], v[144:145]
	v_pk_fma_f32 v[62:63], v[62:63], v[130:131], v[146:147]
	global_store_dwordx4 v236, v[60:63], s[8:9]
	s_waitcnt vmcnt(29)
	v_pk_fma_f32 v[56:57], v[56:57], v[132:133], v[148:149]
	v_pk_fma_f32 v[58:59], v[58:59], v[134:135], v[150:151]
	global_store_dwordx4 v236, v[56:59], s[8:9] offset:64
	s_waitcnt vmcnt(28)
	v_pk_fma_f32 v[52:53], v[52:53], v[136:137], v[152:153]
	v_pk_fma_f32 v[54:55], v[54:55], v[138:139], v[154:155]
	global_store_dwordx4 v236, v[52:55], s[8:9] offset:512
	s_waitcnt vmcnt(27)
	v_pk_fma_f32 v[48:49], v[48:49], v[140:141], v[156:157]
	v_pk_fma_f32 v[50:51], v[50:51], v[142:143], v[158:159]
	global_store_dwordx4 v236, v[48:51], s[8:9] offset:576
	v_add_u32_e32 v236, 0x90000, v238
	s_waitcnt vmcnt(26)
	v_pk_fma_f32 v[44:45], v[44:45], v[128:129], v[164:165]
	v_pk_fma_f32 v[46:47], v[46:47], v[130:131], v[166:167]
	global_store_dwordx4 v236, v[44:47], s[8:9]
	s_waitcnt vmcnt(25)
	v_pk_fma_f32 v[40:41], v[40:41], v[132:133], v[168:169]
	v_pk_fma_f32 v[42:43], v[42:43], v[134:135], v[170:171]
	global_store_dwordx4 v236, v[40:43], s[8:9] offset:64
	s_waitcnt vmcnt(24)
	v_pk_fma_f32 v[36:37], v[36:37], v[136:137], v[172:173]
	v_pk_fma_f32 v[38:39], v[38:39], v[138:139], v[174:175]
	global_store_dwordx4 v236, v[36:39], s[8:9] offset:512
	s_waitcnt vmcnt(23)
	v_pk_fma_f32 v[32:33], v[32:33], v[140:141], v[198:199]
	v_pk_fma_f32 v[34:35], v[34:35], v[142:143], v[200:201]
	global_store_dwordx4 v236, v[32:35], s[8:9] offset:576
	v_add_u32_e32 v236, 0xa0000, v238
	s_waitcnt vmcnt(22)
	v_pk_fma_f32 v[28:29], v[28:29], v[128:129], v[202:203]
	v_pk_fma_f32 v[30:31], v[30:31], v[130:131], v[204:205]
	global_store_dwordx4 v236, v[28:31], s[8:9]
	s_waitcnt vmcnt(21)
	v_pk_fma_f32 v[24:25], v[24:25], v[132:133], v[206:207]
	v_pk_fma_f32 v[26:27], v[26:27], v[134:135], v[208:209]
	global_store_dwordx4 v236, v[24:27], s[8:9] offset:64
	s_waitcnt vmcnt(20)
	v_pk_fma_f32 v[20:21], v[20:21], v[136:137], v[210:211]
	v_pk_fma_f32 v[22:23], v[22:23], v[138:139], v[212:213]
	global_store_dwordx4 v236, v[20:23], s[8:9] offset:512
	s_waitcnt vmcnt(19)
	v_pk_fma_f32 v[16:17], v[16:17], v[140:141], v[214:215]
	v_pk_fma_f32 v[18:19], v[18:19], v[142:143], v[216:217]
	global_store_dwordx4 v236, v[16:19], s[8:9] offset:576
	v_add_u32_e32 v236, 0xb0000, v238
	s_waitcnt vmcnt(18)
	v_pk_fma_f32 v[12:13], v[12:13], v[128:129], v[218:219]
	v_pk_fma_f32 v[14:15], v[14:15], v[130:131], v[220:221]
	global_store_dwordx4 v236, v[12:15], s[8:9]
	s_waitcnt vmcnt(17)
	v_pk_fma_f32 v[8:9], v[8:9], v[132:133], v[222:223]
	v_pk_fma_f32 v[10:11], v[10:11], v[134:135], v[224:225]
	global_store_dwordx4 v236, v[8:11], s[8:9] offset:64
	s_waitcnt vmcnt(16)
	v_pk_fma_f32 v[4:5], v[4:5], v[136:137], v[226:227]
	v_pk_fma_f32 v[6:7], v[6:7], v[138:139], v[228:229]
	global_store_dwordx4 v236, v[4:7], s[8:9] offset:512
	s_waitcnt vmcnt(15)
	v_pk_fma_f32 v[0:1], v[0:1], v[140:141], v[232:233]
	v_pk_fma_f32 v[2:3], v[2:3], v[142:143], v[234:235]
	global_store_dwordx4 v236, v[0:3], s[8:9] offset:576
	s_branch .Lres_end_p9
.Lres_split_p9:
	s_sub_i32 s3, s12, 0x100
	s_mul_i32 s26, s3, 0x1746
	s_lshr_b32 s26, s26, 16
	s_mul_i32 s32, s26, 11
	s_sub_i32 s32, s3, s32
	s_lshl_b32 s38, s3, 18
	s_add_u32 s22, s44, s38
	s_addc_u32 s23, s45, 0
	s_add_u32 s22, s22, 0x2200000
	s_addc_u32 s23, s23, 0
	s_mul_i32 s38, s26, 0x2c0000
	s_add_u32 s24, s44, s38
	s_addc_u32 s25, s45, 0
	s_add_u32 s24, s24, 0x2200000
	s_addc_u32 s25, s25, 0
	s_lshl_b32 s38, s26, 2
	s_add_u32 s4, s46, s38
	s_addc_u32 s5, s47, 0
	s_add_u32 s4, s4, 0xdacbc20
	s_addc_u32 s5, s5, 0
	v_lshlrev_b32_e32 v160, 5, v145
	v_lshl_or_b32 v160, v146, 2, v160
	v_lshlrev_b32_e32 v160, 2, v160
	v_lshl_add_u32 v237, v147, 10, v160
	v_mov_b32_e32 v160, v237
	global_store_dwordx4 v160, v[124:127], s[22:23]
	global_store_dwordx4 v160, v[120:123], s[22:23] offset:64
	global_store_dwordx4 v160, v[116:119], s[22:23] offset:512
	global_store_dwordx4 v160, v[112:115], s[22:23] offset:576
	v_add_u32_e32 v160, 0x4000, v237
	global_store_dwordx4 v160, v[108:111], s[22:23]
	global_store_dwordx4 v160, v[104:107], s[22:23] offset:64
	global_store_dwordx4 v160, v[100:103], s[22:23] offset:512
	global_store_dwordx4 v160, v[96:99], s[22:23] offset:576
	v_add_u32_e32 v160, 0x8000, v237
	global_store_dwordx4 v160, v[92:95], s[22:23]
	global_store_dwordx4 v160, v[88:91], s[22:23] offset:64
	global_store_dwordx4 v160, v[84:87], s[22:23] offset:512
	global_store_dwordx4 v160, v[80:83], s[22:23] offset:576
	v_add_u32_e32 v160, 0xc000, v237
	global_store_dwordx4 v160, v[76:79], s[22:23]
	global_store_dwordx4 v160, v[72:75], s[22:23] offset:64
	global_store_dwordx4 v160, v[68:71], s[22:23] offset:512
	global_store_dwordx4 v160, v[64:67], s[22:23] offset:576
	v_add_u32_e32 v160, 0x20000, v237
	global_store_dwordx4 v160, v[60:63], s[22:23]
	global_store_dwordx4 v160, v[56:59], s[22:23] offset:64
	global_store_dwordx4 v160, v[52:55], s[22:23] offset:512
	global_store_dwordx4 v160, v[48:51], s[22:23] offset:576
	v_add_u32_e32 v160, 0x24000, v237
	global_store_dwordx4 v160, v[44:47], s[22:23]
	global_store_dwordx4 v160, v[40:43], s[22:23] offset:64
	global_store_dwordx4 v160, v[36:39], s[22:23] offset:512
	global_store_dwordx4 v160, v[32:35], s[22:23] offset:576
	v_add_u32_e32 v160, 0x28000, v237
	global_store_dwordx4 v160, v[28:31], s[22:23]
	global_store_dwordx4 v160, v[24:27], s[22:23] offset:64
	global_store_dwordx4 v160, v[20:23], s[22:23] offset:512
	global_store_dwordx4 v160, v[16:19], s[22:23] offset:576
	v_add_u32_e32 v160, 0x2c000, v237
	global_store_dwordx4 v160, v[12:15], s[22:23]
	global_store_dwordx4 v160, v[8:11], s[22:23] offset:64
	global_store_dwordx4 v160, v[4:7], s[22:23] offset:512
	global_store_dwordx4 v160, v[0:3], s[22:23] offset:576
	s_waitcnt vmcnt(0)
	s_barrier
	v_mov_b32_e32 v238, 0
	s_cmp_lg_u32 s48, 0
	s_cbranch_scc1 .Lres_nosig_p9
	buffer_wbl2 sc1
	s_waitcnt vmcnt(0)
	v_mov_b32_e32 v236, 1
	s_mov_b64 exec, 1
	global_atomic_add v238, v236, s[4:5]
	s_mov_b64 exec, -1
.Lres_nosig_p9:
	s_mov_b32 s98, 0
.Lres_spin_p9:
	global_load_dword v236, v238, s[4:5] sc1
	s_add_i32 s98, s98, 1
	s_waitcnt vmcnt(0)
	v_readfirstlane_b32 s38, v236
	s_cmp_ge_u32 s38, 11
	s_cbranch_scc1 .Lres_go_p9
	s_cmp_gt_u32 s98, 0x10000
	s_cbranch_scc1 .Lres_go_p9
	s_sleep 2
	s_branch .Lres_spin_p9
.Lres_go_p9:
	buffer_inv sc1
	v_mbcnt_lo_u32_b32 v232, -1, 0
	v_mbcnt_hi_u32_b32 v232, -1, v232
	v_lshlrev_b32_e32 v232, 4, v232
	s_lshl_b32 s3, s21, 10
	v_add_u32_e32 v233, s3, v232
	global_load_dwordx4 v[128:131], v233, s[0:1]
	s_lshr_b32 s38, s48, 6
	s_mul_i32 s57, s32, 24
	s_add_i32 s99, s57, 24
	s_min_u32 s99, s99, 0x100
	s_add_i32 s57, s57, s38
.Lres_rloop_p9:
	s_cmp_ge_u32 s57, s99
	s_cbranch_scc1 .Lres_end_p9
	s_add_i32 s38, s57, 0
	s_lshl_b32 s98, s38, 10
	v_add_u32_e32 v234, s98, v232
	s_mov_b64 s[22:23], s[24:25]
	global_load_dwordx4 v[144:147], v234, s[22:23]
	s_add_u32 s22, s22, 0x40000
	s_addc_u32 s23, s23, 0
	global_load_dwordx4 v[148:151], v234, s[22:23]
	s_add_u32 s22, s22, 0x40000
	s_addc_u32 s23, s23, 0
	global_load_dwordx4 v[152:155], v234, s[22:23]
	s_add_u32 s22, s22, 0x40000
	s_addc_u32 s23, s23, 0
	global_load_dwordx4 v[156:159], v234, s[22:23]
	s_add_u32 s22, s22, 0x40000
	s_addc_u32 s23, s23, 0
	global_load_dwordx4 v[164:167], v234, s[22:23]
	s_add_u32 s22, s22, 0x40000
	s_addc_u32 s23, s23, 0
	global_load_dwordx4 v[168:171], v234, s[22:23]
	s_add_u32 s22, s22, 0x40000
	s_addc_u32 s23, s23, 0
	global_load_dwordx4 v[172:175], v234, s[22:23]
	s_add_u32 s22, s22, 0x40000
	s_addc_u32 s23, s23, 0
	global_load_dwordx4 v[198:201], v234, s[22:23]
	s_add_u32 s22, s22, 0x40000
	s_addc_u32 s23, s23, 0
	global_load_dwordx4 v[202:205], v234, s[22:23]
	s_add_u32 s22, s22, 0x40000
	s_addc_u32 s23, s23, 0
	global_load_dwordx4 v[206:209], v234, s[22:23]
	s_add_u32 s22, s22, 0x40000
	s_addc_u32 s23, s23, 0
	global_load_dwordx4 v[210:213], v234, s[22:23]
	s_add_i32 s38, s38, s20
	s_lshl_b32 s38, s38, 12
	s_add_i32 s38, s38, s3
	v_add_u32_e32 v235, s38, v232
	global_load_dwordx4 v[214:217], v235, s[8:9]
	s_waitcnt vmcnt(0)
	v_pk_add_f32 v[144:145], v[144:145], v[148:149]
	v_pk_add_f32 v[146:147], v[146:147], v[150:151]
	v_pk_add_f32 v[144:145], v[144:145], v[152:153]
	v_pk_add_f32 v[146:147], v[146:147], v[154:155]
	v_pk_add_f32 v[144:145], v[144:145], v[156:157]
	v_pk_add_f32 v[146:147], v[146:147], v[158:159]
	v_pk_add_f32 v[144:145], v[144:145], v[164:165]
	v_pk_add_f32 v[146:147], v[146:147], v[166:167]
	v_pk_add_f32 v[144:145], v[144:145], v[168:169]
	v_pk_add_f32 v[146:147], v[146:147], v[170:171]
	v_pk_add_f32 v[144:145], v[144:145], v[172:173]
	v_pk_add_f32 v[146:147], v[146:147], v[174:175]
	v_pk_add_f32 v[144:145], v[144:145], v[198:199]
	v_pk_add_f32 v[146:147], v[146:147], v[200:201]
	v_pk_add_f32 v[144:145], v[144:145], v[202:203]
	v_pk_add_f32 v[146:147], v[146:147], v[204:205]
	v_pk_add_f32 v[144:145], v[144:145], v[206:207]
	v_pk_add_f32 v[146:147], v[146:147], v[208:209]
	v_pk_add_f32 v[144:145], v[144:145], v[210:211]
	v_pk_add_f32 v[146:147], v[146:147], v[212:213]
	v_pk_fma_f32 v[144:145], v[144:145], v[128:129], v[214:215]
	v_pk_fma_f32 v[146:147], v[146:147], v[130:131], v[216:217]
	global_store_dwordx4 v235, v[144:147], s[8:9]
	s_add_i32 s57, s57, 8
	s_branch .Lres_rloop_p9
.Lres_end_p9:
	s_branch .LBB0_176
.LBB0_320:
	s_mov_b64 s[4:5], 0

.LBB0_363:
	s_or_b64 exec, exec, s[12:13]
	s_cmpk_gt_i32 s4, 0x3fff
	s_cselect_b32 s13, s29, s59
	s_cselect_b32 s12, s28, s58
	s_cselect_b32 s15, s31, s7
	s_cselect_b32 s14, s30, s6
	s_min_i32 s0, s4, 0x4000
	s_ashr_i32 s0, s0, 13
	s_mulk_i32 s0, 0x1800
	s_ashr_i32 s1, s0, 31
	s_lshl_b64 s[0:1], s[0:1], 2
	s_add_u32 s0, s24, s0
	s_addc_u32 s1, s25, s1
	v_lshlrev_b32_e32 v160, 5, v145
	v_lshlrev_b32_e32 v236, 2, v146
	v_or3_b32 v160, v160, v236, s10
	v_lshlrev_b32_e32 v237, 2, v160
	v_add_u32_e32 v236, s4, v147
	v_lshl_add_u32 v238, v236, 12, v237
	global_load_dwordx4 v[128:131], v237, s[0:1]
	global_load_dwordx4 v[132:135], v237, s[0:1] offset:64
	global_load_dwordx4 v[136:139], v237, s[0:1] offset:512
	global_load_dwordx4 v[140:143], v237, s[0:1] offset:576
	s_movk_i32 s39, 0x4000
	s_movk_i32 s42, 0xc00
	s_movk_i32 s68, 0x1020
	v_mov_b32_e32 v252, 0x358637bd
	v_mov_b32_e32 v250, v246
	v_not_b32_e32 v246, 31
	v_mov_b32_e32 v251, 0x7fc00000
	s_and_b64 vcc, exec, s[8:9]
	s_cbranch_vccz .Lres_split_p6
	v_mov_b32_e32 v160, v238
	global_load_dwordx4 v[144:147], v160, s[14:15]
	global_load_dwordx4 v[148:151], v160, s[14:15] offset:64
	global_load_dwordx4 v[152:155], v160, s[14:15] offset:512
	global_load_dwordx4 v[156:159], v160, s[14:15] offset:576
	v_add_u32_e32 v160, 0x10000, v238
	global_load_dwordx4 v[164:167], v160, s[14:15]
	global_load_dwordx4 v[168:171], v160, s[14:15] offset:64
	global_load_dwordx4 v[172:175], v160, s[14:15] offset:512
	global_load_dwordx4 v[198:201], v160, s[14:15] offset:576
	v_add_u32_e32 v160, 0x20000, v238
	global_load_dwordx4 v[202:205], v160, s[14:15]
	global_load_dwordx4 v[206:209], v160, s[14:15] offset:64
	global_load_dwordx4 v[210:213], v160, s[14:15] offset:512
	global_load_dwordx4 v[214:217], v160, s[14:15] offset:576
	v_add_u32_e32 v160, 0x30000, v238
	global_load_dwordx4 v[218:221], v160, s[14:15]
	global_load_dwordx4 v[222:225], v160, s[14:15] offset:64
	global_load_dwordx4 v[226:229], v160, s[14:15] offset:512
	global_load_dwordx4 v[232:235], v160, s[14:15] offset:576
	s_waitcnt vmcnt(0)
	v_mov_b32_e32 v160, v238
	v_add_u32_e32 v236, 0x80000, v238
	v_pk_fma_f32 v[124:125], v[124:125], v[128:129], v[144:145]
	v_pk_fma_f32 v[126:127], v[126:127], v[130:131], v[146:147]
	global_store_dwordx4 v160, v[124:127], s[12:13]
	global_load_dwordx4 v[144:147], v236, s[14:15]
	v_pk_fma_f32 v[120:121], v[120:121], v[132:133], v[148:149]
	v_pk_fma_f32 v[122:123], v[122:123], v[134:135], v[150:151]
	global_store_dwordx4 v160, v[120:123], s[12:13] offset:64
	global_load_dwordx4 v[148:151], v236, s[14:15] offset:64
	v_pk_fma_f32 v[116:117], v[116:117], v[136:137], v[152:153]
	v_pk_fma_f32 v[118:119], v[118:119], v[138:139], v[154:155]
	global_store_dwordx4 v160, v[116:119], s[12:13] offset:512
	global_load_dwordx4 v[152:155], v236, s[14:15] offset:512
	v_pk_fma_f32 v[112:113], v[112:113], v[140:141], v[156:157]
	v_pk_fma_f32 v[114:115], v[114:115], v[142:143], v[158:159]
	global_store_dwordx4 v160, v[112:115], s[12:13] offset:576
	global_load_dwordx4 v[156:159], v236, s[14:15] offset:576
	v_add_u32_e32 v160, 0x10000, v238
	v_add_u32_e32 v236, 0x90000, v238
	v_pk_fma_f32 v[108:109], v[108:109], v[128:129], v[164:165]
	v_pk_fma_f32 v[110:111], v[110:111], v[130:131], v[166:167]
	global_store_dwordx4 v160, v[108:111], s[12:13]
	global_load_dwordx4 v[164:167], v236, s[14:15]
	v_pk_fma_f32 v[104:105], v[104:105], v[132:133], v[168:169]
	v_pk_fma_f32 v[106:107], v[106:107], v[134:135], v[170:171]
	global_store_dwordx4 v160, v[104:107], s[12:13] offset:64
	global_load_dwordx4 v[168:171], v236, s[14:15] offset:64
	v_pk_fma_f32 v[100:101], v[100:101], v[136:137], v[172:173]
	v_pk_fma_f32 v[102:103], v[102:103], v[138:139], v[174:175]
	global_store_dwordx4 v160, v[100:103], s[12:13] offset:512
	global_load_dwordx4 v[172:175], v236, s[14:15] offset:512
	v_pk_fma_f32 v[96:97], v[96:97], v[140:141], v[198:199]
	v_pk_fma_f32 v[98:99], v[98:99], v[142:143], v[200:201]
	global_store_dwordx4 v160, v[96:99], s[12:13] offset:576
	global_load_dwordx4 v[198:201], v236, s[14:15] offset:576
	v_add_u32_e32 v160, 0x20000, v238
	v_add_u32_e32 v236, 0xa0000, v238
	v_pk_fma_f32 v[92:93], v[92:93], v[128:129], v[202:203]
	v_pk_fma_f32 v[94:95], v[94:95], v[130:131], v[204:205]
	global_store_dwordx4 v160, v[92:95], s[12:13]
	global_load_dwordx4 v[202:205], v236, s[14:15]
	v_pk_fma_f32 v[88:89], v[88:89], v[132:133], v[206:207]
	v_pk_fma_f32 v[90:91], v[90:91], v[134:135], v[208:209]
	global_store_dwordx4 v160, v[88:91], s[12:13] offset:64
	global_load_dwordx4 v[206:209], v236, s[14:15] offset:64
	v_pk_fma_f32 v[84:85], v[84:85], v[136:137], v[210:211]
	v_pk_fma_f32 v[86:87], v[86:87], v[138:139], v[212:213]
	global_store_dwordx4 v160, v[84:87], s[12:13] offset:512
	global_load_dwordx4 v[210:213], v236, s[14:15] offset:512
	v_pk_fma_f32 v[80:81], v[80:81], v[140:141], v[214:215]
	v_pk_fma_f32 v[82:83], v[82:83], v[142:143], v[216:217]
	global_store_dwordx4 v160, v[80:83], s[12:13] offset:576
	global_load_dwordx4 v[214:217], v236, s[14:15] offset:576
	v_add_u32_e32 v160, 0x30000, v238
	v_add_u32_e32 v236, 0xb0000, v238
	v_pk_fma_f32 v[76:77], v[76:77], v[128:129], v[218:219]
	v_pk_fma_f32 v[78:79], v[78:79], v[130:131], v[220:221]
	global_store_dwordx4 v160, v[76:79], s[12:13]
	global_load_dwordx4 v[218:221], v236, s[14:15]
	v_pk_fma_f32 v[72:73], v[72:73], v[132:133], v[222:223]
	v_pk_fma_f32 v[74:75], v[74:75], v[134:135], v[224:225]
	global_store_dwordx4 v160, v[72:75], s[12:13] offset:64
	global_load_dwordx4 v[222:225], v236, s[14:15] offset:64
	v_pk_fma_f32 v[68:69], v[68:69], v[136:137], v[226:227]
	v_pk_fma_f32 v[70:71], v[70:71], v[138:139], v[228:229]
	global_store_dwordx4 v160, v[68:71], s[12:13] offset:512
	global_load_dwordx4 v[226:229], v236, s[14:15] offset:512
	v_pk_fma_f32 v[64:65], v[64:65], v[140:141], v[232:233]
	v_pk_fma_f32 v[66:67], v[66:67], v[142:143], v[234:235]
	global_store_dwordx4 v160, v[64:67], s[12:13] offset:576
	global_load_dwordx4 v[232:235], v236, s[14:15] offset:576
	v_add_u32_e32 v236, 0x80000, v238
	s_waitcnt vmcnt(30)
	v_pk_fma_f32 v[60:61], v[60:61], v[128:129], v[144:145]
	v_pk_fma_f32 v[62:63], v[62:63], v[130:131], v[146:147]
	global_store_dwordx4 v236, v[60:63], s[12:13]
	s_waitcnt vmcnt(29)
	v_pk_fma_f32 v[56:57], v[56:57], v[132:133], v[148:149]
	v_pk_fma_f32 v[58:59], v[58:59], v[134:135], v[150:151]
	global_store_dwordx4 v236, v[56:59], s[12:13] offset:64
	s_waitcnt vmcnt(28)
	v_pk_fma_f32 v[52:53], v[52:53], v[136:137], v[152:153]
	v_pk_fma_f32 v[54:55], v[54:55], v[138:139], v[154:155]
	global_store_dwordx4 v236, v[52:55], s[12:13] offset:512
	s_waitcnt vmcnt(27)
	v_pk_fma_f32 v[48:49], v[48:49], v[140:141], v[156:157]
	v_pk_fma_f32 v[50:51], v[50:51], v[142:143], v[158:159]
	global_store_dwordx4 v236, v[48:51], s[12:13] offset:576
	v_add_u32_e32 v236, 0x90000, v238
	s_waitcnt vmcnt(26)
	v_pk_fma_f32 v[44:45], v[44:45], v[128:129], v[164:165]
	v_pk_fma_f32 v[46:47], v[46:47], v[130:131], v[166:167]
	global_store_dwordx4 v236, v[44:47], s[12:13]
	s_waitcnt vmcnt(25)
	v_pk_fma_f32 v[40:41], v[40:41], v[132:133], v[168:169]
	v_pk_fma_f32 v[42:43], v[42:43], v[134:135], v[170:171]
	global_store_dwordx4 v236, v[40:43], s[12:13] offset:64
	s_waitcnt vmcnt(24)
	v_pk_fma_f32 v[36:37], v[36:37], v[136:137], v[172:173]
	v_pk_fma_f32 v[38:39], v[38:39], v[138:139], v[174:175]
	global_store_dwordx4 v236, v[36:39], s[12:13] offset:512
	s_waitcnt vmcnt(23)
	v_pk_fma_f32 v[32:33], v[32:33], v[140:141], v[198:199]
	v_pk_fma_f32 v[34:35], v[34:35], v[142:143], v[200:201]
	global_store_dwordx4 v236, v[32:35], s[12:13] offset:576
	v_add_u32_e32 v236, 0xa0000, v238
	s_waitcnt vmcnt(22)
	v_pk_fma_f32 v[28:29], v[28:29], v[128:129], v[202:203]
	v_pk_fma_f32 v[30:31], v[30:31], v[130:131], v[204:205]
	global_store_dwordx4 v236, v[28:31], s[12:13]
	s_waitcnt vmcnt(21)
	v_pk_fma_f32 v[24:25], v[24:25], v[132:133], v[206:207]
	v_pk_fma_f32 v[26:27], v[26:27], v[134:135], v[208:209]
	global_store_dwordx4 v236, v[24:27], s[12:13] offset:64
	s_waitcnt vmcnt(20)
	v_pk_fma_f32 v[20:21], v[20:21], v[136:137], v[210:211]
	v_pk_fma_f32 v[22:23], v[22:23], v[138:139], v[212:213]
	global_store_dwordx4 v236, v[20:23], s[12:13] offset:512
	s_waitcnt vmcnt(19)
	v_pk_fma_f32 v[16:17], v[16:17], v[140:141], v[214:215]
	v_pk_fma_f32 v[18:19], v[18:19], v[142:143], v[216:217]
	global_store_dwordx4 v236, v[16:19], s[12:13] offset:576
	v_add_u32_e32 v236, 0xb0000, v238
	s_waitcnt vmcnt(18)
	v_pk_fma_f32 v[12:13], v[12:13], v[128:129], v[218:219]
	v_pk_fma_f32 v[14:15], v[14:15], v[130:131], v[220:221]
	global_store_dwordx4 v236, v[12:15], s[12:13]
	s_waitcnt vmcnt(17)
	v_pk_fma_f32 v[8:9], v[8:9], v[132:133], v[222:223]
	v_pk_fma_f32 v[10:11], v[10:11], v[134:135], v[224:225]
	global_store_dwordx4 v236, v[8:11], s[12:13] offset:64
	s_waitcnt vmcnt(16)
	v_pk_fma_f32 v[4:5], v[4:5], v[136:137], v[226:227]
	v_pk_fma_f32 v[6:7], v[6:7], v[138:139], v[228:229]
	global_store_dwordx4 v236, v[4:7], s[12:13] offset:512
	s_waitcnt vmcnt(15)
	v_pk_fma_f32 v[0:1], v[0:1], v[140:141], v[232:233]
	v_pk_fma_f32 v[2:3], v[2:3], v[142:143], v[234:235]
	global_store_dwordx4 v236, v[0:3], s[12:13] offset:576
	s_branch .Lres_end_p6
.Lres_split_p6:
	s_sub_i32 s3, s23, 0x100
	s_lshr_b32 s5, s3, 2
	s_and_b32 s32, s3, 3
	s_lshl_b32 s36, s3, 18
	s_add_u32 s20, s44, s36
	s_addc_u32 s21, s45, 0
	s_add_u32 s20, s20, 0x2200000
	s_addc_u32 s21, s21, 0
	s_mul_i32 s36, s5, 0x100000
	s_add_u32 s34, s44, s36
	s_addc_u32 s35, s45, 0
	s_add_u32 s34, s34, 0x2200000
	s_addc_u32 s35, s35, 0
	s_lshl_b32 s36, s5, 2
	s_add_u32 s98, s46, s36
	s_addc_u32 s99, s47, 0
	s_add_u32 s98, s98, 0xdacbc00
	s_addc_u32 s99, s99, 0
	v_lshlrev_b32_e32 v160, 5, v145
	v_lshl_or_b32 v160, v146, 2, v160
	v_lshlrev_b32_e32 v160, 2, v160
	v_lshl_add_u32 v237, v147, 10, v160
	v_mov_b32_e32 v160, v237
	global_store_dwordx4 v160, v[124:127], s[20:21]
	global_store_dwordx4 v160, v[120:123], s[20:21] offset:64
	global_store_dwordx4 v160, v[116:119], s[20:21] offset:512
	global_store_dwordx4 v160, v[112:115], s[20:21] offset:576
	v_add_u32_e32 v160, 0x4000, v237
	global_store_dwordx4 v160, v[108:111], s[20:21]
	global_store_dwordx4 v160, v[104:107], s[20:21] offset:64
	global_store_dwordx4 v160, v[100:103], s[20:21] offset:512
	global_store_dwordx4 v160, v[96:99], s[20:21] offset:576
	v_add_u32_e32 v160, 0x8000, v237
	global_store_dwordx4 v160, v[92:95], s[20:21]
	global_store_dwordx4 v160, v[88:91], s[20:21] offset:64
	global_store_dwordx4 v160, v[84:87], s[20:21] offset:512
	global_store_dwordx4 v160, v[80:83], s[20:21] offset:576
	v_add_u32_e32 v160, 0xc000, v237
	global_store_dwordx4 v160, v[76:79], s[20:21]
	global_store_dwordx4 v160, v[72:75], s[20:21] offset:64
	global_store_dwordx4 v160, v[68:71], s[20:21] offset:512
	global_store_dwordx4 v160, v[64:67], s[20:21] offset:576
	v_add_u32_e32 v160, 0x20000, v237
	global_store_dwordx4 v160, v[60:63], s[20:21]
	global_store_dwordx4 v160, v[56:59], s[20:21] offset:64
	global_store_dwordx4 v160, v[52:55], s[20:21] offset:512
	global_store_dwordx4 v160, v[48:51], s[20:21] offset:576
	v_add_u32_e32 v160, 0x24000, v237
	global_store_dwordx4 v160, v[44:47], s[20:21]
	global_store_dwordx4 v160, v[40:43], s[20:21] offset:64
	global_store_dwordx4 v160, v[36:39], s[20:21] offset:512
	global_store_dwordx4 v160, v[32:35], s[20:21] offset:576
	v_add_u32_e32 v160, 0x28000, v237
	global_store_dwordx4 v160, v[28:31], s[20:21]
	global_store_dwordx4 v160, v[24:27], s[20:21] offset:64
	global_store_dwordx4 v160, v[20:23], s[20:21] offset:512
	global_store_dwordx4 v160, v[16:19], s[20:21] offset:576
	v_add_u32_e32 v160, 0x2c000, v237
	global_store_dwordx4 v160, v[12:15], s[20:21]
	global_store_dwordx4 v160, v[8:11], s[20:21] offset:64
	global_store_dwordx4 v160, v[4:7], s[20:21] offset:512
	global_store_dwordx4 v160, v[0:3], s[20:21] offset:576
	s_waitcnt vmcnt(0)
	s_barrier
	v_mov_b32_e32 v238, 0
	s_cmp_lg_u32 s48, 0
	s_cbranch_scc1 .Lres_nosig_p6
	buffer_wbl2 sc1
	s_waitcnt vmcnt(0)
	v_mov_b32_e32 v236, 1
	s_mov_b64 exec, 1
	global_atomic_add v238, v236, s[98:99]
	s_mov_b64 exec, -1
.Lres_nosig_p6:
	s_mov_b32 s67, 0
.Lres_spin_p6:
	global_load_dword v236, v238, s[98:99] sc1
	s_add_i32 s67, s67, 1
	s_waitcnt vmcnt(0)
	v_readfirstlane_b32 s36, v236
	s_cmp_ge_u32 s36, 4
	s_cbranch_scc1 .Lres_go_p6
	s_cmp_gt_u32 s67, 0x10000
	s_cbranch_scc1 .Lres_go_p6
	s_sleep 2
	s_branch .Lres_spin_p6
.Lres_go_p6:
	buffer_inv sc1
	v_mbcnt_lo_u32_b32 v232, -1, 0
	v_mbcnt_hi_u32_b32 v232, -1, v232
	v_lshlrev_b32_e32 v232, 4, v232
	s_lshl_b32 s3, s10, 2
	v_add_u32_e32 v233, s3, v232
	global_load_dwordx4 v[128:131], v233, s[0:1]
	s_lshr_b32 s36, s48, 6
	s_mul_i32 s38, s32, 64
	s_add_i32 s57, s38, 64
	s_min_u32 s57, s57, 0x100
	s_add_i32 s38, s38, s36
.Lres_rloop_p6:
	s_cmp_ge_u32 s38, s57
	s_cbranch_scc1 .Lres_end_p6
	s_add_i32 s36, s38, 0
	s_lshl_b32 s67, s36, 10
	v_add_u32_e32 v234, s67, v232
	s_mov_b64 s[20:21], s[34:35]
	global_load_dwordx4 v[144:147], v234, s[20:21]
	s_add_u32 s20, s20, 0x40000
	s_addc_u32 s21, s21, 0
	global_load_dwordx4 v[148:151], v234, s[20:21]
	s_add_u32 s20, s20, 0x40000
	s_addc_u32 s21, s21, 0
	global_load_dwordx4 v[152:155], v234, s[20:21]
	s_add_u32 s20, s20, 0x40000
	s_addc_u32 s21, s21, 0
	global_load_dwordx4 v[156:159], v234, s[20:21]
	s_add_i32 s36, s36, s4
	s_lshl_b32 s36, s36, 12
	s_add_i32 s36, s36, s3
	v_add_u32_e32 v235, s36, v232
	global_load_dwordx4 v[164:167], v235, s[12:13]
	s_add_i32 s36, s38, 8
	s_lshl_b32 s67, s36, 10
	v_add_u32_e32 v234, s67, v232
	s_mov_b64 s[20:21], s[34:35]
	global_load_dwordx4 v[168:171], v234, s[20:21]
	s_add_u32 s20, s20, 0x40000
	s_addc_u32 s21, s21, 0
	global_load_dwordx4 v[172:175], v234, s[20:21]
	s_add_u32 s20, s20, 0x40000
	s_addc_u32 s21, s21, 0
	global_load_dwordx4 v[198:201], v234, s[20:21]
	s_add_u32 s20, s20, 0x40000
	s_addc_u32 s21, s21, 0
	global_load_dwordx4 v[202:205], v234, s[20:21]
	s_add_i32 s36, s36, s4
	s_lshl_b32 s36, s36, 12
	s_add_i32 s36, s36, s3
	v_add_u32_e32 v237, s36, v232
	global_load_dwordx4 v[206:209], v237, s[12:13]
	s_waitcnt vmcnt(0)
	v_pk_add_f32 v[144:145], v[144:145], v[148:149]
	v_pk_add_f32 v[146:147], v[146:147], v[150:151]
	v_pk_add_f32 v[144:145], v[144:145], v[152:153]
	v_pk_add_f32 v[146:147], v[146:147], v[154:155]
	v_pk_add_f32 v[144:145], v[144:145], v[156:157]
	v_pk_add_f32 v[146:147], v[146:147], v[158:159]
	v_pk_fma_f32 v[144:145], v[144:145], v[128:129], v[164:165]
	v_pk_fma_f32 v[146:147], v[146:147], v[130:131], v[166:167]
	global_store_dwordx4 v235, v[144:147], s[12:13]
	v_pk_add_f32 v[168:169], v[168:169], v[172:173]
	v_pk_add_f32 v[170:171], v[170:171], v[174:175]
	v_pk_add_f32 v[168:169], v[168:169], v[198:199]
	v_pk_add_f32 v[170:171], v[170:171], v[200:201]
	v_pk_add_f32 v[168:169], v[168:169], v[202:203]
	v_pk_add_f32 v[170:171], v[170:171], v[204:205]
	v_pk_fma_f32 v[168:169], v[168:169], v[128:129], v[206:207]
	v_pk_fma_f32 v[170:171], v[170:171], v[130:131], v[208:209]
	global_store_dwordx4 v237, v[168:171], s[12:13]
	s_add_i32 s38, s38, 16
	s_branch .Lres_rloop_p6
.Lres_end_p6:
	s_branch .LBB0_347
.LBB0_491:
	s_mov_b64 s[4:5], 0

.LBB0_763:
	s_and_b64 vcc, exec, s[6:7]
	s_cbranch_vccz .LBB0_953
	v_readlane_b32 s28, v255, 8
	v_readlane_b32 s29, v255, 9
	s_lshl_b32 s28, s28, 1
	s_add_i32 s28, s28, s65
	s_lshl_b32 s29, s29, 1
	v_mbcnt_lo_u32_b32 v0, -1, 0
	v_mbcnt_hi_u32_b32 v0, -1, v0
	s_and_b32 s30, s48, 0xc0
	v_add_u32_e32 v1, s30, v0
	v_lshlrev_b32_e32 v1, 2, v1
	v_lshlrev_b32_e32 v2, 3, v0
	v_and_b32_e32 v5, 1, v0
	v_lshlrev_b32_e32 v5, 3, v5
	v_lshlrev_b32_e32 v3, 2, v0
	v_mov_b32_e32 v4, 0
.Lscan_loop:
	s_cmpk_gt_i32 s28, 0x1ff
	s_cbranch_scc1 .Lscan_done
	s_lshr_b32 s31, s28, 3
	s_and_b32 s34, s28, 7
	s_mul_i32 s0, s31, 0x84000
	s_lshl_b32 s1, s34, 10
	s_add_i32 s0, s0, s1
	s_add_u32 s22, s46, s0
	s_addc_u32 s23, s47, 0
	s_add_u32 s22, s22, 0xb9c8600
	s_addc_u32 s23, s23, 0
	s_mov_b64 s[24:25], s[22:23]
	global_load_dword v110, v1, s[22:23]
	s_add_u32 s22, s22, 0x2000
	s_addc_u32 s23, s23, 0
	global_load_dword v111, v1, s[22:23]
	s_add_u32 s22, s22, 0x2000
	s_addc_u32 s23, s23, 0
	global_load_dword v112, v1, s[22:23]
	s_add_u32 s22, s22, 0x2000
	s_addc_u32 s23, s23, 0
	global_load_dword v113, v1, s[22:23]
	s_add_u32 s22, s22, 0x2000
	s_addc_u32 s23, s23, 0
	global_load_dword v114, v1, s[22:23]
	s_add_u32 s22, s22, 0x2000
	s_addc_u32 s23, s23, 0
	global_load_dword v115, v1, s[22:23]
	s_add_u32 s22, s22, 0x2000
	s_addc_u32 s23, s23, 0
	global_load_dword v116, v1, s[22:23]
	s_add_u32 s22, s22, 0x2000
	s_addc_u32 s23, s23, 0
	global_load_dword v117, v1, s[22:23]
	s_add_u32 s22, s22, 0x2000
	s_addc_u32 s23, s23, 0
	global_load_dword v118, v1, s[22:23]
	s_add_u32 s22, s22, 0x2000
	s_addc_u32 s23, s23, 0
	global_load_dword v119, v1, s[22:23]
	s_add_u32 s22, s22, 0x2000
	s_addc_u32 s23, s23, 0
	global_load_dword v120, v1, s[22:23]
	s_add_u32 s22, s22, 0x2000
	s_addc_u32 s23, s23, 0
	global_load_dword v121, v1, s[22:23]
	s_add_u32 s22, s22, 0x2000
	s_addc_u32 s23, s23, 0
	global_load_dword v122, v1, s[22:23]
	s_add_u32 s22, s22, 0x2000
	s_addc_u32 s23, s23, 0
	global_load_dword v123, v1, s[22:23]
	s_add_u32 s22, s22, 0x2000
	s_addc_u32 s23, s23, 0
	global_load_dword v124, v1, s[22:23]
	s_add_u32 s22, s22, 0x2000
	s_addc_u32 s23, s23, 0
	global_load_dword v125, v1, s[22:23]
	s_add_u32 s22, s22, 0x2000
	s_addc_u32 s23, s23, 0
	global_load_dword v126, v1, s[22:23]
	s_add_u32 s22, s22, 0x2000
	s_addc_u32 s23, s23, 0
	global_load_dword v127, v1, s[22:23]
	s_add_u32 s22, s22, 0x2000
	s_addc_u32 s23, s23, 0
	global_load_dword v131, v1, s[22:23]
	s_add_u32 s22, s22, 0x2000
	s_addc_u32 s23, s23, 0
	global_load_dword v132, v1, s[22:23]
	s_add_u32 s22, s22, 0x2000
	s_addc_u32 s23, s23, 0
	global_load_dword v133, v1, s[22:23]
	s_add_u32 s22, s22, 0x2000
	s_addc_u32 s23, s23, 0
	global_load_dword v134, v1, s[22:23]
	s_add_u32 s22, s22, 0x2000
	s_addc_u32 s23, s23, 0
	global_load_dword v135, v1, s[22:23]
	s_add_u32 s22, s22, 0x2000
	s_addc_u32 s23, s23, 0
	global_load_dword v136, v1, s[22:23]
	s_add_u32 s22, s22, 0x2000
	s_addc_u32 s23, s23, 0
	global_load_dword v137, v1, s[22:23]
	s_add_u32 s22, s22, 0x2000
	s_addc_u32 s23, s23, 0
	global_load_dword v138, v1, s[22:23]
	s_add_u32 s22, s22, 0x2000
	s_addc_u32 s23, s23, 0
	global_load_dword v139, v1, s[22:23]
	s_add_u32 s22, s22, 0x2000
	s_addc_u32 s23, s23, 0
	global_load_dword v140, v1, s[22:23]
	s_add_u32 s22, s22, 0x2000
	s_addc_u32 s23, s23, 0
	global_load_dword v141, v1, s[22:23]
	s_add_u32 s22, s22, 0x2000
	s_addc_u32 s23, s23, 0
	global_load_dword v142, v1, s[22:23]
	s_add_u32 s22, s22, 0x2000
	s_addc_u32 s23, s23, 0
	global_load_dword v143, v1, s[22:23]
	s_add_u32 s22, s22, 0x2000
	s_addc_u32 s23, s23, 0
	global_load_dword v144, v1, s[22:23]
	s_add_u32 s22, s22, 0x2000
	s_addc_u32 s23, s23, 0
	global_load_dword v145, v1, s[22:23]
	s_add_u32 s22, s22, 0x2000
	s_addc_u32 s23, s23, 0
	global_load_dword v146, v1, s[22:23]
	s_add_u32 s22, s22, 0x2000
	s_addc_u32 s23, s23, 0
	global_load_dword v147, v1, s[22:23]
	s_add_u32 s22, s22, 0x2000
	s_addc_u32 s23, s23, 0
	global_load_dword v148, v1, s[22:23]
	s_add_u32 s22, s22, 0x2000
	s_addc_u32 s23, s23, 0
	global_load_dword v149, v1, s[22:23]
	s_add_u32 s22, s22, 0x2000
	s_addc_u32 s23, s23, 0
	global_load_dword v150, v1, s[22:23]
	s_add_u32 s22, s22, 0x2000
	s_addc_u32 s23, s23, 0
	global_load_dword v151, v1, s[22:23]
	s_add_u32 s22, s22, 0x2000
	s_addc_u32 s23, s23, 0
	global_load_dword v152, v1, s[22:23]
	s_add_u32 s22, s22, 0x2000
	s_addc_u32 s23, s23, 0
	global_load_dword v153, v1, s[22:23]
	s_add_u32 s22, s22, 0x2000
	s_addc_u32 s23, s23, 0
	global_load_dword v154, v1, s[22:23]
	s_add_u32 s22, s22, 0x2000
	s_addc_u32 s23, s23, 0
	global_load_dword v155, v1, s[22:23]
	s_add_u32 s22, s22, 0x2000
	s_addc_u32 s23, s23, 0
	global_load_dword v156, v1, s[22:23]
	s_add_u32 s22, s22, 0x2000
	s_addc_u32 s23, s23, 0
	global_load_dword v157, v1, s[22:23]
	s_add_u32 s22, s22, 0x2000
	s_addc_u32 s23, s23, 0
	global_load_dword v158, v1, s[22:23]
	s_add_u32 s22, s22, 0x2000
	s_addc_u32 s23, s23, 0
	global_load_dword v159, v1, s[22:23]
	s_add_u32 s22, s22, 0x2000
	s_addc_u32 s23, s23, 0
	global_load_dword v160, v1, s[22:23]
	s_add_u32 s22, s22, 0x2000
	s_addc_u32 s23, s23, 0
	global_load_dword v164, v1, s[22:23]
	s_add_u32 s22, s22, 0x2000
	s_addc_u32 s23, s23, 0
	global_load_dword v165, v1, s[22:23]
	s_add_u32 s22, s22, 0x2000
	s_addc_u32 s23, s23, 0
	global_load_dword v166, v1, s[22:23]
	s_add_u32 s22, s22, 0x2000
	s_addc_u32 s23, s23, 0
	global_load_dword v167, v1, s[22:23]
	s_add_u32 s22, s22, 0x2000
	s_addc_u32 s23, s23, 0
	global_load_dword v168, v1, s[22:23]
	s_add_u32 s22, s22, 0x2000
	s_addc_u32 s23, s23, 0
	global_load_dword v169, v1, s[22:23]
	s_add_u32 s22, s22, 0x2000
	s_addc_u32 s23, s23, 0
	global_load_dword v170, v1, s[22:23]
	s_add_u32 s22, s22, 0x2000
	s_addc_u32 s23, s23, 0
	global_load_dword v171, v1, s[22:23]
	s_add_u32 s22, s22, 0x2000
	s_addc_u32 s23, s23, 0
	global_load_dword v172, v1, s[22:23]
	s_add_u32 s22, s22, 0x2000
	s_addc_u32 s23, s23, 0
	global_load_dword v173, v1, s[22:23]
	s_add_u32 s22, s22, 0x2000
	s_addc_u32 s23, s23, 0
	global_load_dword v174, v1, s[22:23]
	s_add_u32 s22, s22, 0x2000
	s_addc_u32 s23, s23, 0
	global_load_dword v175, v1, s[22:23]
	s_add_u32 s22, s22, 0x2000
	s_addc_u32 s23, s23, 0
	global_load_dword v198, v1, s[22:23]
	s_add_u32 s22, s22, 0x2000
	s_addc_u32 s23, s23, 0
	global_load_dword v199, v1, s[22:23]
	s_add_u32 s22, s22, 0x2000
	s_addc_u32 s23, s23, 0
	global_load_dword v200, v1, s[22:23]
	s_add_u32 s22, s22, 0x2000
	s_addc_u32 s23, s23, 0
	global_load_dword v201, v1, s[22:23]
	s_add_u32 s22, s22, 0x2000
	s_addc_u32 s23, s23, 0
	global_load_dword v202, v1, s[22:23]
	s_add_u32 s22, s22, 0x2000
	s_addc_u32 s23, s23, 0
	global_load_dword v203, v1, s[22:23]
	v_mov_b32_e32 v16, 0
	v_mov_b32_e32 v17, 0
	s_cmp_lt_u32 s31, 32
	s_cbranch_scc1 .Lscan_type0
	s_mul_i32 s0, s31, 0x210
	s_add_u32 s26, s46, s0
	s_addc_u32 s27, s47, 0
	s_add_u32 s26, s26, 0x33ac000
	s_addc_u32 s27, s27, 0
	global_load_dwordx2 v[6:7], v2, s[26:27]
	global_load_dwordx2 v[8:9], v5, s[26:27] offset:512
	v_mov_b32_e32 v10, 0
	s_or_b32 s0, s34, s30
	s_cmp_eq_u32 s0, 0
	s_cbranch_scc1 .Lscan_v2
	s_waitcnt vmcnt(0)
	v_readlane_b32 s0, v6, 0
	v_readlane_b32 s1, v7, 0
	s_nop 2
	v_readlane_b32 s2, v6, 1
	v_readlane_b32 s3, v7, 1
	v_add_f32_e32 v12, s1, v10
	v_max_f32_e32 v11, s0, v12
	v_sub_f32_e32 v12, v12, v11
	v_sub_f32_e32 v13, s0, v11
	v_mul_f32_e32 v12, 0x3fb8aa3b, v12
	v_mul_f32_e32 v13, 0x3fb8aa3b, v13
	v_exp_f32_e32 v14, v12
	v_exp_f32_e32 v15, v13
	v_cvt_pk_bf16_f32 v20, v16, v17
	global_store_dword v1, v20, s[24:25]
	s_add_u32 s24, s24, 0x2000
	s_addc_u32 s25, s25, 0
	v_lshlrev_b32_e32 v18, 16, v110
	v_and_b32_e32 v19, 0xffff0000, v110
	v_mul_f32_e32 v16, v16, v14
	v_mul_f32_e32 v17, v17, v14
	v_fmac_f32_e32 v16, v15, v18
	v_fmac_f32_e32 v17, v15, v19
	v_readlane_b32 s0, v6, 2
	v_readlane_b32 s1, v7, 2
	v_add_f32_e32 v12, s3, v11
	v_max_f32_e32 v10, s2, v12
	v_sub_f32_e32 v12, v12, v10
	v_sub_f32_e32 v13, s2, v10
	v_mul_f32_e32 v12, 0x3fb8aa3b, v12
	v_mul_f32_e32 v13, 0x3fb8aa3b, v13
	v_exp_f32_e32 v14, v12
	v_exp_f32_e32 v15, v13
	v_cvt_pk_bf16_f32 v21, v16, v17
	global_store_dword v1, v21, s[24:25]
	s_add_u32 s24, s24, 0x2000
	s_addc_u32 s25, s25, 0
	v_lshlrev_b32_e32 v18, 16, v111
	v_and_b32_e32 v19, 0xffff0000, v111
	v_mul_f32_e32 v16, v16, v14
	v_mul_f32_e32 v17, v17, v14
	v_fmac_f32_e32 v16, v15, v18
	v_fmac_f32_e32 v17, v15, v19
	v_readlane_b32 s2, v6, 3
	v_readlane_b32 s3, v7, 3
	v_add_f32_e32 v12, s1, v10
	v_max_f32_e32 v11, s0, v12
	v_sub_f32_e32 v12, v12, v11
	v_sub_f32_e32 v13, s0, v11
	v_mul_f32_e32 v12, 0x3fb8aa3b, v12
	v_mul_f32_e32 v13, 0x3fb8aa3b, v13
	v_exp_f32_e32 v14, v12
	v_exp_f32_e32 v15, v13
	v_cvt_pk_bf16_f32 v20, v16, v17
	global_store_dword v1, v20, s[24:25]
	s_add_u32 s24, s24, 0x2000
	s_addc_u32 s25, s25, 0
	v_lshlrev_b32_e32 v18, 16, v112
	v_and_b32_e32 v19, 0xffff0000, v112
	v_mul_f32_e32 v16, v16, v14
	v_mul_f32_e32 v17, v17, v14
	v_fmac_f32_e32 v16, v15, v18
	v_fmac_f32_e32 v17, v15, v19
	v_readlane_b32 s0, v6, 4
	v_readlane_b32 s1, v7, 4
	v_add_f32_e32 v12, s3, v11
	v_max_f32_e32 v10, s2, v12
	v_sub_f32_e32 v12, v12, v10
	v_sub_f32_e32 v13, s2, v10
	v_mul_f32_e32 v12, 0x3fb8aa3b, v12
	v_mul_f32_e32 v13, 0x3fb8aa3b, v13
	v_exp_f32_e32 v14, v12
	v_exp_f32_e32 v15, v13
	v_cvt_pk_bf16_f32 v21, v16, v17
	global_store_dword v1, v21, s[24:25]
	s_add_u32 s24, s24, 0x2000
	s_addc_u32 s25, s25, 0
	v_lshlrev_b32_e32 v18, 16, v113
	v_and_b32_e32 v19, 0xffff0000, v113
	v_mul_f32_e32 v16, v16, v14
	v_mul_f32_e32 v17, v17, v14
	v_fmac_f32_e32 v16, v15, v18
	v_fmac_f32_e32 v17, v15, v19
	v_readlane_b32 s2, v6, 5
	v_readlane_b32 s3, v7, 5
	v_add_f32_e32 v12, s1, v10
	v_max_f32_e32 v11, s0, v12
	v_sub_f32_e32 v12, v12, v11
	v_sub_f32_e32 v13, s0, v11
	v_mul_f32_e32 v12, 0x3fb8aa3b, v12
	v_mul_f32_e32 v13, 0x3fb8aa3b, v13
	v_exp_f32_e32 v14, v12
	v_exp_f32_e32 v15, v13
	v_cvt_pk_bf16_f32 v20, v16, v17
	global_store_dword v1, v20, s[24:25]
	s_add_u32 s24, s24, 0x2000
	s_addc_u32 s25, s25, 0
	v_lshlrev_b32_e32 v18, 16, v114
	v_and_b32_e32 v19, 0xffff0000, v114
	v_mul_f32_e32 v16, v16, v14
	v_mul_f32_e32 v17, v17, v14
	v_fmac_f32_e32 v16, v15, v18
	v_fmac_f32_e32 v17, v15, v19
	v_readlane_b32 s0, v6, 6
	v_readlane_b32 s1, v7, 6
	v_add_f32_e32 v12, s3, v11
	v_max_f32_e32 v10, s2, v12
	v_sub_f32_e32 v12, v12, v10
	v_sub_f32_e32 v13, s2, v10
	v_mul_f32_e32 v12, 0x3fb8aa3b, v12
	v_mul_f32_e32 v13, 0x3fb8aa3b, v13
	v_exp_f32_e32 v14, v12
	v_exp_f32_e32 v15, v13
	v_cvt_pk_bf16_f32 v21, v16, v17
	global_store_dword v1, v21, s[24:25]
	s_add_u32 s24, s24, 0x2000
	s_addc_u32 s25, s25, 0
	v_lshlrev_b32_e32 v18, 16, v115
	v_and_b32_e32 v19, 0xffff0000, v115
	v_mul_f32_e32 v16, v16, v14
	v_mul_f32_e32 v17, v17, v14
	v_fmac_f32_e32 v16, v15, v18
	v_fmac_f32_e32 v17, v15, v19
	v_readlane_b32 s2, v6, 7
	v_readlane_b32 s3, v7, 7
	v_add_f32_e32 v12, s1, v10
	v_max_f32_e32 v11, s0, v12
	v_sub_f32_e32 v12, v12, v11
	v_sub_f32_e32 v13, s0, v11
	v_mul_f32_e32 v12, 0x3fb8aa3b, v12
	v_mul_f32_e32 v13, 0x3fb8aa3b, v13
	v_exp_f32_e32 v14, v12
	v_exp_f32_e32 v15, v13
	v_cvt_pk_bf16_f32 v20, v16, v17
	global_store_dword v1, v20, s[24:25]
	s_add_u32 s24, s24, 0x2000
	s_addc_u32 s25, s25, 0
	v_lshlrev_b32_e32 v18, 16, v116
	v_and_b32_e32 v19, 0xffff0000, v116
	v_mul_f32_e32 v16, v16, v14
	v_mul_f32_e32 v17, v17, v14
	v_fmac_f32_e32 v16, v15, v18
	v_fmac_f32_e32 v17, v15, v19
	v_readlane_b32 s0, v6, 8
	v_readlane_b32 s1, v7, 8
	v_add_f32_e32 v12, s3, v11
	v_max_f32_e32 v10, s2, v12
	v_sub_f32_e32 v12, v12, v10
	v_sub_f32_e32 v13, s2, v10
	v_mul_f32_e32 v12, 0x3fb8aa3b, v12
	v_mul_f32_e32 v13, 0x3fb8aa3b, v13
	v_exp_f32_e32 v14, v12
	v_exp_f32_e32 v15, v13
	v_cvt_pk_bf16_f32 v21, v16, v17
	global_store_dword v1, v21, s[24:25]
	s_add_u32 s24, s24, 0x2000
	s_addc_u32 s25, s25, 0
	v_lshlrev_b32_e32 v18, 16, v117
	v_and_b32_e32 v19, 0xffff0000, v117
	v_mul_f32_e32 v16, v16, v14
	v_mul_f32_e32 v17, v17, v14
	v_fmac_f32_e32 v16, v15, v18
	v_fmac_f32_e32 v17, v15, v19
	v_readlane_b32 s2, v6, 9
	v_readlane_b32 s3, v7, 9
	v_add_f32_e32 v12, s1, v10
	v_max_f32_e32 v11, s0, v12
	v_sub_f32_e32 v12, v12, v11
	v_sub_f32_e32 v13, s0, v11
	v_mul_f32_e32 v12, 0x3fb8aa3b, v12
	v_mul_f32_e32 v13, 0x3fb8aa3b, v13
	v_exp_f32_e32 v14, v12
	v_exp_f32_e32 v15, v13
	v_cvt_pk_bf16_f32 v20, v16, v17
	global_store_dword v1, v20, s[24:25]
	s_add_u32 s24, s24, 0x2000
	s_addc_u32 s25, s25, 0
	v_lshlrev_b32_e32 v18, 16, v118
	v_and_b32_e32 v19, 0xffff0000, v118
	v_mul_f32_e32 v16, v16, v14
	v_mul_f32_e32 v17, v17, v14
	v_fmac_f32_e32 v16, v15, v18
	v_fmac_f32_e32 v17, v15, v19
	v_readlane_b32 s0, v6, 10
	v_readlane_b32 s1, v7, 10
	v_add_f32_e32 v12, s3, v11
	v_max_f32_e32 v10, s2, v12
	v_sub_f32_e32 v12, v12, v10
	v_sub_f32_e32 v13, s2, v10
	v_mul_f32_e32 v12, 0x3fb8aa3b, v12
	v_mul_f32_e32 v13, 0x3fb8aa3b, v13
	v_exp_f32_e32 v14, v12
	v_exp_f32_e32 v15, v13
	v_cvt_pk_bf16_f32 v21, v16, v17
	global_store_dword v1, v21, s[24:25]
	s_add_u32 s24, s24, 0x2000
	s_addc_u32 s25, s25, 0
	v_lshlrev_b32_e32 v18, 16, v119
	v_and_b32_e32 v19, 0xffff0000, v119
	v_mul_f32_e32 v16, v16, v14
	v_mul_f32_e32 v17, v17, v14
	v_fmac_f32_e32 v16, v15, v18
	v_fmac_f32_e32 v17, v15, v19
	v_readlane_b32 s2, v6, 11
	v_readlane_b32 s3, v7, 11
	v_add_f32_e32 v12, s1, v10
	v_max_f32_e32 v11, s0, v12
	v_sub_f32_e32 v12, v12, v11
	v_sub_f32_e32 v13, s0, v11
	v_mul_f32_e32 v12, 0x3fb8aa3b, v12
	v_mul_f32_e32 v13, 0x3fb8aa3b, v13
	v_exp_f32_e32 v14, v12
	v_exp_f32_e32 v15, v13
	v_cvt_pk_bf16_f32 v20, v16, v17
	global_store_dword v1, v20, s[24:25]
	s_add_u32 s24, s24, 0x2000
	s_addc_u32 s25, s25, 0
	v_lshlrev_b32_e32 v18, 16, v120
	v_and_b32_e32 v19, 0xffff0000, v120
	v_mul_f32_e32 v16, v16, v14
	v_mul_f32_e32 v17, v17, v14
	v_fmac_f32_e32 v16, v15, v18
	v_fmac_f32_e32 v17, v15, v19
	v_readlane_b32 s0, v6, 12
	v_readlane_b32 s1, v7, 12
	v_add_f32_e32 v12, s3, v11
	v_max_f32_e32 v10, s2, v12
	v_sub_f32_e32 v12, v12, v10
	v_sub_f32_e32 v13, s2, v10
	v_mul_f32_e32 v12, 0x3fb8aa3b, v12
	v_mul_f32_e32 v13, 0x3fb8aa3b, v13
	v_exp_f32_e32 v14, v12
	v_exp_f32_e32 v15, v13
	v_cvt_pk_bf16_f32 v21, v16, v17
	global_store_dword v1, v21, s[24:25]
	s_add_u32 s24, s24, 0x2000
	s_addc_u32 s25, s25, 0
	v_lshlrev_b32_e32 v18, 16, v121
	v_and_b32_e32 v19, 0xffff0000, v121
	v_mul_f32_e32 v16, v16, v14
	v_mul_f32_e32 v17, v17, v14
	v_fmac_f32_e32 v16, v15, v18
	v_fmac_f32_e32 v17, v15, v19
	v_readlane_b32 s2, v6, 13
	v_readlane_b32 s3, v7, 13
	v_add_f32_e32 v12, s1, v10
	v_max_f32_e32 v11, s0, v12
	v_sub_f32_e32 v12, v12, v11
	v_sub_f32_e32 v13, s0, v11
	v_mul_f32_e32 v12, 0x3fb8aa3b, v12
	v_mul_f32_e32 v13, 0x3fb8aa3b, v13
	v_exp_f32_e32 v14, v12
	v_exp_f32_e32 v15, v13
	v_cvt_pk_bf16_f32 v20, v16, v17
	global_store_dword v1, v20, s[24:25]
	s_add_u32 s24, s24, 0x2000
	s_addc_u32 s25, s25, 0
	v_lshlrev_b32_e32 v18, 16, v122
	v_and_b32_e32 v19, 0xffff0000, v122
	v_mul_f32_e32 v16, v16, v14
	v_mul_f32_e32 v17, v17, v14
	v_fmac_f32_e32 v16, v15, v18
	v_fmac_f32_e32 v17, v15, v19
	v_readlane_b32 s0, v6, 14
	v_readlane_b32 s1, v7, 14
	v_add_f32_e32 v12, s3, v11
	v_max_f32_e32 v10, s2, v12
	v_sub_f32_e32 v12, v12, v10
	v_sub_f32_e32 v13, s2, v10
	v_mul_f32_e32 v12, 0x3fb8aa3b, v12
	v_mul_f32_e32 v13, 0x3fb8aa3b, v13
	v_exp_f32_e32 v14, v12
	v_exp_f32_e32 v15, v13
	v_cvt_pk_bf16_f32 v21, v16, v17
	global_store_dword v1, v21, s[24:25]
	s_add_u32 s24, s24, 0x2000
	s_addc_u32 s25, s25, 0
	v_lshlrev_b32_e32 v18, 16, v123
	v_and_b32_e32 v19, 0xffff0000, v123
	v_mul_f32_e32 v16, v16, v14
	v_mul_f32_e32 v17, v17, v14
	v_fmac_f32_e32 v16, v15, v18
	v_fmac_f32_e32 v17, v15, v19
	v_readlane_b32 s2, v6, 15
	v_readlane_b32 s3, v7, 15
	v_add_f32_e32 v12, s1, v10
	v_max_f32_e32 v11, s0, v12
	v_sub_f32_e32 v12, v12, v11
	v_sub_f32_e32 v13, s0, v11
	v_mul_f32_e32 v12, 0x3fb8aa3b, v12
	v_mul_f32_e32 v13, 0x3fb8aa3b, v13
	v_exp_f32_e32 v14, v12
	v_exp_f32_e32 v15, v13
	v_cvt_pk_bf16_f32 v20, v16, v17
	global_store_dword v1, v20, s[24:25]
	s_add_u32 s24, s24, 0x2000
	s_addc_u32 s25, s25, 0
	v_lshlrev_b32_e32 v18, 16, v124
	v_and_b32_e32 v19, 0xffff0000, v124
	v_mul_f32_e32 v16, v16, v14
	v_mul_f32_e32 v17, v17, v14
	v_fmac_f32_e32 v16, v15, v18
	v_fmac_f32_e32 v17, v15, v19
	v_readlane_b32 s0, v6, 16
	v_readlane_b32 s1, v7, 16
	v_add_f32_e32 v12, s3, v11
	v_max_f32_e32 v10, s2, v12
	v_sub_f32_e32 v12, v12, v10
	v_sub_f32_e32 v13, s2, v10
	v_mul_f32_e32 v12, 0x3fb8aa3b, v12
	v_mul_f32_e32 v13, 0x3fb8aa3b, v13
	v_exp_f32_e32 v14, v12
	v_exp_f32_e32 v15, v13
	v_cvt_pk_bf16_f32 v21, v16, v17
	global_store_dword v1, v21, s[24:25]
	s_add_u32 s24, s24, 0x2000
	s_addc_u32 s25, s25, 0
	v_lshlrev_b32_e32 v18, 16, v125
	v_and_b32_e32 v19, 0xffff0000, v125
	v_mul_f32_e32 v16, v16, v14
	v_mul_f32_e32 v17, v17, v14
	v_fmac_f32_e32 v16, v15, v18
	v_fmac_f32_e32 v17, v15, v19
	v_readlane_b32 s2, v6, 17
	v_readlane_b32 s3, v7, 17
	v_add_f32_e32 v12, s1, v10
	v_max_f32_e32 v11, s0, v12
	v_sub_f32_e32 v12, v12, v11
	v_sub_f32_e32 v13, s0, v11
	v_mul_f32_e32 v12, 0x3fb8aa3b, v12
	v_mul_f32_e32 v13, 0x3fb8aa3b, v13
	v_exp_f32_e32 v14, v12
	v_exp_f32_e32 v15, v13
	v_cvt_pk_bf16_f32 v20, v16, v17
	global_store_dword v1, v20, s[24:25]
	s_add_u32 s24, s24, 0x2000
	s_addc_u32 s25, s25, 0
	v_lshlrev_b32_e32 v18, 16, v126
	v_and_b32_e32 v19, 0xffff0000, v126
	v_mul_f32_e32 v16, v16, v14
	v_mul_f32_e32 v17, v17, v14
	v_fmac_f32_e32 v16, v15, v18
	v_fmac_f32_e32 v17, v15, v19
	v_readlane_b32 s0, v6, 18
	v_readlane_b32 s1, v7, 18
	v_add_f32_e32 v12, s3, v11
	v_max_f32_e32 v10, s2, v12
	v_sub_f32_e32 v12, v12, v10
	v_sub_f32_e32 v13, s2, v10
	v_mul_f32_e32 v12, 0x3fb8aa3b, v12
	v_mul_f32_e32 v13, 0x3fb8aa3b, v13
	v_exp_f32_e32 v14, v12
	v_exp_f32_e32 v15, v13
	v_cvt_pk_bf16_f32 v21, v16, v17
	global_store_dword v1, v21, s[24:25]
	s_add_u32 s24, s24, 0x2000
	s_addc_u32 s25, s25, 0
	v_lshlrev_b32_e32 v18, 16, v127
	v_and_b32_e32 v19, 0xffff0000, v127
	v_mul_f32_e32 v16, v16, v14
	v_mul_f32_e32 v17, v17, v14
	v_fmac_f32_e32 v16, v15, v18
	v_fmac_f32_e32 v17, v15, v19
	v_readlane_b32 s2, v6, 19
	v_readlane_b32 s3, v7, 19
	v_add_f32_e32 v12, s1, v10
	v_max_f32_e32 v11, s0, v12
	v_sub_f32_e32 v12, v12, v11
	v_sub_f32_e32 v13, s0, v11
	v_mul_f32_e32 v12, 0x3fb8aa3b, v12
	v_mul_f32_e32 v13, 0x3fb8aa3b, v13
	v_exp_f32_e32 v14, v12
	v_exp_f32_e32 v15, v13
	v_cvt_pk_bf16_f32 v20, v16, v17
	global_store_dword v1, v20, s[24:25]
	s_add_u32 s24, s24, 0x2000
	s_addc_u32 s25, s25, 0
	v_lshlrev_b32_e32 v18, 16, v131
	v_and_b32_e32 v19, 0xffff0000, v131
	v_mul_f32_e32 v16, v16, v14
	v_mul_f32_e32 v17, v17, v14
	v_fmac_f32_e32 v16, v15, v18
	v_fmac_f32_e32 v17, v15, v19
	v_readlane_b32 s0, v6, 20
	v_readlane_b32 s1, v7, 20
	v_add_f32_e32 v12, s3, v11
	v_max_f32_e32 v10, s2, v12
	v_sub_f32_e32 v12, v12, v10
	v_sub_f32_e32 v13, s2, v10
	v_mul_f32_e32 v12, 0x3fb8aa3b, v12
	v_mul_f32_e32 v13, 0x3fb8aa3b, v13
	v_exp_f32_e32 v14, v12
	v_exp_f32_e32 v15, v13
	v_cvt_pk_bf16_f32 v21, v16, v17
	global_store_dword v1, v21, s[24:25]
	s_add_u32 s24, s24, 0x2000
	s_addc_u32 s25, s25, 0
	v_lshlrev_b32_e32 v18, 16, v132
	v_and_b32_e32 v19, 0xffff0000, v132
	v_mul_f32_e32 v16, v16, v14
	v_mul_f32_e32 v17, v17, v14
	v_fmac_f32_e32 v16, v15, v18
	v_fmac_f32_e32 v17, v15, v19
	v_readlane_b32 s2, v6, 21
	v_readlane_b32 s3, v7, 21
	v_add_f32_e32 v12, s1, v10
	v_max_f32_e32 v11, s0, v12
	v_sub_f32_e32 v12, v12, v11
	v_sub_f32_e32 v13, s0, v11
	v_mul_f32_e32 v12, 0x3fb8aa3b, v12
	v_mul_f32_e32 v13, 0x3fb8aa3b, v13
	v_exp_f32_e32 v14, v12
	v_exp_f32_e32 v15, v13
	v_cvt_pk_bf16_f32 v20, v16, v17
	global_store_dword v1, v20, s[24:25]
	s_add_u32 s24, s24, 0x2000
	s_addc_u32 s25, s25, 0
	v_lshlrev_b32_e32 v18, 16, v133
	v_and_b32_e32 v19, 0xffff0000, v133
	v_mul_f32_e32 v16, v16, v14
	v_mul_f32_e32 v17, v17, v14
	v_fmac_f32_e32 v16, v15, v18
	v_fmac_f32_e32 v17, v15, v19
	v_readlane_b32 s0, v6, 22
	v_readlane_b32 s1, v7, 22
	v_add_f32_e32 v12, s3, v11
	v_max_f32_e32 v10, s2, v12
	v_sub_f32_e32 v12, v12, v10
	v_sub_f32_e32 v13, s2, v10
	v_mul_f32_e32 v12, 0x3fb8aa3b, v12
	v_mul_f32_e32 v13, 0x3fb8aa3b, v13
	v_exp_f32_e32 v14, v12
	v_exp_f32_e32 v15, v13
	v_cvt_pk_bf16_f32 v21, v16, v17
	global_store_dword v1, v21, s[24:25]
	s_add_u32 s24, s24, 0x2000
	s_addc_u32 s25, s25, 0
	v_lshlrev_b32_e32 v18, 16, v134
	v_and_b32_e32 v19, 0xffff0000, v134
	v_mul_f32_e32 v16, v16, v14
	v_mul_f32_e32 v17, v17, v14
	v_fmac_f32_e32 v16, v15, v18
	v_fmac_f32_e32 v17, v15, v19
	v_readlane_b32 s2, v6, 23
	v_readlane_b32 s3, v7, 23
	v_add_f32_e32 v12, s1, v10
	v_max_f32_e32 v11, s0, v12
	v_sub_f32_e32 v12, v12, v11
	v_sub_f32_e32 v13, s0, v11
	v_mul_f32_e32 v12, 0x3fb8aa3b, v12
	v_mul_f32_e32 v13, 0x3fb8aa3b, v13
	v_exp_f32_e32 v14, v12
	v_exp_f32_e32 v15, v13
	v_cvt_pk_bf16_f32 v20, v16, v17
	global_store_dword v1, v20, s[24:25]
	s_add_u32 s24, s24, 0x2000
	s_addc_u32 s25, s25, 0
	v_lshlrev_b32_e32 v18, 16, v135
	v_and_b32_e32 v19, 0xffff0000, v135
	v_mul_f32_e32 v16, v16, v14
	v_mul_f32_e32 v17, v17, v14
	v_fmac_f32_e32 v16, v15, v18
	v_fmac_f32_e32 v17, v15, v19
	v_readlane_b32 s0, v6, 24
	v_readlane_b32 s1, v7, 24
	v_add_f32_e32 v12, s3, v11
	v_max_f32_e32 v10, s2, v12
	v_sub_f32_e32 v12, v12, v10
	v_sub_f32_e32 v13, s2, v10
	v_mul_f32_e32 v12, 0x3fb8aa3b, v12
	v_mul_f32_e32 v13, 0x3fb8aa3b, v13
	v_exp_f32_e32 v14, v12
	v_exp_f32_e32 v15, v13
	v_cvt_pk_bf16_f32 v21, v16, v17
	global_store_dword v1, v21, s[24:25]
	s_add_u32 s24, s24, 0x2000
	s_addc_u32 s25, s25, 0
	v_lshlrev_b32_e32 v18, 16, v136
	v_and_b32_e32 v19, 0xffff0000, v136
	v_mul_f32_e32 v16, v16, v14
	v_mul_f32_e32 v17, v17, v14
	v_fmac_f32_e32 v16, v15, v18
	v_fmac_f32_e32 v17, v15, v19
	v_readlane_b32 s2, v6, 25
	v_readlane_b32 s3, v7, 25
	v_add_f32_e32 v12, s1, v10
	v_max_f32_e32 v11, s0, v12
	v_sub_f32_e32 v12, v12, v11
	v_sub_f32_e32 v13, s0, v11
	v_mul_f32_e32 v12, 0x3fb8aa3b, v12
	v_mul_f32_e32 v13, 0x3fb8aa3b, v13
	v_exp_f32_e32 v14, v12
	v_exp_f32_e32 v15, v13
	v_cvt_pk_bf16_f32 v20, v16, v17
	global_store_dword v1, v20, s[24:25]
	s_add_u32 s24, s24, 0x2000
	s_addc_u32 s25, s25, 0
	v_lshlrev_b32_e32 v18, 16, v137
	v_and_b32_e32 v19, 0xffff0000, v137
	v_mul_f32_e32 v16, v16, v14
	v_mul_f32_e32 v17, v17, v14
	v_fmac_f32_e32 v16, v15, v18
	v_fmac_f32_e32 v17, v15, v19
	v_readlane_b32 s0, v6, 26
	v_readlane_b32 s1, v7, 26
	v_add_f32_e32 v12, s3, v11
	v_max_f32_e32 v10, s2, v12
	v_sub_f32_e32 v12, v12, v10
	v_sub_f32_e32 v13, s2, v10
	v_mul_f32_e32 v12, 0x3fb8aa3b, v12
	v_mul_f32_e32 v13, 0x3fb8aa3b, v13
	v_exp_f32_e32 v14, v12
	v_exp_f32_e32 v15, v13
	v_cvt_pk_bf16_f32 v21, v16, v17
	global_store_dword v1, v21, s[24:25]
	s_add_u32 s24, s24, 0x2000
	s_addc_u32 s25, s25, 0
	v_lshlrev_b32_e32 v18, 16, v138
	v_and_b32_e32 v19, 0xffff0000, v138
	v_mul_f32_e32 v16, v16, v14
	v_mul_f32_e32 v17, v17, v14
	v_fmac_f32_e32 v16, v15, v18
	v_fmac_f32_e32 v17, v15, v19
	v_readlane_b32 s2, v6, 27
	v_readlane_b32 s3, v7, 27
	v_add_f32_e32 v12, s1, v10
	v_max_f32_e32 v11, s0, v12
	v_sub_f32_e32 v12, v12, v11
	v_sub_f32_e32 v13, s0, v11
	v_mul_f32_e32 v12, 0x3fb8aa3b, v12
	v_mul_f32_e32 v13, 0x3fb8aa3b, v13
	v_exp_f32_e32 v14, v12
	v_exp_f32_e32 v15, v13
	v_cvt_pk_bf16_f32 v20, v16, v17
	global_store_dword v1, v20, s[24:25]
	s_add_u32 s24, s24, 0x2000
	s_addc_u32 s25, s25, 0
	v_lshlrev_b32_e32 v18, 16, v139
	v_and_b32_e32 v19, 0xffff0000, v139
	v_mul_f32_e32 v16, v16, v14
	v_mul_f32_e32 v17, v17, v14
	v_fmac_f32_e32 v16, v15, v18
	v_fmac_f32_e32 v17, v15, v19
	v_readlane_b32 s0, v6, 28
	v_readlane_b32 s1, v7, 28
	v_add_f32_e32 v12, s3, v11
	v_max_f32_e32 v10, s2, v12
	v_sub_f32_e32 v12, v12, v10
	v_sub_f32_e32 v13, s2, v10
	v_mul_f32_e32 v12, 0x3fb8aa3b, v12
	v_mul_f32_e32 v13, 0x3fb8aa3b, v13
	v_exp_f32_e32 v14, v12
	v_exp_f32_e32 v15, v13
	v_cvt_pk_bf16_f32 v21, v16, v17
	global_store_dword v1, v21, s[24:25]
	s_add_u32 s24, s24, 0x2000
	s_addc_u32 s25, s25, 0
	v_lshlrev_b32_e32 v18, 16, v140
	v_and_b32_e32 v19, 0xffff0000, v140
	v_mul_f32_e32 v16, v16, v14
	v_mul_f32_e32 v17, v17, v14
	v_fmac_f32_e32 v16, v15, v18
	v_fmac_f32_e32 v17, v15, v19
	v_readlane_b32 s2, v6, 29
	v_readlane_b32 s3, v7, 29
	v_add_f32_e32 v12, s1, v10
	v_max_f32_e32 v11, s0, v12
	v_sub_f32_e32 v12, v12, v11
	v_sub_f32_e32 v13, s0, v11
	v_mul_f32_e32 v12, 0x3fb8aa3b, v12
	v_mul_f32_e32 v13, 0x3fb8aa3b, v13
	v_exp_f32_e32 v14, v12
	v_exp_f32_e32 v15, v13
	v_cvt_pk_bf16_f32 v20, v16, v17
	global_store_dword v1, v20, s[24:25]
	s_add_u32 s24, s24, 0x2000
	s_addc_u32 s25, s25, 0
	v_lshlrev_b32_e32 v18, 16, v141
	v_and_b32_e32 v19, 0xffff0000, v141
	v_mul_f32_e32 v16, v16, v14
	v_mul_f32_e32 v17, v17, v14
	v_fmac_f32_e32 v16, v15, v18
	v_fmac_f32_e32 v17, v15, v19
	v_readlane_b32 s0, v6, 30
	v_readlane_b32 s1, v7, 30
	v_add_f32_e32 v12, s3, v11
	v_max_f32_e32 v10, s2, v12
	v_sub_f32_e32 v12, v12, v10
	v_sub_f32_e32 v13, s2, v10
	v_mul_f32_e32 v12, 0x3fb8aa3b, v12
	v_mul_f32_e32 v13, 0x3fb8aa3b, v13
	v_exp_f32_e32 v14, v12
	v_exp_f32_e32 v15, v13
	v_cvt_pk_bf16_f32 v21, v16, v17
	global_store_dword v1, v21, s[24:25]
	s_add_u32 s24, s24, 0x2000
	s_addc_u32 s25, s25, 0
	v_lshlrev_b32_e32 v18, 16, v142
	v_and_b32_e32 v19, 0xffff0000, v142
	v_mul_f32_e32 v16, v16, v14
	v_mul_f32_e32 v17, v17, v14
	v_fmac_f32_e32 v16, v15, v18
	v_fmac_f32_e32 v17, v15, v19
	v_readlane_b32 s2, v6, 31
	v_readlane_b32 s3, v7, 31
	v_add_f32_e32 v12, s1, v10
	v_max_f32_e32 v11, s0, v12
	v_sub_f32_e32 v12, v12, v11
	v_sub_f32_e32 v13, s0, v11
	v_mul_f32_e32 v12, 0x3fb8aa3b, v12
	v_mul_f32_e32 v13, 0x3fb8aa3b, v13
	v_exp_f32_e32 v14, v12
	v_exp_f32_e32 v15, v13
	v_cvt_pk_bf16_f32 v20, v16, v17
	global_store_dword v1, v20, s[24:25]
	s_add_u32 s24, s24, 0x2000
	s_addc_u32 s25, s25, 0
	v_lshlrev_b32_e32 v18, 16, v143
	v_and_b32_e32 v19, 0xffff0000, v143
	v_mul_f32_e32 v16, v16, v14
	v_mul_f32_e32 v17, v17, v14
	v_fmac_f32_e32 v16, v15, v18
	v_fmac_f32_e32 v17, v15, v19
	v_readlane_b32 s0, v6, 32
	v_readlane_b32 s1, v7, 32
	v_add_f32_e32 v12, s3, v11
	v_max_f32_e32 v10, s2, v12
	v_sub_f32_e32 v12, v12, v10
	v_sub_f32_e32 v13, s2, v10
	v_mul_f32_e32 v12, 0x3fb8aa3b, v12
	v_mul_f32_e32 v13, 0x3fb8aa3b, v13
	v_exp_f32_e32 v14, v12
	v_exp_f32_e32 v15, v13
	v_cvt_pk_bf16_f32 v21, v16, v17
	global_store_dword v1, v21, s[24:25]
	s_add_u32 s24, s24, 0x2000
	s_addc_u32 s25, s25, 0
	v_lshlrev_b32_e32 v18, 16, v144
	v_and_b32_e32 v19, 0xffff0000, v144
	v_mul_f32_e32 v16, v16, v14
	v_mul_f32_e32 v17, v17, v14
	v_fmac_f32_e32 v16, v15, v18
	v_fmac_f32_e32 v17, v15, v19
	v_readlane_b32 s2, v6, 33
	v_readlane_b32 s3, v7, 33
	v_add_f32_e32 v12, s1, v10
	v_max_f32_e32 v11, s0, v12
	v_sub_f32_e32 v12, v12, v11
	v_sub_f32_e32 v13, s0, v11
	v_mul_f32_e32 v12, 0x3fb8aa3b, v12
	v_mul_f32_e32 v13, 0x3fb8aa3b, v13
	v_exp_f32_e32 v14, v12
	v_exp_f32_e32 v15, v13
	v_cvt_pk_bf16_f32 v20, v16, v17
	global_store_dword v1, v20, s[24:25]
	s_add_u32 s24, s24, 0x2000
	s_addc_u32 s25, s25, 0
	v_lshlrev_b32_e32 v18, 16, v145
	v_and_b32_e32 v19, 0xffff0000, v145
	v_mul_f32_e32 v16, v16, v14
	v_mul_f32_e32 v17, v17, v14
	v_fmac_f32_e32 v16, v15, v18
	v_fmac_f32_e32 v17, v15, v19
	v_readlane_b32 s0, v6, 34
	v_readlane_b32 s1, v7, 34
	v_add_f32_e32 v12, s3, v11
	v_max_f32_e32 v10, s2, v12
	v_sub_f32_e32 v12, v12, v10
	v_sub_f32_e32 v13, s2, v10
	v_mul_f32_e32 v12, 0x3fb8aa3b, v12
	v_mul_f32_e32 v13, 0x3fb8aa3b, v13
	v_exp_f32_e32 v14, v12
	v_exp_f32_e32 v15, v13
	v_cvt_pk_bf16_f32 v21, v16, v17
	global_store_dword v1, v21, s[24:25]
	s_add_u32 s24, s24, 0x2000
	s_addc_u32 s25, s25, 0
	v_lshlrev_b32_e32 v18, 16, v146
	v_and_b32_e32 v19, 0xffff0000, v146
	v_mul_f32_e32 v16, v16, v14
	v_mul_f32_e32 v17, v17, v14
	v_fmac_f32_e32 v16, v15, v18
	v_fmac_f32_e32 v17, v15, v19
	v_readlane_b32 s2, v6, 35
	v_readlane_b32 s3, v7, 35
	v_add_f32_e32 v12, s1, v10
	v_max_f32_e32 v11, s0, v12
	v_sub_f32_e32 v12, v12, v11
	v_sub_f32_e32 v13, s0, v11
	v_mul_f32_e32 v12, 0x3fb8aa3b, v12
	v_mul_f32_e32 v13, 0x3fb8aa3b, v13
	v_exp_f32_e32 v14, v12
	v_exp_f32_e32 v15, v13
	v_cvt_pk_bf16_f32 v20, v16, v17
	global_store_dword v1, v20, s[24:25]
	s_add_u32 s24, s24, 0x2000
	s_addc_u32 s25, s25, 0
	v_lshlrev_b32_e32 v18, 16, v147
	v_and_b32_e32 v19, 0xffff0000, v147
	v_mul_f32_e32 v16, v16, v14
	v_mul_f32_e32 v17, v17, v14
	v_fmac_f32_e32 v16, v15, v18
	v_fmac_f32_e32 v17, v15, v19
	v_readlane_b32 s0, v6, 36
	v_readlane_b32 s1, v7, 36
	v_add_f32_e32 v12, s3, v11
	v_max_f32_e32 v10, s2, v12
	v_sub_f32_e32 v12, v12, v10
	v_sub_f32_e32 v13, s2, v10
	v_mul_f32_e32 v12, 0x3fb8aa3b, v12
	v_mul_f32_e32 v13, 0x3fb8aa3b, v13
	v_exp_f32_e32 v14, v12
	v_exp_f32_e32 v15, v13
	v_cvt_pk_bf16_f32 v21, v16, v17
	global_store_dword v1, v21, s[24:25]
	s_add_u32 s24, s24, 0x2000
	s_addc_u32 s25, s25, 0
	v_lshlrev_b32_e32 v18, 16, v148
	v_and_b32_e32 v19, 0xffff0000, v148
	v_mul_f32_e32 v16, v16, v14
	v_mul_f32_e32 v17, v17, v14
	v_fmac_f32_e32 v16, v15, v18
	v_fmac_f32_e32 v17, v15, v19
	v_readlane_b32 s2, v6, 37
	v_readlane_b32 s3, v7, 37
	v_add_f32_e32 v12, s1, v10
	v_max_f32_e32 v11, s0, v12
	v_sub_f32_e32 v12, v12, v11
	v_sub_f32_e32 v13, s0, v11
	v_mul_f32_e32 v12, 0x3fb8aa3b, v12
	v_mul_f32_e32 v13, 0x3fb8aa3b, v13
	v_exp_f32_e32 v14, v12
	v_exp_f32_e32 v15, v13
	v_cvt_pk_bf16_f32 v20, v16, v17
	global_store_dword v1, v20, s[24:25]
	s_add_u32 s24, s24, 0x2000
	s_addc_u32 s25, s25, 0
	v_lshlrev_b32_e32 v18, 16, v149
	v_and_b32_e32 v19, 0xffff0000, v149
	v_mul_f32_e32 v16, v16, v14
	v_mul_f32_e32 v17, v17, v14
	v_fmac_f32_e32 v16, v15, v18
	v_fmac_f32_e32 v17, v15, v19
	v_readlane_b32 s0, v6, 38
	v_readlane_b32 s1, v7, 38
	v_add_f32_e32 v12, s3, v11
	v_max_f32_e32 v10, s2, v12
	v_sub_f32_e32 v12, v12, v10
	v_sub_f32_e32 v13, s2, v10
	v_mul_f32_e32 v12, 0x3fb8aa3b, v12
	v_mul_f32_e32 v13, 0x3fb8aa3b, v13
	v_exp_f32_e32 v14, v12
	v_exp_f32_e32 v15, v13
	v_cvt_pk_bf16_f32 v21, v16, v17
	global_store_dword v1, v21, s[24:25]
	s_add_u32 s24, s24, 0x2000
	s_addc_u32 s25, s25, 0
	v_lshlrev_b32_e32 v18, 16, v150
	v_and_b32_e32 v19, 0xffff0000, v150
	v_mul_f32_e32 v16, v16, v14
	v_mul_f32_e32 v17, v17, v14
	v_fmac_f32_e32 v16, v15, v18
	v_fmac_f32_e32 v17, v15, v19
	v_readlane_b32 s2, v6, 39
	v_readlane_b32 s3, v7, 39
	v_add_f32_e32 v12, s1, v10
	v_max_f32_e32 v11, s0, v12
	v_sub_f32_e32 v12, v12, v11
	v_sub_f32_e32 v13, s0, v11
	v_mul_f32_e32 v12, 0x3fb8aa3b, v12
	v_mul_f32_e32 v13, 0x3fb8aa3b, v13
	v_exp_f32_e32 v14, v12
	v_exp_f32_e32 v15, v13
	v_cvt_pk_bf16_f32 v20, v16, v17
	global_store_dword v1, v20, s[24:25]
	s_add_u32 s24, s24, 0x2000
	s_addc_u32 s25, s25, 0
	v_lshlrev_b32_e32 v18, 16, v151
	v_and_b32_e32 v19, 0xffff0000, v151
	v_mul_f32_e32 v16, v16, v14
	v_mul_f32_e32 v17, v17, v14
	v_fmac_f32_e32 v16, v15, v18
	v_fmac_f32_e32 v17, v15, v19
	v_readlane_b32 s0, v6, 40
	v_readlane_b32 s1, v7, 40
	v_add_f32_e32 v12, s3, v11
	v_max_f32_e32 v10, s2, v12
	v_sub_f32_e32 v12, v12, v10
	v_sub_f32_e32 v13, s2, v10
	v_mul_f32_e32 v12, 0x3fb8aa3b, v12
	v_mul_f32_e32 v13, 0x3fb8aa3b, v13
	v_exp_f32_e32 v14, v12
	v_exp_f32_e32 v15, v13
	v_cvt_pk_bf16_f32 v21, v16, v17
	global_store_dword v1, v21, s[24:25]
	s_add_u32 s24, s24, 0x2000
	s_addc_u32 s25, s25, 0
	v_lshlrev_b32_e32 v18, 16, v152
	v_and_b32_e32 v19, 0xffff0000, v152
	v_mul_f32_e32 v16, v16, v14
	v_mul_f32_e32 v17, v17, v14
	v_fmac_f32_e32 v16, v15, v18
	v_fmac_f32_e32 v17, v15, v19
	v_readlane_b32 s2, v6, 41
	v_readlane_b32 s3, v7, 41
	v_add_f32_e32 v12, s1, v10
	v_max_f32_e32 v11, s0, v12
	v_sub_f32_e32 v12, v12, v11
	v_sub_f32_e32 v13, s0, v11
	v_mul_f32_e32 v12, 0x3fb8aa3b, v12
	v_mul_f32_e32 v13, 0x3fb8aa3b, v13
	v_exp_f32_e32 v14, v12
	v_exp_f32_e32 v15, v13
	v_cvt_pk_bf16_f32 v20, v16, v17
	global_store_dword v1, v20, s[24:25]
	s_add_u32 s24, s24, 0x2000
	s_addc_u32 s25, s25, 0
	v_lshlrev_b32_e32 v18, 16, v153
	v_and_b32_e32 v19, 0xffff0000, v153
	v_mul_f32_e32 v16, v16, v14
	v_mul_f32_e32 v17, v17, v14
	v_fmac_f32_e32 v16, v15, v18
	v_fmac_f32_e32 v17, v15, v19
	v_readlane_b32 s0, v6, 42
	v_readlane_b32 s1, v7, 42
	v_add_f32_e32 v12, s3, v11
	v_max_f32_e32 v10, s2, v12
	v_sub_f32_e32 v12, v12, v10
	v_sub_f32_e32 v13, s2, v10
	v_mul_f32_e32 v12, 0x3fb8aa3b, v12
	v_mul_f32_e32 v13, 0x3fb8aa3b, v13
	v_exp_f32_e32 v14, v12
	v_exp_f32_e32 v15, v13
	v_cvt_pk_bf16_f32 v21, v16, v17
	global_store_dword v1, v21, s[24:25]
	s_add_u32 s24, s24, 0x2000
	s_addc_u32 s25, s25, 0
	v_lshlrev_b32_e32 v18, 16, v154
	v_and_b32_e32 v19, 0xffff0000, v154
	v_mul_f32_e32 v16, v16, v14
	v_mul_f32_e32 v17, v17, v14
	v_fmac_f32_e32 v16, v15, v18
	v_fmac_f32_e32 v17, v15, v19
	v_readlane_b32 s2, v6, 43
	v_readlane_b32 s3, v7, 43
	v_add_f32_e32 v12, s1, v10
	v_max_f32_e32 v11, s0, v12
	v_sub_f32_e32 v12, v12, v11
	v_sub_f32_e32 v13, s0, v11
	v_mul_f32_e32 v12, 0x3fb8aa3b, v12
	v_mul_f32_e32 v13, 0x3fb8aa3b, v13
	v_exp_f32_e32 v14, v12
	v_exp_f32_e32 v15, v13
	v_cvt_pk_bf16_f32 v20, v16, v17
	global_store_dword v1, v20, s[24:25]
	s_add_u32 s24, s24, 0x2000
	s_addc_u32 s25, s25, 0
	v_lshlrev_b32_e32 v18, 16, v155
	v_and_b32_e32 v19, 0xffff0000, v155
	v_mul_f32_e32 v16, v16, v14
	v_mul_f32_e32 v17, v17, v14
	v_fmac_f32_e32 v16, v15, v18
	v_fmac_f32_e32 v17, v15, v19
	v_readlane_b32 s0, v6, 44
	v_readlane_b32 s1, v7, 44
	v_add_f32_e32 v12, s3, v11
	v_max_f32_e32 v10, s2, v12
	v_sub_f32_e32 v12, v12, v10
	v_sub_f32_e32 v13, s2, v10
	v_mul_f32_e32 v12, 0x3fb8aa3b, v12
	v_mul_f32_e32 v13, 0x3fb8aa3b, v13
	v_exp_f32_e32 v14, v12
	v_exp_f32_e32 v15, v13
	v_cvt_pk_bf16_f32 v21, v16, v17
	global_store_dword v1, v21, s[24:25]
	s_add_u32 s24, s24, 0x2000
	s_addc_u32 s25, s25, 0
	v_lshlrev_b32_e32 v18, 16, v156
	v_and_b32_e32 v19, 0xffff0000, v156
	v_mul_f32_e32 v16, v16, v14
	v_mul_f32_e32 v17, v17, v14
	v_fmac_f32_e32 v16, v15, v18
	v_fmac_f32_e32 v17, v15, v19
	v_readlane_b32 s2, v6, 45
	v_readlane_b32 s3, v7, 45
	v_add_f32_e32 v12, s1, v10
	v_max_f32_e32 v11, s0, v12
	v_sub_f32_e32 v12, v12, v11
	v_sub_f32_e32 v13, s0, v11
	v_mul_f32_e32 v12, 0x3fb8aa3b, v12
	v_mul_f32_e32 v13, 0x3fb8aa3b, v13
	v_exp_f32_e32 v14, v12
	v_exp_f32_e32 v15, v13
	v_cvt_pk_bf16_f32 v20, v16, v17
	global_store_dword v1, v20, s[24:25]
	s_add_u32 s24, s24, 0x2000
	s_addc_u32 s25, s25, 0
	v_lshlrev_b32_e32 v18, 16, v157
	v_and_b32_e32 v19, 0xffff0000, v157
	v_mul_f32_e32 v16, v16, v14
	v_mul_f32_e32 v17, v17, v14
	v_fmac_f32_e32 v16, v15, v18
	v_fmac_f32_e32 v17, v15, v19
	v_readlane_b32 s0, v6, 46
	v_readlane_b32 s1, v7, 46
	v_add_f32_e32 v12, s3, v11
	v_max_f32_e32 v10, s2, v12
	v_sub_f32_e32 v12, v12, v10
	v_sub_f32_e32 v13, s2, v10
	v_mul_f32_e32 v12, 0x3fb8aa3b, v12
	v_mul_f32_e32 v13, 0x3fb8aa3b, v13
	v_exp_f32_e32 v14, v12
	v_exp_f32_e32 v15, v13
	v_cvt_pk_bf16_f32 v21, v16, v17
	global_store_dword v1, v21, s[24:25]
	s_add_u32 s24, s24, 0x2000
	s_addc_u32 s25, s25, 0
	v_lshlrev_b32_e32 v18, 16, v158
	v_and_b32_e32 v19, 0xffff0000, v158
	v_mul_f32_e32 v16, v16, v14
	v_mul_f32_e32 v17, v17, v14
	v_fmac_f32_e32 v16, v15, v18
	v_fmac_f32_e32 v17, v15, v19
	v_readlane_b32 s2, v6, 47
	v_readlane_b32 s3, v7, 47
	v_add_f32_e32 v12, s1, v10
	v_max_f32_e32 v11, s0, v12
	v_sub_f32_e32 v12, v12, v11
	v_sub_f32_e32 v13, s0, v11
	v_mul_f32_e32 v12, 0x3fb8aa3b, v12
	v_mul_f32_e32 v13, 0x3fb8aa3b, v13
	v_exp_f32_e32 v14, v12
	v_exp_f32_e32 v15, v13
	v_cvt_pk_bf16_f32 v20, v16, v17
	global_store_dword v1, v20, s[24:25]
	s_add_u32 s24, s24, 0x2000
	s_addc_u32 s25, s25, 0
	v_lshlrev_b32_e32 v18, 16, v159
	v_and_b32_e32 v19, 0xffff0000, v159
	v_mul_f32_e32 v16, v16, v14
	v_mul_f32_e32 v17, v17, v14
	v_fmac_f32_e32 v16, v15, v18
	v_fmac_f32_e32 v17, v15, v19
	v_readlane_b32 s0, v6, 48
	v_readlane_b32 s1, v7, 48
	v_add_f32_e32 v12, s3, v11
	v_max_f32_e32 v10, s2, v12
	v_sub_f32_e32 v12, v12, v10
	v_sub_f32_e32 v13, s2, v10
	v_mul_f32_e32 v12, 0x3fb8aa3b, v12
	v_mul_f32_e32 v13, 0x3fb8aa3b, v13
	v_exp_f32_e32 v14, v12
	v_exp_f32_e32 v15, v13
	v_cvt_pk_bf16_f32 v21, v16, v17
	global_store_dword v1, v21, s[24:25]
	s_add_u32 s24, s24, 0x2000
	s_addc_u32 s25, s25, 0
	v_lshlrev_b32_e32 v18, 16, v160
	v_and_b32_e32 v19, 0xffff0000, v160
	v_mul_f32_e32 v16, v16, v14
	v_mul_f32_e32 v17, v17, v14
	v_fmac_f32_e32 v16, v15, v18
	v_fmac_f32_e32 v17, v15, v19
	v_readlane_b32 s2, v6, 49
	v_readlane_b32 s3, v7, 49
	v_add_f32_e32 v12, s1, v10
	v_max_f32_e32 v11, s0, v12
	v_sub_f32_e32 v12, v12, v11
	v_sub_f32_e32 v13, s0, v11
	v_mul_f32_e32 v12, 0x3fb8aa3b, v12
	v_mul_f32_e32 v13, 0x3fb8aa3b, v13
	v_exp_f32_e32 v14, v12
	v_exp_f32_e32 v15, v13
	v_cvt_pk_bf16_f32 v20, v16, v17
	global_store_dword v1, v20, s[24:25]
	s_add_u32 s24, s24, 0x2000
	s_addc_u32 s25, s25, 0
	v_lshlrev_b32_e32 v18, 16, v164
	v_and_b32_e32 v19, 0xffff0000, v164
	v_mul_f32_e32 v16, v16, v14
	v_mul_f32_e32 v17, v17, v14
	v_fmac_f32_e32 v16, v15, v18
	v_fmac_f32_e32 v17, v15, v19
	v_readlane_b32 s0, v6, 50
	v_readlane_b32 s1, v7, 50
	v_add_f32_e32 v12, s3, v11
	v_max_f32_e32 v10, s2, v12
	v_sub_f32_e32 v12, v12, v10
	v_sub_f32_e32 v13, s2, v10
	v_mul_f32_e32 v12, 0x3fb8aa3b, v12
	v_mul_f32_e32 v13, 0x3fb8aa3b, v13
	v_exp_f32_e32 v14, v12
	v_exp_f32_e32 v15, v13
	v_cvt_pk_bf16_f32 v21, v16, v17
	global_store_dword v1, v21, s[24:25]
	s_add_u32 s24, s24, 0x2000
	s_addc_u32 s25, s25, 0
	v_lshlrev_b32_e32 v18, 16, v165
	v_and_b32_e32 v19, 0xffff0000, v165
	v_mul_f32_e32 v16, v16, v14
	v_mul_f32_e32 v17, v17, v14
	v_fmac_f32_e32 v16, v15, v18
	v_fmac_f32_e32 v17, v15, v19
	v_readlane_b32 s2, v6, 51
	v_readlane_b32 s3, v7, 51
	v_add_f32_e32 v12, s1, v10
	v_max_f32_e32 v11, s0, v12
	v_sub_f32_e32 v12, v12, v11
	v_sub_f32_e32 v13, s0, v11
	v_mul_f32_e32 v12, 0x3fb8aa3b, v12
	v_mul_f32_e32 v13, 0x3fb8aa3b, v13
	v_exp_f32_e32 v14, v12
	v_exp_f32_e32 v15, v13
	v_cvt_pk_bf16_f32 v20, v16, v17
	global_store_dword v1, v20, s[24:25]
	s_add_u32 s24, s24, 0x2000
	s_addc_u32 s25, s25, 0
	v_lshlrev_b32_e32 v18, 16, v166
	v_and_b32_e32 v19, 0xffff0000, v166
	v_mul_f32_e32 v16, v16, v14
	v_mul_f32_e32 v17, v17, v14
	v_fmac_f32_e32 v16, v15, v18
	v_fmac_f32_e32 v17, v15, v19
	v_readlane_b32 s0, v6, 52
	v_readlane_b32 s1, v7, 52
	v_add_f32_e32 v12, s3, v11
	v_max_f32_e32 v10, s2, v12
	v_sub_f32_e32 v12, v12, v10
	v_sub_f32_e32 v13, s2, v10
	v_mul_f32_e32 v12, 0x3fb8aa3b, v12
	v_mul_f32_e32 v13, 0x3fb8aa3b, v13
	v_exp_f32_e32 v14, v12
	v_exp_f32_e32 v15, v13
	v_cvt_pk_bf16_f32 v21, v16, v17
	global_store_dword v1, v21, s[24:25]
	s_add_u32 s24, s24, 0x2000
	s_addc_u32 s25, s25, 0
	v_lshlrev_b32_e32 v18, 16, v167
	v_and_b32_e32 v19, 0xffff0000, v167
	v_mul_f32_e32 v16, v16, v14
	v_mul_f32_e32 v17, v17, v14
	v_fmac_f32_e32 v16, v15, v18
	v_fmac_f32_e32 v17, v15, v19
	v_readlane_b32 s2, v6, 53
	v_readlane_b32 s3, v7, 53
	v_add_f32_e32 v12, s1, v10
	v_max_f32_e32 v11, s0, v12
	v_sub_f32_e32 v12, v12, v11
	v_sub_f32_e32 v13, s0, v11
	v_mul_f32_e32 v12, 0x3fb8aa3b, v12
	v_mul_f32_e32 v13, 0x3fb8aa3b, v13
	v_exp_f32_e32 v14, v12
	v_exp_f32_e32 v15, v13
	v_cvt_pk_bf16_f32 v20, v16, v17
	global_store_dword v1, v20, s[24:25]
	s_add_u32 s24, s24, 0x2000
	s_addc_u32 s25, s25, 0
	v_lshlrev_b32_e32 v18, 16, v168
	v_and_b32_e32 v19, 0xffff0000, v168
	v_mul_f32_e32 v16, v16, v14
	v_mul_f32_e32 v17, v17, v14
	v_fmac_f32_e32 v16, v15, v18
	v_fmac_f32_e32 v17, v15, v19
	v_readlane_b32 s0, v6, 54
	v_readlane_b32 s1, v7, 54
	v_add_f32_e32 v12, s3, v11
	v_max_f32_e32 v10, s2, v12
	v_sub_f32_e32 v12, v12, v10
	v_sub_f32_e32 v13, s2, v10
	v_mul_f32_e32 v12, 0x3fb8aa3b, v12
	v_mul_f32_e32 v13, 0x3fb8aa3b, v13
	v_exp_f32_e32 v14, v12
	v_exp_f32_e32 v15, v13
	v_cvt_pk_bf16_f32 v21, v16, v17
	global_store_dword v1, v21, s[24:25]
	s_add_u32 s24, s24, 0x2000
	s_addc_u32 s25, s25, 0
	v_lshlrev_b32_e32 v18, 16, v169
	v_and_b32_e32 v19, 0xffff0000, v169
	v_mul_f32_e32 v16, v16, v14
	v_mul_f32_e32 v17, v17, v14
	v_fmac_f32_e32 v16, v15, v18
	v_fmac_f32_e32 v17, v15, v19
	v_readlane_b32 s2, v6, 55
	v_readlane_b32 s3, v7, 55
	v_add_f32_e32 v12, s1, v10
	v_max_f32_e32 v11, s0, v12
	v_sub_f32_e32 v12, v12, v11
	v_sub_f32_e32 v13, s0, v11
	v_mul_f32_e32 v12, 0x3fb8aa3b, v12
	v_mul_f32_e32 v13, 0x3fb8aa3b, v13
	v_exp_f32_e32 v14, v12
	v_exp_f32_e32 v15, v13
	v_cvt_pk_bf16_f32 v20, v16, v17
	global_store_dword v1, v20, s[24:25]
	s_add_u32 s24, s24, 0x2000
	s_addc_u32 s25, s25, 0
	v_lshlrev_b32_e32 v18, 16, v170
	v_and_b32_e32 v19, 0xffff0000, v170
	v_mul_f32_e32 v16, v16, v14
	v_mul_f32_e32 v17, v17, v14
	v_fmac_f32_e32 v16, v15, v18
	v_fmac_f32_e32 v17, v15, v19
	v_readlane_b32 s0, v6, 56
	v_readlane_b32 s1, v7, 56
	v_add_f32_e32 v12, s3, v11
	v_max_f32_e32 v10, s2, v12
	v_sub_f32_e32 v12, v12, v10
	v_sub_f32_e32 v13, s2, v10
	v_mul_f32_e32 v12, 0x3fb8aa3b, v12
	v_mul_f32_e32 v13, 0x3fb8aa3b, v13
	v_exp_f32_e32 v14, v12
	v_exp_f32_e32 v15, v13
	v_cvt_pk_bf16_f32 v21, v16, v17
	global_store_dword v1, v21, s[24:25]
	s_add_u32 s24, s24, 0x2000
	s_addc_u32 s25, s25, 0
	v_lshlrev_b32_e32 v18, 16, v171
	v_and_b32_e32 v19, 0xffff0000, v171
	v_mul_f32_e32 v16, v16, v14
	v_mul_f32_e32 v17, v17, v14
	v_fmac_f32_e32 v16, v15, v18
	v_fmac_f32_e32 v17, v15, v19
	v_readlane_b32 s2, v6, 57
	v_readlane_b32 s3, v7, 57
	v_add_f32_e32 v12, s1, v10
	v_max_f32_e32 v11, s0, v12
	v_sub_f32_e32 v12, v12, v11
	v_sub_f32_e32 v13, s0, v11
	v_mul_f32_e32 v12, 0x3fb8aa3b, v12
	v_mul_f32_e32 v13, 0x3fb8aa3b, v13
	v_exp_f32_e32 v14, v12
	v_exp_f32_e32 v15, v13
	v_cvt_pk_bf16_f32 v20, v16, v17
	global_store_dword v1, v20, s[24:25]
	s_add_u32 s24, s24, 0x2000
	s_addc_u32 s25, s25, 0
	v_lshlrev_b32_e32 v18, 16, v172
	v_and_b32_e32 v19, 0xffff0000, v172
	v_mul_f32_e32 v16, v16, v14
	v_mul_f32_e32 v17, v17, v14
	v_fmac_f32_e32 v16, v15, v18
	v_fmac_f32_e32 v17, v15, v19
	v_readlane_b32 s0, v6, 58
	v_readlane_b32 s1, v7, 58
	v_add_f32_e32 v12, s3, v11
	v_max_f32_e32 v10, s2, v12
	v_sub_f32_e32 v12, v12, v10
	v_sub_f32_e32 v13, s2, v10
	v_mul_f32_e32 v12, 0x3fb8aa3b, v12
	v_mul_f32_e32 v13, 0x3fb8aa3b, v13
	v_exp_f32_e32 v14, v12
	v_exp_f32_e32 v15, v13
	v_cvt_pk_bf16_f32 v21, v16, v17
	global_store_dword v1, v21, s[24:25]
	s_add_u32 s24, s24, 0x2000
	s_addc_u32 s25, s25, 0
	v_lshlrev_b32_e32 v18, 16, v173
	v_and_b32_e32 v19, 0xffff0000, v173
	v_mul_f32_e32 v16, v16, v14
	v_mul_f32_e32 v17, v17, v14
	v_fmac_f32_e32 v16, v15, v18
	v_fmac_f32_e32 v17, v15, v19
	v_readlane_b32 s2, v6, 59
	v_readlane_b32 s3, v7, 59
	v_add_f32_e32 v12, s1, v10
	v_max_f32_e32 v11, s0, v12
	v_sub_f32_e32 v12, v12, v11
	v_sub_f32_e32 v13, s0, v11
	v_mul_f32_e32 v12, 0x3fb8aa3b, v12
	v_mul_f32_e32 v13, 0x3fb8aa3b, v13
	v_exp_f32_e32 v14, v12
	v_exp_f32_e32 v15, v13
	v_cvt_pk_bf16_f32 v20, v16, v17
	global_store_dword v1, v20, s[24:25]
	s_add_u32 s24, s24, 0x2000
	s_addc_u32 s25, s25, 0
	v_lshlrev_b32_e32 v18, 16, v174
	v_and_b32_e32 v19, 0xffff0000, v174
	v_mul_f32_e32 v16, v16, v14
	v_mul_f32_e32 v17, v17, v14
	v_fmac_f32_e32 v16, v15, v18
	v_fmac_f32_e32 v17, v15, v19
	v_readlane_b32 s0, v6, 60
	v_readlane_b32 s1, v7, 60
	v_add_f32_e32 v12, s3, v11
	v_max_f32_e32 v10, s2, v12
	v_sub_f32_e32 v12, v12, v10
	v_sub_f32_e32 v13, s2, v10
	v_mul_f32_e32 v12, 0x3fb8aa3b, v12
	v_mul_f32_e32 v13, 0x3fb8aa3b, v13
	v_exp_f32_e32 v14, v12
	v_exp_f32_e32 v15, v13
	v_cvt_pk_bf16_f32 v21, v16, v17
	global_store_dword v1, v21, s[24:25]
	s_add_u32 s24, s24, 0x2000
	s_addc_u32 s25, s25, 0
	v_lshlrev_b32_e32 v18, 16, v175
	v_and_b32_e32 v19, 0xffff0000, v175
	v_mul_f32_e32 v16, v16, v14
	v_mul_f32_e32 v17, v17, v14
	v_fmac_f32_e32 v16, v15, v18
	v_fmac_f32_e32 v17, v15, v19
	v_readlane_b32 s2, v6, 61
	v_readlane_b32 s3, v7, 61
	v_add_f32_e32 v12, s1, v10
	v_max_f32_e32 v11, s0, v12
	v_sub_f32_e32 v12, v12, v11
	v_sub_f32_e32 v13, s0, v11
	v_mul_f32_e32 v12, 0x3fb8aa3b, v12
	v_mul_f32_e32 v13, 0x3fb8aa3b, v13
	v_exp_f32_e32 v14, v12
	v_exp_f32_e32 v15, v13
	v_cvt_pk_bf16_f32 v20, v16, v17
	global_store_dword v1, v20, s[24:25]
	s_add_u32 s24, s24, 0x2000
	s_addc_u32 s25, s25, 0
	v_lshlrev_b32_e32 v18, 16, v198
	v_and_b32_e32 v19, 0xffff0000, v198
	v_mul_f32_e32 v16, v16, v14
	v_mul_f32_e32 v17, v17, v14
	v_fmac_f32_e32 v16, v15, v18
	v_fmac_f32_e32 v17, v15, v19
	v_readlane_b32 s0, v6, 62
	v_readlane_b32 s1, v7, 62
	v_add_f32_e32 v12, s3, v11
	v_max_f32_e32 v10, s2, v12
	v_sub_f32_e32 v12, v12, v10
	v_sub_f32_e32 v13, s2, v10
	v_mul_f32_e32 v12, 0x3fb8aa3b, v12
	v_mul_f32_e32 v13, 0x3fb8aa3b, v13
	v_exp_f32_e32 v14, v12
	v_exp_f32_e32 v15, v13
	v_cvt_pk_bf16_f32 v21, v16, v17
	global_store_dword v1, v21, s[24:25]
	s_add_u32 s24, s24, 0x2000
	s_addc_u32 s25, s25, 0
	v_lshlrev_b32_e32 v18, 16, v199
	v_and_b32_e32 v19, 0xffff0000, v199
	v_mul_f32_e32 v16, v16, v14
	v_mul_f32_e32 v17, v17, v14
	v_fmac_f32_e32 v16, v15, v18
	v_fmac_f32_e32 v17, v15, v19
	v_readlane_b32 s2, v6, 63
	v_readlane_b32 s3, v7, 63
	v_add_f32_e32 v12, s1, v10
	v_max_f32_e32 v11, s0, v12
	v_sub_f32_e32 v12, v12, v11
	v_sub_f32_e32 v13, s0, v11
	v_mul_f32_e32 v12, 0x3fb8aa3b, v12
	v_mul_f32_e32 v13, 0x3fb8aa3b, v13
	v_exp_f32_e32 v14, v12
	v_exp_f32_e32 v15, v13
	v_cvt_pk_bf16_f32 v20, v16, v17
	global_store_dword v1, v20, s[24:25]
	s_add_u32 s24, s24, 0x2000
	s_addc_u32 s25, s25, 0
	v_lshlrev_b32_e32 v18, 16, v200
	v_and_b32_e32 v19, 0xffff0000, v200
	v_mul_f32_e32 v16, v16, v14
	v_mul_f32_e32 v17, v17, v14
	v_fmac_f32_e32 v16, v15, v18
	v_fmac_f32_e32 v17, v15, v19
	v_readlane_b32 s0, v8, 0
	v_readlane_b32 s1, v9, 0
	v_add_f32_e32 v12, s3, v11
	v_max_f32_e32 v10, s2, v12
	v_sub_f32_e32 v12, v12, v10
	v_sub_f32_e32 v13, s2, v10
	v_mul_f32_e32 v12, 0x3fb8aa3b, v12
	v_mul_f32_e32 v13, 0x3fb8aa3b, v13
	v_exp_f32_e32 v14, v12
	v_exp_f32_e32 v15, v13
	v_cvt_pk_bf16_f32 v21, v16, v17
	global_store_dword v1, v21, s[24:25]
	s_add_u32 s24, s24, 0x2000
	s_addc_u32 s25, s25, 0
	v_lshlrev_b32_e32 v18, 16, v201
	v_and_b32_e32 v19, 0xffff0000, v201
	v_mul_f32_e32 v16, v16, v14
	v_mul_f32_e32 v17, v17, v14
	v_fmac_f32_e32 v16, v15, v18
	v_fmac_f32_e32 v17, v15, v19
	v_readlane_b32 s2, v8, 1
	v_readlane_b32 s3, v9, 1
	v_add_f32_e32 v12, s1, v10
	v_max_f32_e32 v11, s0, v12
	v_sub_f32_e32 v12, v12, v11
	v_sub_f32_e32 v13, s0, v11
	v_mul_f32_e32 v12, 0x3fb8aa3b, v12
	v_mul_f32_e32 v13, 0x3fb8aa3b, v13
	v_exp_f32_e32 v14, v12
	v_exp_f32_e32 v15, v13
	v_cvt_pk_bf16_f32 v20, v16, v17
	global_store_dword v1, v20, s[24:25]
	s_add_u32 s24, s24, 0x2000
	s_addc_u32 s25, s25, 0
	v_lshlrev_b32_e32 v18, 16, v202
	v_and_b32_e32 v19, 0xffff0000, v202
	v_mul_f32_e32 v16, v16, v14
	v_mul_f32_e32 v17, v17, v14
	v_fmac_f32_e32 v16, v15, v18
	v_fmac_f32_e32 v17, v15, v19
	v_cvt_pk_bf16_f32 v21, v16, v17
	global_store_dword v1, v21, s[24:25]
	s_branch .Lscan_next
.Lscan_v2:
	s_mul_i32 s0, s31, 0x4200
	s_add_u32 s22, s46, s0
	s_addc_u32 s23, s47, 0
	s_add_u32 s22, s22, 0x32a4000
	s_addc_u32 s23, s23, 0
	s_mov_b64 s[34:35], s[22:23]
	global_load_dword v204, v3, s[22:23]
	s_add_u32 s22, s22, 0x100
	s_addc_u32 s23, s23, 0
	global_load_dword v205, v3, s[22:23]
	s_add_u32 s22, s22, 0x100
	s_addc_u32 s23, s23, 0
	global_load_dword v206, v3, s[22:23]
	s_add_u32 s22, s22, 0x100
	s_addc_u32 s23, s23, 0
	global_load_dword v207, v3, s[22:23]
	s_add_u32 s22, s22, 0x100
	s_addc_u32 s23, s23, 0
	global_load_dword v208, v3, s[22:23]
	s_add_u32 s22, s22, 0x100
	s_addc_u32 s23, s23, 0
	global_load_dword v209, v3, s[22:23]
	s_add_u32 s22, s22, 0x100
	s_addc_u32 s23, s23, 0
	global_load_dword v210, v3, s[22:23]
	s_add_u32 s22, s22, 0x100
	s_addc_u32 s23, s23, 0
	global_load_dword v211, v3, s[22:23]
	s_add_u32 s22, s22, 0x100
	s_addc_u32 s23, s23, 0
	global_load_dword v212, v3, s[22:23]
	s_add_u32 s22, s22, 0x100
	s_addc_u32 s23, s23, 0
	global_load_dword v213, v3, s[22:23]
	s_add_u32 s22, s22, 0x100
	s_addc_u32 s23, s23, 0
	global_load_dword v214, v3, s[22:23]
	s_add_u32 s22, s22, 0x100
	s_addc_u32 s23, s23, 0
	global_load_dword v215, v3, s[22:23]
	s_add_u32 s22, s22, 0x100
	s_addc_u32 s23, s23, 0
	global_load_dword v216, v3, s[22:23]
	s_add_u32 s22, s22, 0x100
	s_addc_u32 s23, s23, 0
	global_load_dword v217, v3, s[22:23]
	s_add_u32 s22, s22, 0x100
	s_addc_u32 s23, s23, 0
	global_load_dword v218, v3, s[22:23]
	s_add_u32 s22, s22, 0x100
	s_addc_u32 s23, s23, 0
	global_load_dword v219, v3, s[22:23]
	s_add_u32 s22, s22, 0x100
	s_addc_u32 s23, s23, 0
	global_load_dword v220, v3, s[22:23]
	s_add_u32 s22, s22, 0x100
	s_addc_u32 s23, s23, 0
	global_load_dword v221, v3, s[22:23]
	s_add_u32 s22, s22, 0x100
	s_addc_u32 s23, s23, 0
	global_load_dword v222, v3, s[22:23]
	s_add_u32 s22, s22, 0x100
	s_addc_u32 s23, s23, 0
	global_load_dword v223, v3, s[22:23]
	s_add_u32 s22, s22, 0x100
	s_addc_u32 s23, s23, 0
	global_load_dword v224, v3, s[22:23]
	s_add_u32 s22, s22, 0x100
	s_addc_u32 s23, s23, 0
	global_load_dword v225, v3, s[22:23]
	s_add_u32 s22, s22, 0x100
	s_addc_u32 s23, s23, 0
	global_load_dword v226, v3, s[22:23]
	s_add_u32 s22, s22, 0x100
	s_addc_u32 s23, s23, 0
	global_load_dword v227, v3, s[22:23]
	s_add_u32 s22, s22, 0x100
	s_addc_u32 s23, s23, 0
	global_load_dword v228, v3, s[22:23]
	s_add_u32 s22, s22, 0x100
	s_addc_u32 s23, s23, 0
	global_load_dword v229, v3, s[22:23]
	s_add_u32 s22, s22, 0x100
	s_addc_u32 s23, s23, 0
	global_load_dword v232, v3, s[22:23]
	s_add_u32 s22, s22, 0x100
	s_addc_u32 s23, s23, 0
	global_load_dword v233, v3, s[22:23]
	s_add_u32 s22, s22, 0x100
	s_addc_u32 s23, s23, 0
	global_load_dword v234, v3, s[22:23]
	s_add_u32 s22, s22, 0x100
	s_addc_u32 s23, s23, 0
	global_load_dword v235, v3, s[22:23]
	s_add_u32 s22, s22, 0x100
	s_addc_u32 s23, s23, 0
	global_load_dword v236, v3, s[22:23]
	s_add_u32 s22, s22, 0x100
	s_addc_u32 s23, s23, 0
	global_load_dword v237, v3, s[22:23]
	s_add_u32 s22, s22, 0x100
	s_addc_u32 s23, s23, 0
	global_load_dword v238, v3, s[22:23]
	s_add_u32 s22, s22, 0x100
	s_addc_u32 s23, s23, 0
	global_load_dword v239, v3, s[22:23]
	s_add_u32 s22, s22, 0x100
	s_addc_u32 s23, s23, 0
	global_load_dword v240, v3, s[22:23]
	s_add_u32 s22, s22, 0x100
	s_addc_u32 s23, s23, 0
	global_load_dword v241, v3, s[22:23]
	s_add_u32 s22, s22, 0x100
	s_addc_u32 s23, s23, 0
	global_load_dword v242, v3, s[22:23]
	s_add_u32 s22, s22, 0x100
	s_addc_u32 s23, s23, 0
	global_load_dword v243, v3, s[22:23]
	s_add_u32 s22, s22, 0x100
	s_addc_u32 s23, s23, 0
	global_load_dword v244, v3, s[22:23]
	s_add_u32 s22, s22, 0x100
	s_addc_u32 s23, s23, 0
	global_load_dword v245, v3, s[22:23]
	s_add_u32 s22, s22, 0x100
	s_addc_u32 s23, s23, 0
	global_load_dword v60, v3, s[22:23]
	s_add_u32 s22, s22, 0x100
	s_addc_u32 s23, s23, 0
	global_load_dword v61, v3, s[22:23]
	s_add_u32 s22, s22, 0x100
	s_addc_u32 s23, s23, 0
	global_load_dword v62, v3, s[22:23]
	s_add_u32 s22, s22, 0x100
	s_addc_u32 s23, s23, 0
	global_load_dword v63, v3, s[22:23]
	s_add_u32 s22, s22, 0x100
	s_addc_u32 s23, s23, 0
	global_load_dword v64, v3, s[22:23]
	s_add_u32 s22, s22, 0x100
	s_addc_u32 s23, s23, 0
	global_load_dword v65, v3, s[22:23]
	s_add_u32 s22, s22, 0x100
	s_addc_u32 s23, s23, 0
	global_load_dword v66, v3, s[22:23]
	s_add_u32 s22, s22, 0x100
	s_addc_u32 s23, s23, 0
	global_load_dword v67, v3, s[22:23]
	s_add_u32 s22, s22, 0x100
	s_addc_u32 s23, s23, 0
	global_load_dword v68, v3, s[22:23]
	s_add_u32 s22, s22, 0x100
	s_addc_u32 s23, s23, 0
	global_load_dword v69, v3, s[22:23]
	s_add_u32 s22, s22, 0x100
	s_addc_u32 s23, s23, 0
	global_load_dword v70, v3, s[22:23]
	s_add_u32 s22, s22, 0x100
	s_addc_u32 s23, s23, 0
	global_load_dword v71, v3, s[22:23]
	s_add_u32 s22, s22, 0x100
	s_addc_u32 s23, s23, 0
	global_load_dword v72, v3, s[22:23]
	s_add_u32 s22, s22, 0x100
	s_addc_u32 s23, s23, 0
	global_load_dword v73, v3, s[22:23]
	s_add_u32 s22, s22, 0x100
	s_addc_u32 s23, s23, 0
	global_load_dword v74, v3, s[22:23]
	s_add_u32 s22, s22, 0x100
	s_addc_u32 s23, s23, 0
	global_load_dword v75, v3, s[22:23]
	s_add_u32 s22, s22, 0x100
	s_addc_u32 s23, s23, 0
	global_load_dword v48, v3, s[22:23]
	s_add_u32 s22, s22, 0x100
	s_addc_u32 s23, s23, 0
	global_load_dword v49, v3, s[22:23]
	s_add_u32 s22, s22, 0x100
	s_addc_u32 s23, s23, 0
	global_load_dword v50, v3, s[22:23]
	s_add_u32 s22, s22, 0x100
	s_addc_u32 s23, s23, 0
	global_load_dword v51, v3, s[22:23]
	s_add_u32 s22, s22, 0x100
	s_addc_u32 s23, s23, 0
	global_load_dword v52, v3, s[22:23]
	s_add_u32 s22, s22, 0x100
	s_addc_u32 s23, s23, 0
	global_load_dword v53, v3, s[22:23]
	s_add_u32 s22, s22, 0x100
	s_addc_u32 s23, s23, 0
	global_load_dword v54, v3, s[22:23]
	s_add_u32 s22, s22, 0x100
	s_addc_u32 s23, s23, 0
	global_load_dword v55, v3, s[22:23]
	s_add_u32 s22, s22, 0x100
	s_addc_u32 s23, s23, 0
	global_load_dword v36, v3, s[22:23]
	s_add_u32 s22, s22, 0x100
	s_addc_u32 s23, s23, 0
	global_load_dword v37, v3, s[22:23]
	s_mul_i32 s0, s31, 0x108
	s_add_u32 s22, s46, s0
	s_addc_u32 s23, s47, 0
	s_add_u32 s22, s22, 0x33b4400
	s_addc_u32 s23, s23, 0
	v_mov_b32_e32 v22, 0
	s_waitcnt vmcnt(0)
	v_readlane_b32 s0, v6, 0
	v_readlane_b32 s1, v7, 0
	s_nop 2
	v_readlane_b32 s2, v6, 1
	v_readlane_b32 s3, v7, 1
	v_add_f32_e32 v12, s1, v10
	v_max_f32_e32 v11, s0, v12
	v_sub_f32_e32 v12, v12, v11
	v_sub_f32_e32 v13, s0, v11
	v_mul_f32_e32 v12, 0x3fb8aa3b, v12
	v_mul_f32_e32 v13, 0x3fb8aa3b, v13
	v_exp_f32_e32 v14, v12
	v_exp_f32_e32 v15, v13
	s_mov_b64 exec, 1
	global_store_dword v4, v10, s[22:23] offset:0
	s_mov_b64 exec, -1
	v_cvt_pk_bf16_f32 v20, v16, v17
	global_store_dword v1, v20, s[24:25]
	global_store_dword v3, v22, s[34:35]
	s_add_u32 s24, s24, 0x2000
	s_addc_u32 s25, s25, 0
	s_add_u32 s34, s34, 0x100
	s_addc_u32 s35, s35, 0
	v_lshlrev_b32_e32 v18, 16, v110
	v_and_b32_e32 v19, 0xffff0000, v110
	v_mul_f32_e32 v16, v16, v14
	v_mul_f32_e32 v17, v17, v14
	v_fmac_f32_e32 v16, v15, v18
	v_fmac_f32_e32 v17, v15, v19
	v_mul_f32_e32 v22, v22, v14
	v_fmac_f32_e32 v22, v15, v204
	v_readlane_b32 s0, v6, 2
	v_readlane_b32 s1, v7, 2
	v_add_f32_e32 v12, s3, v11
	v_max_f32_e32 v10, s2, v12
	v_sub_f32_e32 v12, v12, v10
	v_sub_f32_e32 v13, s2, v10
	v_mul_f32_e32 v12, 0x3fb8aa3b, v12
	v_mul_f32_e32 v13, 0x3fb8aa3b, v13
	v_exp_f32_e32 v14, v12
	v_exp_f32_e32 v15, v13
	s_mov_b64 exec, 1
	global_store_dword v4, v11, s[22:23] offset:4
	s_mov_b64 exec, -1
	v_cvt_pk_bf16_f32 v21, v16, v17
	global_store_dword v1, v21, s[24:25]
	global_store_dword v3, v22, s[34:35]
	s_add_u32 s24, s24, 0x2000
	s_addc_u32 s25, s25, 0
	s_add_u32 s34, s34, 0x100
	s_addc_u32 s35, s35, 0
	v_lshlrev_b32_e32 v18, 16, v111
	v_and_b32_e32 v19, 0xffff0000, v111
	v_mul_f32_e32 v16, v16, v14
	v_mul_f32_e32 v17, v17, v14
	v_fmac_f32_e32 v16, v15, v18
	v_fmac_f32_e32 v17, v15, v19
	v_mul_f32_e32 v22, v22, v14
	v_fmac_f32_e32 v22, v15, v205
	v_readlane_b32 s2, v6, 3
	v_readlane_b32 s3, v7, 3
	v_add_f32_e32 v12, s1, v10
	v_max_f32_e32 v11, s0, v12
	v_sub_f32_e32 v12, v12, v11
	v_sub_f32_e32 v13, s0, v11
	v_mul_f32_e32 v12, 0x3fb8aa3b, v12
	v_mul_f32_e32 v13, 0x3fb8aa3b, v13
	v_exp_f32_e32 v14, v12
	v_exp_f32_e32 v15, v13
	s_mov_b64 exec, 1
	global_store_dword v4, v10, s[22:23] offset:8
	s_mov_b64 exec, -1
	v_cvt_pk_bf16_f32 v20, v16, v17
	global_store_dword v1, v20, s[24:25]
	global_store_dword v3, v22, s[34:35]
	s_add_u32 s24, s24, 0x2000
	s_addc_u32 s25, s25, 0
	s_add_u32 s34, s34, 0x100
	s_addc_u32 s35, s35, 0
	v_lshlrev_b32_e32 v18, 16, v112
	v_and_b32_e32 v19, 0xffff0000, v112
	v_mul_f32_e32 v16, v16, v14
	v_mul_f32_e32 v17, v17, v14
	v_fmac_f32_e32 v16, v15, v18
	v_fmac_f32_e32 v17, v15, v19
	v_mul_f32_e32 v22, v22, v14
	v_fmac_f32_e32 v22, v15, v206
	v_readlane_b32 s0, v6, 4
	v_readlane_b32 s1, v7, 4
	v_add_f32_e32 v12, s3, v11
	v_max_f32_e32 v10, s2, v12
	v_sub_f32_e32 v12, v12, v10
	v_sub_f32_e32 v13, s2, v10
	v_mul_f32_e32 v12, 0x3fb8aa3b, v12
	v_mul_f32_e32 v13, 0x3fb8aa3b, v13
	v_exp_f32_e32 v14, v12
	v_exp_f32_e32 v15, v13
	s_mov_b64 exec, 1
	global_store_dword v4, v11, s[22:23] offset:12
	s_mov_b64 exec, -1
	v_cvt_pk_bf16_f32 v21, v16, v17
	global_store_dword v1, v21, s[24:25]
	global_store_dword v3, v22, s[34:35]
	s_add_u32 s24, s24, 0x2000
	s_addc_u32 s25, s25, 0
	s_add_u32 s34, s34, 0x100
	s_addc_u32 s35, s35, 0
	v_lshlrev_b32_e32 v18, 16, v113
	v_and_b32_e32 v19, 0xffff0000, v113
	v_mul_f32_e32 v16, v16, v14
	v_mul_f32_e32 v17, v17, v14
	v_fmac_f32_e32 v16, v15, v18
	v_fmac_f32_e32 v17, v15, v19
	v_mul_f32_e32 v22, v22, v14
	v_fmac_f32_e32 v22, v15, v207
	v_readlane_b32 s2, v6, 5
	v_readlane_b32 s3, v7, 5
	v_add_f32_e32 v12, s1, v10
	v_max_f32_e32 v11, s0, v12
	v_sub_f32_e32 v12, v12, v11
	v_sub_f32_e32 v13, s0, v11
	v_mul_f32_e32 v12, 0x3fb8aa3b, v12
	v_mul_f32_e32 v13, 0x3fb8aa3b, v13
	v_exp_f32_e32 v14, v12
	v_exp_f32_e32 v15, v13
	s_mov_b64 exec, 1
	global_store_dword v4, v10, s[22:23] offset:16
	s_mov_b64 exec, -1
	v_cvt_pk_bf16_f32 v20, v16, v17
	global_store_dword v1, v20, s[24:25]
	global_store_dword v3, v22, s[34:35]
	s_add_u32 s24, s24, 0x2000
	s_addc_u32 s25, s25, 0
	s_add_u32 s34, s34, 0x100
	s_addc_u32 s35, s35, 0
	v_lshlrev_b32_e32 v18, 16, v114
	v_and_b32_e32 v19, 0xffff0000, v114
	v_mul_f32_e32 v16, v16, v14
	v_mul_f32_e32 v17, v17, v14
	v_fmac_f32_e32 v16, v15, v18
	v_fmac_f32_e32 v17, v15, v19
	v_mul_f32_e32 v22, v22, v14
	v_fmac_f32_e32 v22, v15, v208
	v_readlane_b32 s0, v6, 6
	v_readlane_b32 s1, v7, 6
	v_add_f32_e32 v12, s3, v11
	v_max_f32_e32 v10, s2, v12
	v_sub_f32_e32 v12, v12, v10
	v_sub_f32_e32 v13, s2, v10
	v_mul_f32_e32 v12, 0x3fb8aa3b, v12
	v_mul_f32_e32 v13, 0x3fb8aa3b, v13
	v_exp_f32_e32 v14, v12
	v_exp_f32_e32 v15, v13
	s_mov_b64 exec, 1
	global_store_dword v4, v11, s[22:23] offset:20
	s_mov_b64 exec, -1
	v_cvt_pk_bf16_f32 v21, v16, v17
	global_store_dword v1, v21, s[24:25]
	global_store_dword v3, v22, s[34:35]
	s_add_u32 s24, s24, 0x2000
	s_addc_u32 s25, s25, 0
	s_add_u32 s34, s34, 0x100
	s_addc_u32 s35, s35, 0
	v_lshlrev_b32_e32 v18, 16, v115
	v_and_b32_e32 v19, 0xffff0000, v115
	v_mul_f32_e32 v16, v16, v14
	v_mul_f32_e32 v17, v17, v14
	v_fmac_f32_e32 v16, v15, v18
	v_fmac_f32_e32 v17, v15, v19
	v_mul_f32_e32 v22, v22, v14
	v_fmac_f32_e32 v22, v15, v209
	v_readlane_b32 s2, v6, 7
	v_readlane_b32 s3, v7, 7
	v_add_f32_e32 v12, s1, v10
	v_max_f32_e32 v11, s0, v12
	v_sub_f32_e32 v12, v12, v11
	v_sub_f32_e32 v13, s0, v11
	v_mul_f32_e32 v12, 0x3fb8aa3b, v12
	v_mul_f32_e32 v13, 0x3fb8aa3b, v13
	v_exp_f32_e32 v14, v12
	v_exp_f32_e32 v15, v13
	s_mov_b64 exec, 1
	global_store_dword v4, v10, s[22:23] offset:24
	s_mov_b64 exec, -1
	v_cvt_pk_bf16_f32 v20, v16, v17
	global_store_dword v1, v20, s[24:25]
	global_store_dword v3, v22, s[34:35]
	s_add_u32 s24, s24, 0x2000
	s_addc_u32 s25, s25, 0
	s_add_u32 s34, s34, 0x100
	s_addc_u32 s35, s35, 0
	v_lshlrev_b32_e32 v18, 16, v116
	v_and_b32_e32 v19, 0xffff0000, v116
	v_mul_f32_e32 v16, v16, v14
	v_mul_f32_e32 v17, v17, v14
	v_fmac_f32_e32 v16, v15, v18
	v_fmac_f32_e32 v17, v15, v19
	v_mul_f32_e32 v22, v22, v14
	v_fmac_f32_e32 v22, v15, v210
	v_readlane_b32 s0, v6, 8
	v_readlane_b32 s1, v7, 8
	v_add_f32_e32 v12, s3, v11
	v_max_f32_e32 v10, s2, v12
	v_sub_f32_e32 v12, v12, v10
	v_sub_f32_e32 v13, s2, v10
	v_mul_f32_e32 v12, 0x3fb8aa3b, v12
	v_mul_f32_e32 v13, 0x3fb8aa3b, v13
	v_exp_f32_e32 v14, v12
	v_exp_f32_e32 v15, v13
	s_mov_b64 exec, 1
	global_store_dword v4, v11, s[22:23] offset:28
	s_mov_b64 exec, -1
	v_cvt_pk_bf16_f32 v21, v16, v17
	global_store_dword v1, v21, s[24:25]
	global_store_dword v3, v22, s[34:35]
	s_add_u32 s24, s24, 0x2000
	s_addc_u32 s25, s25, 0
	s_add_u32 s34, s34, 0x100
	s_addc_u32 s35, s35, 0
	v_lshlrev_b32_e32 v18, 16, v117
	v_and_b32_e32 v19, 0xffff0000, v117
	v_mul_f32_e32 v16, v16, v14
	v_mul_f32_e32 v17, v17, v14
	v_fmac_f32_e32 v16, v15, v18
	v_fmac_f32_e32 v17, v15, v19
	v_mul_f32_e32 v22, v22, v14
	v_fmac_f32_e32 v22, v15, v211
	v_readlane_b32 s2, v6, 9
	v_readlane_b32 s3, v7, 9
	v_add_f32_e32 v12, s1, v10
	v_max_f32_e32 v11, s0, v12
	v_sub_f32_e32 v12, v12, v11
	v_sub_f32_e32 v13, s0, v11
	v_mul_f32_e32 v12, 0x3fb8aa3b, v12
	v_mul_f32_e32 v13, 0x3fb8aa3b, v13
	v_exp_f32_e32 v14, v12
	v_exp_f32_e32 v15, v13
	s_mov_b64 exec, 1
	global_store_dword v4, v10, s[22:23] offset:32
	s_mov_b64 exec, -1
	v_cvt_pk_bf16_f32 v20, v16, v17
	global_store_dword v1, v20, s[24:25]
	global_store_dword v3, v22, s[34:35]
	s_add_u32 s24, s24, 0x2000
	s_addc_u32 s25, s25, 0
	s_add_u32 s34, s34, 0x100
	s_addc_u32 s35, s35, 0
	v_lshlrev_b32_e32 v18, 16, v118
	v_and_b32_e32 v19, 0xffff0000, v118
	v_mul_f32_e32 v16, v16, v14
	v_mul_f32_e32 v17, v17, v14
	v_fmac_f32_e32 v16, v15, v18
	v_fmac_f32_e32 v17, v15, v19
	v_mul_f32_e32 v22, v22, v14
	v_fmac_f32_e32 v22, v15, v212
	v_readlane_b32 s0, v6, 10
	v_readlane_b32 s1, v7, 10
	v_add_f32_e32 v12, s3, v11
	v_max_f32_e32 v10, s2, v12
	v_sub_f32_e32 v12, v12, v10
	v_sub_f32_e32 v13, s2, v10
	v_mul_f32_e32 v12, 0x3fb8aa3b, v12
	v_mul_f32_e32 v13, 0x3fb8aa3b, v13
	v_exp_f32_e32 v14, v12
	v_exp_f32_e32 v15, v13
	s_mov_b64 exec, 1
	global_store_dword v4, v11, s[22:23] offset:36
	s_mov_b64 exec, -1
	v_cvt_pk_bf16_f32 v21, v16, v17
	global_store_dword v1, v21, s[24:25]
	global_store_dword v3, v22, s[34:35]
	s_add_u32 s24, s24, 0x2000
	s_addc_u32 s25, s25, 0
	s_add_u32 s34, s34, 0x100
	s_addc_u32 s35, s35, 0
	v_lshlrev_b32_e32 v18, 16, v119
	v_and_b32_e32 v19, 0xffff0000, v119
	v_mul_f32_e32 v16, v16, v14
	v_mul_f32_e32 v17, v17, v14
	v_fmac_f32_e32 v16, v15, v18
	v_fmac_f32_e32 v17, v15, v19
	v_mul_f32_e32 v22, v22, v14
	v_fmac_f32_e32 v22, v15, v213
	v_readlane_b32 s2, v6, 11
	v_readlane_b32 s3, v7, 11
	v_add_f32_e32 v12, s1, v10
	v_max_f32_e32 v11, s0, v12
	v_sub_f32_e32 v12, v12, v11
	v_sub_f32_e32 v13, s0, v11
	v_mul_f32_e32 v12, 0x3fb8aa3b, v12
	v_mul_f32_e32 v13, 0x3fb8aa3b, v13
	v_exp_f32_e32 v14, v12
	v_exp_f32_e32 v15, v13
	s_mov_b64 exec, 1
	global_store_dword v4, v10, s[22:23] offset:40
	s_mov_b64 exec, -1
	v_cvt_pk_bf16_f32 v20, v16, v17
	global_store_dword v1, v20, s[24:25]
	global_store_dword v3, v22, s[34:35]
	s_add_u32 s24, s24, 0x2000
	s_addc_u32 s25, s25, 0
	s_add_u32 s34, s34, 0x100
	s_addc_u32 s35, s35, 0
	v_lshlrev_b32_e32 v18, 16, v120
	v_and_b32_e32 v19, 0xffff0000, v120
	v_mul_f32_e32 v16, v16, v14
	v_mul_f32_e32 v17, v17, v14
	v_fmac_f32_e32 v16, v15, v18
	v_fmac_f32_e32 v17, v15, v19
	v_mul_f32_e32 v22, v22, v14
	v_fmac_f32_e32 v22, v15, v214
	v_readlane_b32 s0, v6, 12
	v_readlane_b32 s1, v7, 12
	v_add_f32_e32 v12, s3, v11
	v_max_f32_e32 v10, s2, v12
	v_sub_f32_e32 v12, v12, v10
	v_sub_f32_e32 v13, s2, v10
	v_mul_f32_e32 v12, 0x3fb8aa3b, v12
	v_mul_f32_e32 v13, 0x3fb8aa3b, v13
	v_exp_f32_e32 v14, v12
	v_exp_f32_e32 v15, v13
	s_mov_b64 exec, 1
	global_store_dword v4, v11, s[22:23] offset:44
	s_mov_b64 exec, -1
	v_cvt_pk_bf16_f32 v21, v16, v17
	global_store_dword v1, v21, s[24:25]
	global_store_dword v3, v22, s[34:35]
	s_add_u32 s24, s24, 0x2000
	s_addc_u32 s25, s25, 0
	s_add_u32 s34, s34, 0x100
	s_addc_u32 s35, s35, 0
	v_lshlrev_b32_e32 v18, 16, v121
	v_and_b32_e32 v19, 0xffff0000, v121
	v_mul_f32_e32 v16, v16, v14
	v_mul_f32_e32 v17, v17, v14
	v_fmac_f32_e32 v16, v15, v18
	v_fmac_f32_e32 v17, v15, v19
	v_mul_f32_e32 v22, v22, v14
	v_fmac_f32_e32 v22, v15, v215
	v_readlane_b32 s2, v6, 13
	v_readlane_b32 s3, v7, 13
	v_add_f32_e32 v12, s1, v10
	v_max_f32_e32 v11, s0, v12
	v_sub_f32_e32 v12, v12, v11
	v_sub_f32_e32 v13, s0, v11
	v_mul_f32_e32 v12, 0x3fb8aa3b, v12
	v_mul_f32_e32 v13, 0x3fb8aa3b, v13
	v_exp_f32_e32 v14, v12
	v_exp_f32_e32 v15, v13
	s_mov_b64 exec, 1
	global_store_dword v4, v10, s[22:23] offset:48
	s_mov_b64 exec, -1
	v_cvt_pk_bf16_f32 v20, v16, v17
	global_store_dword v1, v20, s[24:25]
	global_store_dword v3, v22, s[34:35]
	s_add_u32 s24, s24, 0x2000
	s_addc_u32 s25, s25, 0
	s_add_u32 s34, s34, 0x100
	s_addc_u32 s35, s35, 0
	v_lshlrev_b32_e32 v18, 16, v122
	v_and_b32_e32 v19, 0xffff0000, v122
	v_mul_f32_e32 v16, v16, v14
	v_mul_f32_e32 v17, v17, v14
	v_fmac_f32_e32 v16, v15, v18
	v_fmac_f32_e32 v17, v15, v19
	v_mul_f32_e32 v22, v22, v14
	v_fmac_f32_e32 v22, v15, v216
	v_readlane_b32 s0, v6, 14
	v_readlane_b32 s1, v7, 14
	v_add_f32_e32 v12, s3, v11
	v_max_f32_e32 v10, s2, v12
	v_sub_f32_e32 v12, v12, v10
	v_sub_f32_e32 v13, s2, v10
	v_mul_f32_e32 v12, 0x3fb8aa3b, v12
	v_mul_f32_e32 v13, 0x3fb8aa3b, v13
	v_exp_f32_e32 v14, v12
	v_exp_f32_e32 v15, v13
	s_mov_b64 exec, 1
	global_store_dword v4, v11, s[22:23] offset:52
	s_mov_b64 exec, -1
	v_cvt_pk_bf16_f32 v21, v16, v17
	global_store_dword v1, v21, s[24:25]
	global_store_dword v3, v22, s[34:35]
	s_add_u32 s24, s24, 0x2000
	s_addc_u32 s25, s25, 0
	s_add_u32 s34, s34, 0x100
	s_addc_u32 s35, s35, 0
	v_lshlrev_b32_e32 v18, 16, v123
	v_and_b32_e32 v19, 0xffff0000, v123
	v_mul_f32_e32 v16, v16, v14
	v_mul_f32_e32 v17, v17, v14
	v_fmac_f32_e32 v16, v15, v18
	v_fmac_f32_e32 v17, v15, v19
	v_mul_f32_e32 v22, v22, v14
	v_fmac_f32_e32 v22, v15, v217
	v_readlane_b32 s2, v6, 15
	v_readlane_b32 s3, v7, 15
	v_add_f32_e32 v12, s1, v10
	v_max_f32_e32 v11, s0, v12
	v_sub_f32_e32 v12, v12, v11
	v_sub_f32_e32 v13, s0, v11
	v_mul_f32_e32 v12, 0x3fb8aa3b, v12
	v_mul_f32_e32 v13, 0x3fb8aa3b, v13
	v_exp_f32_e32 v14, v12
	v_exp_f32_e32 v15, v13
	s_mov_b64 exec, 1
	global_store_dword v4, v10, s[22:23] offset:56
	s_mov_b64 exec, -1
	v_cvt_pk_bf16_f32 v20, v16, v17
	global_store_dword v1, v20, s[24:25]
	global_store_dword v3, v22, s[34:35]
	s_add_u32 s24, s24, 0x2000
	s_addc_u32 s25, s25, 0
	s_add_u32 s34, s34, 0x100
	s_addc_u32 s35, s35, 0
	v_lshlrev_b32_e32 v18, 16, v124
	v_and_b32_e32 v19, 0xffff0000, v124
	v_mul_f32_e32 v16, v16, v14
	v_mul_f32_e32 v17, v17, v14
	v_fmac_f32_e32 v16, v15, v18
	v_fmac_f32_e32 v17, v15, v19
	v_mul_f32_e32 v22, v22, v14
	v_fmac_f32_e32 v22, v15, v218
	v_readlane_b32 s0, v6, 16
	v_readlane_b32 s1, v7, 16
	v_add_f32_e32 v12, s3, v11
	v_max_f32_e32 v10, s2, v12
	v_sub_f32_e32 v12, v12, v10
	v_sub_f32_e32 v13, s2, v10
	v_mul_f32_e32 v12, 0x3fb8aa3b, v12
	v_mul_f32_e32 v13, 0x3fb8aa3b, v13
	v_exp_f32_e32 v14, v12
	v_exp_f32_e32 v15, v13
	s_mov_b64 exec, 1
	global_store_dword v4, v11, s[22:23] offset:60
	s_mov_b64 exec, -1
	v_cvt_pk_bf16_f32 v21, v16, v17
	global_store_dword v1, v21, s[24:25]
	global_store_dword v3, v22, s[34:35]
	s_add_u32 s24, s24, 0x2000
	s_addc_u32 s25, s25, 0
	s_add_u32 s34, s34, 0x100
	s_addc_u32 s35, s35, 0
	v_lshlrev_b32_e32 v18, 16, v125
	v_and_b32_e32 v19, 0xffff0000, v125
	v_mul_f32_e32 v16, v16, v14
	v_mul_f32_e32 v17, v17, v14
	v_fmac_f32_e32 v16, v15, v18
	v_fmac_f32_e32 v17, v15, v19
	v_mul_f32_e32 v22, v22, v14
	v_fmac_f32_e32 v22, v15, v219
	v_readlane_b32 s2, v6, 17
	v_readlane_b32 s3, v7, 17
	v_add_f32_e32 v12, s1, v10
	v_max_f32_e32 v11, s0, v12
	v_sub_f32_e32 v12, v12, v11
	v_sub_f32_e32 v13, s0, v11
	v_mul_f32_e32 v12, 0x3fb8aa3b, v12
	v_mul_f32_e32 v13, 0x3fb8aa3b, v13
	v_exp_f32_e32 v14, v12
	v_exp_f32_e32 v15, v13
	s_mov_b64 exec, 1
	global_store_dword v4, v10, s[22:23] offset:64
	s_mov_b64 exec, -1
	v_cvt_pk_bf16_f32 v20, v16, v17
	global_store_dword v1, v20, s[24:25]
	global_store_dword v3, v22, s[34:35]
	s_add_u32 s24, s24, 0x2000
	s_addc_u32 s25, s25, 0
	s_add_u32 s34, s34, 0x100
	s_addc_u32 s35, s35, 0
	v_lshlrev_b32_e32 v18, 16, v126
	v_and_b32_e32 v19, 0xffff0000, v126
	v_mul_f32_e32 v16, v16, v14
	v_mul_f32_e32 v17, v17, v14
	v_fmac_f32_e32 v16, v15, v18
	v_fmac_f32_e32 v17, v15, v19
	v_mul_f32_e32 v22, v22, v14
	v_fmac_f32_e32 v22, v15, v220
	v_readlane_b32 s0, v6, 18
	v_readlane_b32 s1, v7, 18
	v_add_f32_e32 v12, s3, v11
	v_max_f32_e32 v10, s2, v12
	v_sub_f32_e32 v12, v12, v10
	v_sub_f32_e32 v13, s2, v10
	v_mul_f32_e32 v12, 0x3fb8aa3b, v12
	v_mul_f32_e32 v13, 0x3fb8aa3b, v13
	v_exp_f32_e32 v14, v12
	v_exp_f32_e32 v15, v13
	s_mov_b64 exec, 1
	global_store_dword v4, v11, s[22:23] offset:68
	s_mov_b64 exec, -1
	v_cvt_pk_bf16_f32 v21, v16, v17
	global_store_dword v1, v21, s[24:25]
	global_store_dword v3, v22, s[34:35]
	s_add_u32 s24, s24, 0x2000
	s_addc_u32 s25, s25, 0
	s_add_u32 s34, s34, 0x100
	s_addc_u32 s35, s35, 0
	v_lshlrev_b32_e32 v18, 16, v127
	v_and_b32_e32 v19, 0xffff0000, v127
	v_mul_f32_e32 v16, v16, v14
	v_mul_f32_e32 v17, v17, v14
	v_fmac_f32_e32 v16, v15, v18
	v_fmac_f32_e32 v17, v15, v19
	v_mul_f32_e32 v22, v22, v14
	v_fmac_f32_e32 v22, v15, v221
	v_readlane_b32 s2, v6, 19
	v_readlane_b32 s3, v7, 19
	v_add_f32_e32 v12, s1, v10
	v_max_f32_e32 v11, s0, v12
	v_sub_f32_e32 v12, v12, v11
	v_sub_f32_e32 v13, s0, v11
	v_mul_f32_e32 v12, 0x3fb8aa3b, v12
	v_mul_f32_e32 v13, 0x3fb8aa3b, v13
	v_exp_f32_e32 v14, v12
	v_exp_f32_e32 v15, v13
	s_mov_b64 exec, 1
	global_store_dword v4, v10, s[22:23] offset:72
	s_mov_b64 exec, -1
	v_cvt_pk_bf16_f32 v20, v16, v17
	global_store_dword v1, v20, s[24:25]
	global_store_dword v3, v22, s[34:35]
	s_add_u32 s24, s24, 0x2000
	s_addc_u32 s25, s25, 0
	s_add_u32 s34, s34, 0x100
	s_addc_u32 s35, s35, 0
	v_lshlrev_b32_e32 v18, 16, v131
	v_and_b32_e32 v19, 0xffff0000, v131
	v_mul_f32_e32 v16, v16, v14
	v_mul_f32_e32 v17, v17, v14
	v_fmac_f32_e32 v16, v15, v18
	v_fmac_f32_e32 v17, v15, v19
	v_mul_f32_e32 v22, v22, v14
	v_fmac_f32_e32 v22, v15, v222
	v_readlane_b32 s0, v6, 20
	v_readlane_b32 s1, v7, 20
	v_add_f32_e32 v12, s3, v11
	v_max_f32_e32 v10, s2, v12
	v_sub_f32_e32 v12, v12, v10
	v_sub_f32_e32 v13, s2, v10
	v_mul_f32_e32 v12, 0x3fb8aa3b, v12
	v_mul_f32_e32 v13, 0x3fb8aa3b, v13
	v_exp_f32_e32 v14, v12
	v_exp_f32_e32 v15, v13
	s_mov_b64 exec, 1
	global_store_dword v4, v11, s[22:23] offset:76
	s_mov_b64 exec, -1
	v_cvt_pk_bf16_f32 v21, v16, v17
	global_store_dword v1, v21, s[24:25]
	global_store_dword v3, v22, s[34:35]
	s_add_u32 s24, s24, 0x2000
	s_addc_u32 s25, s25, 0
	s_add_u32 s34, s34, 0x100
	s_addc_u32 s35, s35, 0
	v_lshlrev_b32_e32 v18, 16, v132
	v_and_b32_e32 v19, 0xffff0000, v132
	v_mul_f32_e32 v16, v16, v14
	v_mul_f32_e32 v17, v17, v14
	v_fmac_f32_e32 v16, v15, v18
	v_fmac_f32_e32 v17, v15, v19
	v_mul_f32_e32 v22, v22, v14
	v_fmac_f32_e32 v22, v15, v223
	v_readlane_b32 s2, v6, 21
	v_readlane_b32 s3, v7, 21
	v_add_f32_e32 v12, s1, v10
	v_max_f32_e32 v11, s0, v12
	v_sub_f32_e32 v12, v12, v11
	v_sub_f32_e32 v13, s0, v11
	v_mul_f32_e32 v12, 0x3fb8aa3b, v12
	v_mul_f32_e32 v13, 0x3fb8aa3b, v13
	v_exp_f32_e32 v14, v12
	v_exp_f32_e32 v15, v13
	s_mov_b64 exec, 1
	global_store_dword v4, v10, s[22:23] offset:80
	s_mov_b64 exec, -1
	v_cvt_pk_bf16_f32 v20, v16, v17
	global_store_dword v1, v20, s[24:25]
	global_store_dword v3, v22, s[34:35]
	s_add_u32 s24, s24, 0x2000
	s_addc_u32 s25, s25, 0
	s_add_u32 s34, s34, 0x100
	s_addc_u32 s35, s35, 0
	v_lshlrev_b32_e32 v18, 16, v133
	v_and_b32_e32 v19, 0xffff0000, v133
	v_mul_f32_e32 v16, v16, v14
	v_mul_f32_e32 v17, v17, v14
	v_fmac_f32_e32 v16, v15, v18
	v_fmac_f32_e32 v17, v15, v19
	v_mul_f32_e32 v22, v22, v14
	v_fmac_f32_e32 v22, v15, v224
	v_readlane_b32 s0, v6, 22
	v_readlane_b32 s1, v7, 22
	v_add_f32_e32 v12, s3, v11
	v_max_f32_e32 v10, s2, v12
	v_sub_f32_e32 v12, v12, v10
	v_sub_f32_e32 v13, s2, v10
	v_mul_f32_e32 v12, 0x3fb8aa3b, v12
	v_mul_f32_e32 v13, 0x3fb8aa3b, v13
	v_exp_f32_e32 v14, v12
	v_exp_f32_e32 v15, v13
	s_mov_b64 exec, 1
	global_store_dword v4, v11, s[22:23] offset:84
	s_mov_b64 exec, -1
	v_cvt_pk_bf16_f32 v21, v16, v17
	global_store_dword v1, v21, s[24:25]
	global_store_dword v3, v22, s[34:35]
	s_add_u32 s24, s24, 0x2000
	s_addc_u32 s25, s25, 0
	s_add_u32 s34, s34, 0x100
	s_addc_u32 s35, s35, 0
	v_lshlrev_b32_e32 v18, 16, v134
	v_and_b32_e32 v19, 0xffff0000, v134
	v_mul_f32_e32 v16, v16, v14
	v_mul_f32_e32 v17, v17, v14
	v_fmac_f32_e32 v16, v15, v18
	v_fmac_f32_e32 v17, v15, v19
	v_mul_f32_e32 v22, v22, v14
	v_fmac_f32_e32 v22, v15, v225
	v_readlane_b32 s2, v6, 23
	v_readlane_b32 s3, v7, 23
	v_add_f32_e32 v12, s1, v10
	v_max_f32_e32 v11, s0, v12
	v_sub_f32_e32 v12, v12, v11
	v_sub_f32_e32 v13, s0, v11
	v_mul_f32_e32 v12, 0x3fb8aa3b, v12
	v_mul_f32_e32 v13, 0x3fb8aa3b, v13
	v_exp_f32_e32 v14, v12
	v_exp_f32_e32 v15, v13
	s_mov_b64 exec, 1
	global_store_dword v4, v10, s[22:23] offset:88
	s_mov_b64 exec, -1
	v_cvt_pk_bf16_f32 v20, v16, v17
	global_store_dword v1, v20, s[24:25]
	global_store_dword v3, v22, s[34:35]
	s_add_u32 s24, s24, 0x2000
	s_addc_u32 s25, s25, 0
	s_add_u32 s34, s34, 0x100
	s_addc_u32 s35, s35, 0
	v_lshlrev_b32_e32 v18, 16, v135
	v_and_b32_e32 v19, 0xffff0000, v135
	v_mul_f32_e32 v16, v16, v14
	v_mul_f32_e32 v17, v17, v14
	v_fmac_f32_e32 v16, v15, v18
	v_fmac_f32_e32 v17, v15, v19
	v_mul_f32_e32 v22, v22, v14
	v_fmac_f32_e32 v22, v15, v226
	v_readlane_b32 s0, v6, 24
	v_readlane_b32 s1, v7, 24
	v_add_f32_e32 v12, s3, v11
	v_max_f32_e32 v10, s2, v12
	v_sub_f32_e32 v12, v12, v10
	v_sub_f32_e32 v13, s2, v10
	v_mul_f32_e32 v12, 0x3fb8aa3b, v12
	v_mul_f32_e32 v13, 0x3fb8aa3b, v13
	v_exp_f32_e32 v14, v12
	v_exp_f32_e32 v15, v13
	s_mov_b64 exec, 1
	global_store_dword v4, v11, s[22:23] offset:92
	s_mov_b64 exec, -1
	v_cvt_pk_bf16_f32 v21, v16, v17
	global_store_dword v1, v21, s[24:25]
	global_store_dword v3, v22, s[34:35]
	s_add_u32 s24, s24, 0x2000
	s_addc_u32 s25, s25, 0
	s_add_u32 s34, s34, 0x100
	s_addc_u32 s35, s35, 0
	v_lshlrev_b32_e32 v18, 16, v136
	v_and_b32_e32 v19, 0xffff0000, v136
	v_mul_f32_e32 v16, v16, v14
	v_mul_f32_e32 v17, v17, v14
	v_fmac_f32_e32 v16, v15, v18
	v_fmac_f32_e32 v17, v15, v19
	v_mul_f32_e32 v22, v22, v14
	v_fmac_f32_e32 v22, v15, v227
	v_readlane_b32 s2, v6, 25
	v_readlane_b32 s3, v7, 25
	v_add_f32_e32 v12, s1, v10
	v_max_f32_e32 v11, s0, v12
	v_sub_f32_e32 v12, v12, v11
	v_sub_f32_e32 v13, s0, v11
	v_mul_f32_e32 v12, 0x3fb8aa3b, v12
	v_mul_f32_e32 v13, 0x3fb8aa3b, v13
	v_exp_f32_e32 v14, v12
	v_exp_f32_e32 v15, v13
	s_mov_b64 exec, 1
	global_store_dword v4, v10, s[22:23] offset:96
	s_mov_b64 exec, -1
	v_cvt_pk_bf16_f32 v20, v16, v17
	global_store_dword v1, v20, s[24:25]
	global_store_dword v3, v22, s[34:35]
	s_add_u32 s24, s24, 0x2000
	s_addc_u32 s25, s25, 0
	s_add_u32 s34, s34, 0x100
	s_addc_u32 s35, s35, 0
	v_lshlrev_b32_e32 v18, 16, v137
	v_and_b32_e32 v19, 0xffff0000, v137
	v_mul_f32_e32 v16, v16, v14
	v_mul_f32_e32 v17, v17, v14
	v_fmac_f32_e32 v16, v15, v18
	v_fmac_f32_e32 v17, v15, v19
	v_mul_f32_e32 v22, v22, v14
	v_fmac_f32_e32 v22, v15, v228
	v_readlane_b32 s0, v6, 26
	v_readlane_b32 s1, v7, 26
	v_add_f32_e32 v12, s3, v11
	v_max_f32_e32 v10, s2, v12
	v_sub_f32_e32 v12, v12, v10
	v_sub_f32_e32 v13, s2, v10
	v_mul_f32_e32 v12, 0x3fb8aa3b, v12
	v_mul_f32_e32 v13, 0x3fb8aa3b, v13
	v_exp_f32_e32 v14, v12
	v_exp_f32_e32 v15, v13
	s_mov_b64 exec, 1
	global_store_dword v4, v11, s[22:23] offset:100
	s_mov_b64 exec, -1
	v_cvt_pk_bf16_f32 v21, v16, v17
	global_store_dword v1, v21, s[24:25]
	global_store_dword v3, v22, s[34:35]
	s_add_u32 s24, s24, 0x2000
	s_addc_u32 s25, s25, 0
	s_add_u32 s34, s34, 0x100
	s_addc_u32 s35, s35, 0
	v_lshlrev_b32_e32 v18, 16, v138
	v_and_b32_e32 v19, 0xffff0000, v138
	v_mul_f32_e32 v16, v16, v14
	v_mul_f32_e32 v17, v17, v14
	v_fmac_f32_e32 v16, v15, v18
	v_fmac_f32_e32 v17, v15, v19
	v_mul_f32_e32 v22, v22, v14
	v_fmac_f32_e32 v22, v15, v229
	v_readlane_b32 s2, v6, 27
	v_readlane_b32 s3, v7, 27
	v_add_f32_e32 v12, s1, v10
	v_max_f32_e32 v11, s0, v12
	v_sub_f32_e32 v12, v12, v11
	v_sub_f32_e32 v13, s0, v11
	v_mul_f32_e32 v12, 0x3fb8aa3b, v12
	v_mul_f32_e32 v13, 0x3fb8aa3b, v13
	v_exp_f32_e32 v14, v12
	v_exp_f32_e32 v15, v13
	s_mov_b64 exec, 1
	global_store_dword v4, v10, s[22:23] offset:104
	s_mov_b64 exec, -1
	v_cvt_pk_bf16_f32 v20, v16, v17
	global_store_dword v1, v20, s[24:25]
	global_store_dword v3, v22, s[34:35]
	s_add_u32 s24, s24, 0x2000
	s_addc_u32 s25, s25, 0
	s_add_u32 s34, s34, 0x100
	s_addc_u32 s35, s35, 0
	v_lshlrev_b32_e32 v18, 16, v139
	v_and_b32_e32 v19, 0xffff0000, v139
	v_mul_f32_e32 v16, v16, v14
	v_mul_f32_e32 v17, v17, v14
	v_fmac_f32_e32 v16, v15, v18
	v_fmac_f32_e32 v17, v15, v19
	v_mul_f32_e32 v22, v22, v14
	v_fmac_f32_e32 v22, v15, v232
	v_readlane_b32 s0, v6, 28
	v_readlane_b32 s1, v7, 28
	v_add_f32_e32 v12, s3, v11
	v_max_f32_e32 v10, s2, v12
	v_sub_f32_e32 v12, v12, v10
	v_sub_f32_e32 v13, s2, v10
	v_mul_f32_e32 v12, 0x3fb8aa3b, v12
	v_mul_f32_e32 v13, 0x3fb8aa3b, v13
	v_exp_f32_e32 v14, v12
	v_exp_f32_e32 v15, v13
	s_mov_b64 exec, 1
	global_store_dword v4, v11, s[22:23] offset:108
	s_mov_b64 exec, -1
	v_cvt_pk_bf16_f32 v21, v16, v17
	global_store_dword v1, v21, s[24:25]
	global_store_dword v3, v22, s[34:35]
	s_add_u32 s24, s24, 0x2000
	s_addc_u32 s25, s25, 0
	s_add_u32 s34, s34, 0x100
	s_addc_u32 s35, s35, 0
	v_lshlrev_b32_e32 v18, 16, v140
	v_and_b32_e32 v19, 0xffff0000, v140
	v_mul_f32_e32 v16, v16, v14
	v_mul_f32_e32 v17, v17, v14
	v_fmac_f32_e32 v16, v15, v18
	v_fmac_f32_e32 v17, v15, v19
	v_mul_f32_e32 v22, v22, v14
	v_fmac_f32_e32 v22, v15, v233
	v_readlane_b32 s2, v6, 29
	v_readlane_b32 s3, v7, 29
	v_add_f32_e32 v12, s1, v10
	v_max_f32_e32 v11, s0, v12
	v_sub_f32_e32 v12, v12, v11
	v_sub_f32_e32 v13, s0, v11
	v_mul_f32_e32 v12, 0x3fb8aa3b, v12
	v_mul_f32_e32 v13, 0x3fb8aa3b, v13
	v_exp_f32_e32 v14, v12
	v_exp_f32_e32 v15, v13
	s_mov_b64 exec, 1
	global_store_dword v4, v10, s[22:23] offset:112
	s_mov_b64 exec, -1
	v_cvt_pk_bf16_f32 v20, v16, v17
	global_store_dword v1, v20, s[24:25]
	global_store_dword v3, v22, s[34:35]
	s_add_u32 s24, s24, 0x2000
	s_addc_u32 s25, s25, 0
	s_add_u32 s34, s34, 0x100
	s_addc_u32 s35, s35, 0
	v_lshlrev_b32_e32 v18, 16, v141
	v_and_b32_e32 v19, 0xffff0000, v141
	v_mul_f32_e32 v16, v16, v14
	v_mul_f32_e32 v17, v17, v14
	v_fmac_f32_e32 v16, v15, v18
	v_fmac_f32_e32 v17, v15, v19
	v_mul_f32_e32 v22, v22, v14
	v_fmac_f32_e32 v22, v15, v234
	v_readlane_b32 s0, v6, 30
	v_readlane_b32 s1, v7, 30
	v_add_f32_e32 v12, s3, v11
	v_max_f32_e32 v10, s2, v12
	v_sub_f32_e32 v12, v12, v10
	v_sub_f32_e32 v13, s2, v10
	v_mul_f32_e32 v12, 0x3fb8aa3b, v12
	v_mul_f32_e32 v13, 0x3fb8aa3b, v13
	v_exp_f32_e32 v14, v12
	v_exp_f32_e32 v15, v13
	s_mov_b64 exec, 1
	global_store_dword v4, v11, s[22:23] offset:116
	s_mov_b64 exec, -1
	v_cvt_pk_bf16_f32 v21, v16, v17
	global_store_dword v1, v21, s[24:25]
	global_store_dword v3, v22, s[34:35]
	s_add_u32 s24, s24, 0x2000
	s_addc_u32 s25, s25, 0
	s_add_u32 s34, s34, 0x100
	s_addc_u32 s35, s35, 0
	v_lshlrev_b32_e32 v18, 16, v142
	v_and_b32_e32 v19, 0xffff0000, v142
	v_mul_f32_e32 v16, v16, v14
	v_mul_f32_e32 v17, v17, v14
	v_fmac_f32_e32 v16, v15, v18
	v_fmac_f32_e32 v17, v15, v19
	v_mul_f32_e32 v22, v22, v14
	v_fmac_f32_e32 v22, v15, v235
	v_readlane_b32 s2, v6, 31
	v_readlane_b32 s3, v7, 31
	v_add_f32_e32 v12, s1, v10
	v_max_f32_e32 v11, s0, v12
	v_sub_f32_e32 v12, v12, v11
	v_sub_f32_e32 v13, s0, v11
	v_mul_f32_e32 v12, 0x3fb8aa3b, v12
	v_mul_f32_e32 v13, 0x3fb8aa3b, v13
	v_exp_f32_e32 v14, v12
	v_exp_f32_e32 v15, v13
	s_mov_b64 exec, 1
	global_store_dword v4, v10, s[22:23] offset:120
	s_mov_b64 exec, -1
	v_cvt_pk_bf16_f32 v20, v16, v17
	global_store_dword v1, v20, s[24:25]
	global_store_dword v3, v22, s[34:35]
	s_add_u32 s24, s24, 0x2000
	s_addc_u32 s25, s25, 0
	s_add_u32 s34, s34, 0x100
	s_addc_u32 s35, s35, 0
	v_lshlrev_b32_e32 v18, 16, v143
	v_and_b32_e32 v19, 0xffff0000, v143
	v_mul_f32_e32 v16, v16, v14
	v_mul_f32_e32 v17, v17, v14
	v_fmac_f32_e32 v16, v15, v18
	v_fmac_f32_e32 v17, v15, v19
	v_mul_f32_e32 v22, v22, v14
	v_fmac_f32_e32 v22, v15, v236
	v_readlane_b32 s0, v6, 32
	v_readlane_b32 s1, v7, 32
	v_add_f32_e32 v12, s3, v11
	v_max_f32_e32 v10, s2, v12
	v_sub_f32_e32 v12, v12, v10
	v_sub_f32_e32 v13, s2, v10
	v_mul_f32_e32 v12, 0x3fb8aa3b, v12
	v_mul_f32_e32 v13, 0x3fb8aa3b, v13
	v_exp_f32_e32 v14, v12
	v_exp_f32_e32 v15, v13
	s_mov_b64 exec, 1
	global_store_dword v4, v11, s[22:23] offset:124
	s_mov_b64 exec, -1
	v_cvt_pk_bf16_f32 v21, v16, v17
	global_store_dword v1, v21, s[24:25]
	global_store_dword v3, v22, s[34:35]
	s_add_u32 s24, s24, 0x2000
	s_addc_u32 s25, s25, 0
	s_add_u32 s34, s34, 0x100
	s_addc_u32 s35, s35, 0
	v_lshlrev_b32_e32 v18, 16, v144
	v_and_b32_e32 v19, 0xffff0000, v144
	v_mul_f32_e32 v16, v16, v14
	v_mul_f32_e32 v17, v17, v14
	v_fmac_f32_e32 v16, v15, v18
	v_fmac_f32_e32 v17, v15, v19
	v_mul_f32_e32 v22, v22, v14
	v_fmac_f32_e32 v22, v15, v237
	v_readlane_b32 s2, v6, 33
	v_readlane_b32 s3, v7, 33
	v_add_f32_e32 v12, s1, v10
	v_max_f32_e32 v11, s0, v12
	v_sub_f32_e32 v12, v12, v11
	v_sub_f32_e32 v13, s0, v11
	v_mul_f32_e32 v12, 0x3fb8aa3b, v12
	v_mul_f32_e32 v13, 0x3fb8aa3b, v13
	v_exp_f32_e32 v14, v12
	v_exp_f32_e32 v15, v13
	s_mov_b64 exec, 1
	global_store_dword v4, v10, s[22:23] offset:128
	s_mov_b64 exec, -1
	v_cvt_pk_bf16_f32 v20, v16, v17
	global_store_dword v1, v20, s[24:25]
	global_store_dword v3, v22, s[34:35]
	s_add_u32 s24, s24, 0x2000
	s_addc_u32 s25, s25, 0
	s_add_u32 s34, s34, 0x100
	s_addc_u32 s35, s35, 0
	v_lshlrev_b32_e32 v18, 16, v145
	v_and_b32_e32 v19, 0xffff0000, v145
	v_mul_f32_e32 v16, v16, v14
	v_mul_f32_e32 v17, v17, v14
	v_fmac_f32_e32 v16, v15, v18
	v_fmac_f32_e32 v17, v15, v19
	v_mul_f32_e32 v22, v22, v14
	v_fmac_f32_e32 v22, v15, v238
	v_readlane_b32 s0, v6, 34
	v_readlane_b32 s1, v7, 34
	v_add_f32_e32 v12, s3, v11
	v_max_f32_e32 v10, s2, v12
	v_sub_f32_e32 v12, v12, v10
	v_sub_f32_e32 v13, s2, v10
	v_mul_f32_e32 v12, 0x3fb8aa3b, v12
	v_mul_f32_e32 v13, 0x3fb8aa3b, v13
	v_exp_f32_e32 v14, v12
	v_exp_f32_e32 v15, v13
	s_mov_b64 exec, 1
	global_store_dword v4, v11, s[22:23] offset:132
	s_mov_b64 exec, -1
	v_cvt_pk_bf16_f32 v21, v16, v17
	global_store_dword v1, v21, s[24:25]
	global_store_dword v3, v22, s[34:35]
	s_add_u32 s24, s24, 0x2000
	s_addc_u32 s25, s25, 0
	s_add_u32 s34, s34, 0x100
	s_addc_u32 s35, s35, 0
	v_lshlrev_b32_e32 v18, 16, v146
	v_and_b32_e32 v19, 0xffff0000, v146
	v_mul_f32_e32 v16, v16, v14
	v_mul_f32_e32 v17, v17, v14
	v_fmac_f32_e32 v16, v15, v18
	v_fmac_f32_e32 v17, v15, v19
	v_mul_f32_e32 v22, v22, v14
	v_fmac_f32_e32 v22, v15, v239
	v_readlane_b32 s2, v6, 35
	v_readlane_b32 s3, v7, 35
	v_add_f32_e32 v12, s1, v10
	v_max_f32_e32 v11, s0, v12
	v_sub_f32_e32 v12, v12, v11
	v_sub_f32_e32 v13, s0, v11
	v_mul_f32_e32 v12, 0x3fb8aa3b, v12
	v_mul_f32_e32 v13, 0x3fb8aa3b, v13
	v_exp_f32_e32 v14, v12
	v_exp_f32_e32 v15, v13
	s_mov_b64 exec, 1
	global_store_dword v4, v10, s[22:23] offset:136
	s_mov_b64 exec, -1
	v_cvt_pk_bf16_f32 v20, v16, v17
	global_store_dword v1, v20, s[24:25]
	global_store_dword v3, v22, s[34:35]
	s_add_u32 s24, s24, 0x2000
	s_addc_u32 s25, s25, 0
	s_add_u32 s34, s34, 0x100
	s_addc_u32 s35, s35, 0
	v_lshlrev_b32_e32 v18, 16, v147
	v_and_b32_e32 v19, 0xffff0000, v147
	v_mul_f32_e32 v16, v16, v14
	v_mul_f32_e32 v17, v17, v14
	v_fmac_f32_e32 v16, v15, v18
	v_fmac_f32_e32 v17, v15, v19
	v_mul_f32_e32 v22, v22, v14
	v_fmac_f32_e32 v22, v15, v240
	v_readlane_b32 s0, v6, 36
	v_readlane_b32 s1, v7, 36
	v_add_f32_e32 v12, s3, v11
	v_max_f32_e32 v10, s2, v12
	v_sub_f32_e32 v12, v12, v10
	v_sub_f32_e32 v13, s2, v10
	v_mul_f32_e32 v12, 0x3fb8aa3b, v12
	v_mul_f32_e32 v13, 0x3fb8aa3b, v13
	v_exp_f32_e32 v14, v12
	v_exp_f32_e32 v15, v13
	s_mov_b64 exec, 1
	global_store_dword v4, v11, s[22:23] offset:140
	s_mov_b64 exec, -1
	v_cvt_pk_bf16_f32 v21, v16, v17
	global_store_dword v1, v21, s[24:25]
	global_store_dword v3, v22, s[34:35]
	s_add_u32 s24, s24, 0x2000
	s_addc_u32 s25, s25, 0
	s_add_u32 s34, s34, 0x100
	s_addc_u32 s35, s35, 0
	v_lshlrev_b32_e32 v18, 16, v148
	v_and_b32_e32 v19, 0xffff0000, v148
	v_mul_f32_e32 v16, v16, v14
	v_mul_f32_e32 v17, v17, v14
	v_fmac_f32_e32 v16, v15, v18
	v_fmac_f32_e32 v17, v15, v19
	v_mul_f32_e32 v22, v22, v14
	v_fmac_f32_e32 v22, v15, v241
	v_readlane_b32 s2, v6, 37
	v_readlane_b32 s3, v7, 37
	v_add_f32_e32 v12, s1, v10
	v_max_f32_e32 v11, s0, v12
	v_sub_f32_e32 v12, v12, v11
	v_sub_f32_e32 v13, s0, v11
	v_mul_f32_e32 v12, 0x3fb8aa3b, v12
	v_mul_f32_e32 v13, 0x3fb8aa3b, v13
	v_exp_f32_e32 v14, v12
	v_exp_f32_e32 v15, v13
	s_mov_b64 exec, 1
	global_store_dword v4, v10, s[22:23] offset:144
	s_mov_b64 exec, -1
	v_cvt_pk_bf16_f32 v20, v16, v17
	global_store_dword v1, v20, s[24:25]
	global_store_dword v3, v22, s[34:35]
	s_add_u32 s24, s24, 0x2000
	s_addc_u32 s25, s25, 0
	s_add_u32 s34, s34, 0x100
	s_addc_u32 s35, s35, 0
	v_lshlrev_b32_e32 v18, 16, v149
	v_and_b32_e32 v19, 0xffff0000, v149
	v_mul_f32_e32 v16, v16, v14
	v_mul_f32_e32 v17, v17, v14
	v_fmac_f32_e32 v16, v15, v18
	v_fmac_f32_e32 v17, v15, v19
	v_mul_f32_e32 v22, v22, v14
	v_fmac_f32_e32 v22, v15, v242
	v_readlane_b32 s0, v6, 38
	v_readlane_b32 s1, v7, 38
	v_add_f32_e32 v12, s3, v11
	v_max_f32_e32 v10, s2, v12
	v_sub_f32_e32 v12, v12, v10
	v_sub_f32_e32 v13, s2, v10
	v_mul_f32_e32 v12, 0x3fb8aa3b, v12
	v_mul_f32_e32 v13, 0x3fb8aa3b, v13
	v_exp_f32_e32 v14, v12
	v_exp_f32_e32 v15, v13
	s_mov_b64 exec, 1
	global_store_dword v4, v11, s[22:23] offset:148
	s_mov_b64 exec, -1
	v_cvt_pk_bf16_f32 v21, v16, v17
	global_store_dword v1, v21, s[24:25]
	global_store_dword v3, v22, s[34:35]
	s_add_u32 s24, s24, 0x2000
	s_addc_u32 s25, s25, 0
	s_add_u32 s34, s34, 0x100
	s_addc_u32 s35, s35, 0
	v_lshlrev_b32_e32 v18, 16, v150
	v_and_b32_e32 v19, 0xffff0000, v150
	v_mul_f32_e32 v16, v16, v14
	v_mul_f32_e32 v17, v17, v14
	v_fmac_f32_e32 v16, v15, v18
	v_fmac_f32_e32 v17, v15, v19
	v_mul_f32_e32 v22, v22, v14
	v_fmac_f32_e32 v22, v15, v243
	v_readlane_b32 s2, v6, 39
	v_readlane_b32 s3, v7, 39
	v_add_f32_e32 v12, s1, v10
	v_max_f32_e32 v11, s0, v12
	v_sub_f32_e32 v12, v12, v11
	v_sub_f32_e32 v13, s0, v11
	v_mul_f32_e32 v12, 0x3fb8aa3b, v12
	v_mul_f32_e32 v13, 0x3fb8aa3b, v13
	v_exp_f32_e32 v14, v12
	v_exp_f32_e32 v15, v13
	s_mov_b64 exec, 1
	global_store_dword v4, v10, s[22:23] offset:152
	s_mov_b64 exec, -1
	v_cvt_pk_bf16_f32 v20, v16, v17
	global_store_dword v1, v20, s[24:25]
	global_store_dword v3, v22, s[34:35]
	s_add_u32 s24, s24, 0x2000
	s_addc_u32 s25, s25, 0
	s_add_u32 s34, s34, 0x100
	s_addc_u32 s35, s35, 0
	v_lshlrev_b32_e32 v18, 16, v151
	v_and_b32_e32 v19, 0xffff0000, v151
	v_mul_f32_e32 v16, v16, v14
	v_mul_f32_e32 v17, v17, v14
	v_fmac_f32_e32 v16, v15, v18
	v_fmac_f32_e32 v17, v15, v19
	v_mul_f32_e32 v22, v22, v14
	v_fmac_f32_e32 v22, v15, v244
	v_readlane_b32 s0, v6, 40
	v_readlane_b32 s1, v7, 40
	v_add_f32_e32 v12, s3, v11
	v_max_f32_e32 v10, s2, v12
	v_sub_f32_e32 v12, v12, v10
	v_sub_f32_e32 v13, s2, v10
	v_mul_f32_e32 v12, 0x3fb8aa3b, v12
	v_mul_f32_e32 v13, 0x3fb8aa3b, v13
	v_exp_f32_e32 v14, v12
	v_exp_f32_e32 v15, v13
	s_mov_b64 exec, 1
	global_store_dword v4, v11, s[22:23] offset:156
	s_mov_b64 exec, -1
	v_cvt_pk_bf16_f32 v21, v16, v17
	global_store_dword v1, v21, s[24:25]
	global_store_dword v3, v22, s[34:35]
	s_add_u32 s24, s24, 0x2000
	s_addc_u32 s25, s25, 0
	s_add_u32 s34, s34, 0x100
	s_addc_u32 s35, s35, 0
	v_lshlrev_b32_e32 v18, 16, v152
	v_and_b32_e32 v19, 0xffff0000, v152
	v_mul_f32_e32 v16, v16, v14
	v_mul_f32_e32 v17, v17, v14
	v_fmac_f32_e32 v16, v15, v18
	v_fmac_f32_e32 v17, v15, v19
	v_mul_f32_e32 v22, v22, v14
	v_fmac_f32_e32 v22, v15, v245
	v_readlane_b32 s2, v6, 41
	v_readlane_b32 s3, v7, 41
	v_add_f32_e32 v12, s1, v10
	v_max_f32_e32 v11, s0, v12
	v_sub_f32_e32 v12, v12, v11
	v_sub_f32_e32 v13, s0, v11
	v_mul_f32_e32 v12, 0x3fb8aa3b, v12
	v_mul_f32_e32 v13, 0x3fb8aa3b, v13
	v_exp_f32_e32 v14, v12
	v_exp_f32_e32 v15, v13
	s_mov_b64 exec, 1
	global_store_dword v4, v10, s[22:23] offset:160
	s_mov_b64 exec, -1
	v_cvt_pk_bf16_f32 v20, v16, v17
	global_store_dword v1, v20, s[24:25]
	global_store_dword v3, v22, s[34:35]
	s_add_u32 s24, s24, 0x2000
	s_addc_u32 s25, s25, 0
	s_add_u32 s34, s34, 0x100
	s_addc_u32 s35, s35, 0
	v_lshlrev_b32_e32 v18, 16, v153
	v_and_b32_e32 v19, 0xffff0000, v153
	v_mul_f32_e32 v16, v16, v14
	v_mul_f32_e32 v17, v17, v14
	v_fmac_f32_e32 v16, v15, v18
	v_fmac_f32_e32 v17, v15, v19
	v_mul_f32_e32 v22, v22, v14
	v_fmac_f32_e32 v22, v15, v60
	v_readlane_b32 s0, v6, 42
	v_readlane_b32 s1, v7, 42
	v_add_f32_e32 v12, s3, v11
	v_max_f32_e32 v10, s2, v12
	v_sub_f32_e32 v12, v12, v10
	v_sub_f32_e32 v13, s2, v10
	v_mul_f32_e32 v12, 0x3fb8aa3b, v12
	v_mul_f32_e32 v13, 0x3fb8aa3b, v13
	v_exp_f32_e32 v14, v12
	v_exp_f32_e32 v15, v13
	s_mov_b64 exec, 1
	global_store_dword v4, v11, s[22:23] offset:164
	s_mov_b64 exec, -1
	v_cvt_pk_bf16_f32 v21, v16, v17
	global_store_dword v1, v21, s[24:25]
	global_store_dword v3, v22, s[34:35]
	s_add_u32 s24, s24, 0x2000
	s_addc_u32 s25, s25, 0
	s_add_u32 s34, s34, 0x100
	s_addc_u32 s35, s35, 0
	v_lshlrev_b32_e32 v18, 16, v154
	v_and_b32_e32 v19, 0xffff0000, v154
	v_mul_f32_e32 v16, v16, v14
	v_mul_f32_e32 v17, v17, v14
	v_fmac_f32_e32 v16, v15, v18
	v_fmac_f32_e32 v17, v15, v19
	v_mul_f32_e32 v22, v22, v14
	v_fmac_f32_e32 v22, v15, v61
	v_readlane_b32 s2, v6, 43
	v_readlane_b32 s3, v7, 43
	v_add_f32_e32 v12, s1, v10
	v_max_f32_e32 v11, s0, v12
	v_sub_f32_e32 v12, v12, v11
	v_sub_f32_e32 v13, s0, v11
	v_mul_f32_e32 v12, 0x3fb8aa3b, v12
	v_mul_f32_e32 v13, 0x3fb8aa3b, v13
	v_exp_f32_e32 v14, v12
	v_exp_f32_e32 v15, v13
	s_mov_b64 exec, 1
	global_store_dword v4, v10, s[22:23] offset:168
	s_mov_b64 exec, -1
	v_cvt_pk_bf16_f32 v20, v16, v17
	global_store_dword v1, v20, s[24:25]
	global_store_dword v3, v22, s[34:35]
	s_add_u32 s24, s24, 0x2000
	s_addc_u32 s25, s25, 0
	s_add_u32 s34, s34, 0x100
	s_addc_u32 s35, s35, 0
	v_lshlrev_b32_e32 v18, 16, v155
	v_and_b32_e32 v19, 0xffff0000, v155
	v_mul_f32_e32 v16, v16, v14
	v_mul_f32_e32 v17, v17, v14
	v_fmac_f32_e32 v16, v15, v18
	v_fmac_f32_e32 v17, v15, v19
	v_mul_f32_e32 v22, v22, v14
	v_fmac_f32_e32 v22, v15, v62
	v_readlane_b32 s0, v6, 44
	v_readlane_b32 s1, v7, 44
	v_add_f32_e32 v12, s3, v11
	v_max_f32_e32 v10, s2, v12
	v_sub_f32_e32 v12, v12, v10
	v_sub_f32_e32 v13, s2, v10
	v_mul_f32_e32 v12, 0x3fb8aa3b, v12
	v_mul_f32_e32 v13, 0x3fb8aa3b, v13
	v_exp_f32_e32 v14, v12
	v_exp_f32_e32 v15, v13
	s_mov_b64 exec, 1
	global_store_dword v4, v11, s[22:23] offset:172
	s_mov_b64 exec, -1
	v_cvt_pk_bf16_f32 v21, v16, v17
	global_store_dword v1, v21, s[24:25]
	global_store_dword v3, v22, s[34:35]
	s_add_u32 s24, s24, 0x2000
	s_addc_u32 s25, s25, 0
	s_add_u32 s34, s34, 0x100
	s_addc_u32 s35, s35, 0
	v_lshlrev_b32_e32 v18, 16, v156
	v_and_b32_e32 v19, 0xffff0000, v156
	v_mul_f32_e32 v16, v16, v14
	v_mul_f32_e32 v17, v17, v14
	v_fmac_f32_e32 v16, v15, v18
	v_fmac_f32_e32 v17, v15, v19
	v_mul_f32_e32 v22, v22, v14
	v_fmac_f32_e32 v22, v15, v63
	v_readlane_b32 s2, v6, 45
	v_readlane_b32 s3, v7, 45
	v_add_f32_e32 v12, s1, v10
	v_max_f32_e32 v11, s0, v12
	v_sub_f32_e32 v12, v12, v11
	v_sub_f32_e32 v13, s0, v11
	v_mul_f32_e32 v12, 0x3fb8aa3b, v12
	v_mul_f32_e32 v13, 0x3fb8aa3b, v13
	v_exp_f32_e32 v14, v12
	v_exp_f32_e32 v15, v13
	s_mov_b64 exec, 1
	global_store_dword v4, v10, s[22:23] offset:176
	s_mov_b64 exec, -1
	v_cvt_pk_bf16_f32 v20, v16, v17
	global_store_dword v1, v20, s[24:25]
	global_store_dword v3, v22, s[34:35]
	s_add_u32 s24, s24, 0x2000
	s_addc_u32 s25, s25, 0
	s_add_u32 s34, s34, 0x100
	s_addc_u32 s35, s35, 0
	v_lshlrev_b32_e32 v18, 16, v157
	v_and_b32_e32 v19, 0xffff0000, v157
	v_mul_f32_e32 v16, v16, v14
	v_mul_f32_e32 v17, v17, v14
	v_fmac_f32_e32 v16, v15, v18
	v_fmac_f32_e32 v17, v15, v19
	v_mul_f32_e32 v22, v22, v14
	v_fmac_f32_e32 v22, v15, v64
	v_readlane_b32 s0, v6, 46
	v_readlane_b32 s1, v7, 46
	v_add_f32_e32 v12, s3, v11
	v_max_f32_e32 v10, s2, v12
	v_sub_f32_e32 v12, v12, v10
	v_sub_f32_e32 v13, s2, v10
	v_mul_f32_e32 v12, 0x3fb8aa3b, v12
	v_mul_f32_e32 v13, 0x3fb8aa3b, v13
	v_exp_f32_e32 v14, v12
	v_exp_f32_e32 v15, v13
	s_mov_b64 exec, 1
	global_store_dword v4, v11, s[22:23] offset:180
	s_mov_b64 exec, -1
	v_cvt_pk_bf16_f32 v21, v16, v17
	global_store_dword v1, v21, s[24:25]
	global_store_dword v3, v22, s[34:35]
	s_add_u32 s24, s24, 0x2000
	s_addc_u32 s25, s25, 0
	s_add_u32 s34, s34, 0x100
	s_addc_u32 s35, s35, 0
	v_lshlrev_b32_e32 v18, 16, v158
	v_and_b32_e32 v19, 0xffff0000, v158
	v_mul_f32_e32 v16, v16, v14
	v_mul_f32_e32 v17, v17, v14
	v_fmac_f32_e32 v16, v15, v18
	v_fmac_f32_e32 v17, v15, v19
	v_mul_f32_e32 v22, v22, v14
	v_fmac_f32_e32 v22, v15, v65
	v_readlane_b32 s2, v6, 47
	v_readlane_b32 s3, v7, 47
	v_add_f32_e32 v12, s1, v10
	v_max_f32_e32 v11, s0, v12
	v_sub_f32_e32 v12, v12, v11
	v_sub_f32_e32 v13, s0, v11
	v_mul_f32_e32 v12, 0x3fb8aa3b, v12
	v_mul_f32_e32 v13, 0x3fb8aa3b, v13
	v_exp_f32_e32 v14, v12
	v_exp_f32_e32 v15, v13
	s_mov_b64 exec, 1
	global_store_dword v4, v10, s[22:23] offset:184
	s_mov_b64 exec, -1
	v_cvt_pk_bf16_f32 v20, v16, v17
	global_store_dword v1, v20, s[24:25]
	global_store_dword v3, v22, s[34:35]
	s_add_u32 s24, s24, 0x2000
	s_addc_u32 s25, s25, 0
	s_add_u32 s34, s34, 0x100
	s_addc_u32 s35, s35, 0
	v_lshlrev_b32_e32 v18, 16, v159
	v_and_b32_e32 v19, 0xffff0000, v159
	v_mul_f32_e32 v16, v16, v14
	v_mul_f32_e32 v17, v17, v14
	v_fmac_f32_e32 v16, v15, v18
	v_fmac_f32_e32 v17, v15, v19
	v_mul_f32_e32 v22, v22, v14
	v_fmac_f32_e32 v22, v15, v66
	v_readlane_b32 s0, v6, 48
	v_readlane_b32 s1, v7, 48
	v_add_f32_e32 v12, s3, v11
	v_max_f32_e32 v10, s2, v12
	v_sub_f32_e32 v12, v12, v10
	v_sub_f32_e32 v13, s2, v10
	v_mul_f32_e32 v12, 0x3fb8aa3b, v12
	v_mul_f32_e32 v13, 0x3fb8aa3b, v13
	v_exp_f32_e32 v14, v12
	v_exp_f32_e32 v15, v13
	s_mov_b64 exec, 1
	global_store_dword v4, v11, s[22:23] offset:188
	s_mov_b64 exec, -1
	v_cvt_pk_bf16_f32 v21, v16, v17
	global_store_dword v1, v21, s[24:25]
	global_store_dword v3, v22, s[34:35]
	s_add_u32 s24, s24, 0x2000
	s_addc_u32 s25, s25, 0
	s_add_u32 s34, s34, 0x100
	s_addc_u32 s35, s35, 0
	v_lshlrev_b32_e32 v18, 16, v160
	v_and_b32_e32 v19, 0xffff0000, v160
	v_mul_f32_e32 v16, v16, v14
	v_mul_f32_e32 v17, v17, v14
	v_fmac_f32_e32 v16, v15, v18
	v_fmac_f32_e32 v17, v15, v19
	v_mul_f32_e32 v22, v22, v14
	v_fmac_f32_e32 v22, v15, v67
	v_readlane_b32 s2, v6, 49
	v_readlane_b32 s3, v7, 49
	v_add_f32_e32 v12, s1, v10
	v_max_f32_e32 v11, s0, v12
	v_sub_f32_e32 v12, v12, v11
	v_sub_f32_e32 v13, s0, v11
	v_mul_f32_e32 v12, 0x3fb8aa3b, v12
	v_mul_f32_e32 v13, 0x3fb8aa3b, v13
	v_exp_f32_e32 v14, v12
	v_exp_f32_e32 v15, v13
	s_mov_b64 exec, 1
	global_store_dword v4, v10, s[22:23] offset:192
	s_mov_b64 exec, -1
	v_cvt_pk_bf16_f32 v20, v16, v17
	global_store_dword v1, v20, s[24:25]
	global_store_dword v3, v22, s[34:35]
	s_add_u32 s24, s24, 0x2000
	s_addc_u32 s25, s25, 0
	s_add_u32 s34, s34, 0x100
	s_addc_u32 s35, s35, 0
	v_lshlrev_b32_e32 v18, 16, v164
	v_and_b32_e32 v19, 0xffff0000, v164
	v_mul_f32_e32 v16, v16, v14
	v_mul_f32_e32 v17, v17, v14
	v_fmac_f32_e32 v16, v15, v18
	v_fmac_f32_e32 v17, v15, v19
	v_mul_f32_e32 v22, v22, v14
	v_fmac_f32_e32 v22, v15, v68
	v_readlane_b32 s0, v6, 50
	v_readlane_b32 s1, v7, 50
	v_add_f32_e32 v12, s3, v11
	v_max_f32_e32 v10, s2, v12
	v_sub_f32_e32 v12, v12, v10
	v_sub_f32_e32 v13, s2, v10
	v_mul_f32_e32 v12, 0x3fb8aa3b, v12
	v_mul_f32_e32 v13, 0x3fb8aa3b, v13
	v_exp_f32_e32 v14, v12
	v_exp_f32_e32 v15, v13
	s_mov_b64 exec, 1
	global_store_dword v4, v11, s[22:23] offset:196
	s_mov_b64 exec, -1
	v_cvt_pk_bf16_f32 v21, v16, v17
	global_store_dword v1, v21, s[24:25]
	global_store_dword v3, v22, s[34:35]
	s_add_u32 s24, s24, 0x2000
	s_addc_u32 s25, s25, 0
	s_add_u32 s34, s34, 0x100
	s_addc_u32 s35, s35, 0
	v_lshlrev_b32_e32 v18, 16, v165
	v_and_b32_e32 v19, 0xffff0000, v165
	v_mul_f32_e32 v16, v16, v14
	v_mul_f32_e32 v17, v17, v14
	v_fmac_f32_e32 v16, v15, v18
	v_fmac_f32_e32 v17, v15, v19
	v_mul_f32_e32 v22, v22, v14
	v_fmac_f32_e32 v22, v15, v69
	v_readlane_b32 s2, v6, 51
	v_readlane_b32 s3, v7, 51
	v_add_f32_e32 v12, s1, v10
	v_max_f32_e32 v11, s0, v12
	v_sub_f32_e32 v12, v12, v11
	v_sub_f32_e32 v13, s0, v11
	v_mul_f32_e32 v12, 0x3fb8aa3b, v12
	v_mul_f32_e32 v13, 0x3fb8aa3b, v13
	v_exp_f32_e32 v14, v12
	v_exp_f32_e32 v15, v13
	s_mov_b64 exec, 1
	global_store_dword v4, v10, s[22:23] offset:200
	s_mov_b64 exec, -1
	v_cvt_pk_bf16_f32 v20, v16, v17
	global_store_dword v1, v20, s[24:25]
	global_store_dword v3, v22, s[34:35]
	s_add_u32 s24, s24, 0x2000
	s_addc_u32 s25, s25, 0
	s_add_u32 s34, s34, 0x100
	s_addc_u32 s35, s35, 0
	v_lshlrev_b32_e32 v18, 16, v166
	v_and_b32_e32 v19, 0xffff0000, v166
	v_mul_f32_e32 v16, v16, v14
	v_mul_f32_e32 v17, v17, v14
	v_fmac_f32_e32 v16, v15, v18
	v_fmac_f32_e32 v17, v15, v19
	v_mul_f32_e32 v22, v22, v14
	v_fmac_f32_e32 v22, v15, v70
	v_readlane_b32 s0, v6, 52
	v_readlane_b32 s1, v7, 52
	v_add_f32_e32 v12, s3, v11
	v_max_f32_e32 v10, s2, v12
	v_sub_f32_e32 v12, v12, v10
	v_sub_f32_e32 v13, s2, v10
	v_mul_f32_e32 v12, 0x3fb8aa3b, v12
	v_mul_f32_e32 v13, 0x3fb8aa3b, v13
	v_exp_f32_e32 v14, v12
	v_exp_f32_e32 v15, v13
	s_mov_b64 exec, 1
	global_store_dword v4, v11, s[22:23] offset:204
	s_mov_b64 exec, -1
	v_cvt_pk_bf16_f32 v21, v16, v17
	global_store_dword v1, v21, s[24:25]
	global_store_dword v3, v22, s[34:35]
	s_add_u32 s24, s24, 0x2000
	s_addc_u32 s25, s25, 0
	s_add_u32 s34, s34, 0x100
	s_addc_u32 s35, s35, 0
	v_lshlrev_b32_e32 v18, 16, v167
	v_and_b32_e32 v19, 0xffff0000, v167
	v_mul_f32_e32 v16, v16, v14
	v_mul_f32_e32 v17, v17, v14
	v_fmac_f32_e32 v16, v15, v18
	v_fmac_f32_e32 v17, v15, v19
	v_mul_f32_e32 v22, v22, v14
	v_fmac_f32_e32 v22, v15, v71
	v_readlane_b32 s2, v6, 53
	v_readlane_b32 s3, v7, 53
	v_add_f32_e32 v12, s1, v10
	v_max_f32_e32 v11, s0, v12
	v_sub_f32_e32 v12, v12, v11
	v_sub_f32_e32 v13, s0, v11
	v_mul_f32_e32 v12, 0x3fb8aa3b, v12
	v_mul_f32_e32 v13, 0x3fb8aa3b, v13
	v_exp_f32_e32 v14, v12
	v_exp_f32_e32 v15, v13
	s_mov_b64 exec, 1
	global_store_dword v4, v10, s[22:23] offset:208
	s_mov_b64 exec, -1
	v_cvt_pk_bf16_f32 v20, v16, v17
	global_store_dword v1, v20, s[24:25]
	global_store_dword v3, v22, s[34:35]
	s_add_u32 s24, s24, 0x2000
	s_addc_u32 s25, s25, 0
	s_add_u32 s34, s34, 0x100
	s_addc_u32 s35, s35, 0
	v_lshlrev_b32_e32 v18, 16, v168
	v_and_b32_e32 v19, 0xffff0000, v168
	v_mul_f32_e32 v16, v16, v14
	v_mul_f32_e32 v17, v17, v14
	v_fmac_f32_e32 v16, v15, v18
	v_fmac_f32_e32 v17, v15, v19
	v_mul_f32_e32 v22, v22, v14
	v_fmac_f32_e32 v22, v15, v72
	v_readlane_b32 s0, v6, 54
	v_readlane_b32 s1, v7, 54
	v_add_f32_e32 v12, s3, v11
	v_max_f32_e32 v10, s2, v12
	v_sub_f32_e32 v12, v12, v10
	v_sub_f32_e32 v13, s2, v10
	v_mul_f32_e32 v12, 0x3fb8aa3b, v12
	v_mul_f32_e32 v13, 0x3fb8aa3b, v13
	v_exp_f32_e32 v14, v12
	v_exp_f32_e32 v15, v13
	s_mov_b64 exec, 1
	global_store_dword v4, v11, s[22:23] offset:212
	s_mov_b64 exec, -1
	v_cvt_pk_bf16_f32 v21, v16, v17
	global_store_dword v1, v21, s[24:25]
	global_store_dword v3, v22, s[34:35]
	s_add_u32 s24, s24, 0x2000
	s_addc_u32 s25, s25, 0
	s_add_u32 s34, s34, 0x100
	s_addc_u32 s35, s35, 0
	v_lshlrev_b32_e32 v18, 16, v169
	v_and_b32_e32 v19, 0xffff0000, v169
	v_mul_f32_e32 v16, v16, v14
	v_mul_f32_e32 v17, v17, v14
	v_fmac_f32_e32 v16, v15, v18
	v_fmac_f32_e32 v17, v15, v19
	v_mul_f32_e32 v22, v22, v14
	v_fmac_f32_e32 v22, v15, v73
	v_readlane_b32 s2, v6, 55
	v_readlane_b32 s3, v7, 55
	v_add_f32_e32 v12, s1, v10
	v_max_f32_e32 v11, s0, v12
	v_sub_f32_e32 v12, v12, v11
	v_sub_f32_e32 v13, s0, v11
	v_mul_f32_e32 v12, 0x3fb8aa3b, v12
	v_mul_f32_e32 v13, 0x3fb8aa3b, v13
	v_exp_f32_e32 v14, v12
	v_exp_f32_e32 v15, v13
	s_mov_b64 exec, 1
	global_store_dword v4, v10, s[22:23] offset:216
	s_mov_b64 exec, -1
	v_cvt_pk_bf16_f32 v20, v16, v17
	global_store_dword v1, v20, s[24:25]
	global_store_dword v3, v22, s[34:35]
	s_add_u32 s24, s24, 0x2000
	s_addc_u32 s25, s25, 0
	s_add_u32 s34, s34, 0x100
	s_addc_u32 s35, s35, 0
	v_lshlrev_b32_e32 v18, 16, v170
	v_and_b32_e32 v19, 0xffff0000, v170
	v_mul_f32_e32 v16, v16, v14
	v_mul_f32_e32 v17, v17, v14
	v_fmac_f32_e32 v16, v15, v18
	v_fmac_f32_e32 v17, v15, v19
	v_mul_f32_e32 v22, v22, v14
	v_fmac_f32_e32 v22, v15, v74
	v_readlane_b32 s0, v6, 56
	v_readlane_b32 s1, v7, 56
	v_add_f32_e32 v12, s3, v11
	v_max_f32_e32 v10, s2, v12
	v_sub_f32_e32 v12, v12, v10
	v_sub_f32_e32 v13, s2, v10
	v_mul_f32_e32 v12, 0x3fb8aa3b, v12
	v_mul_f32_e32 v13, 0x3fb8aa3b, v13
	v_exp_f32_e32 v14, v12
	v_exp_f32_e32 v15, v13
	s_mov_b64 exec, 1
	global_store_dword v4, v11, s[22:23] offset:220
	s_mov_b64 exec, -1
	v_cvt_pk_bf16_f32 v21, v16, v17
	global_store_dword v1, v21, s[24:25]
	global_store_dword v3, v22, s[34:35]
	s_add_u32 s24, s24, 0x2000
	s_addc_u32 s25, s25, 0
	s_add_u32 s34, s34, 0x100
	s_addc_u32 s35, s35, 0
	v_lshlrev_b32_e32 v18, 16, v171
	v_and_b32_e32 v19, 0xffff0000, v171
	v_mul_f32_e32 v16, v16, v14
	v_mul_f32_e32 v17, v17, v14
	v_fmac_f32_e32 v16, v15, v18
	v_fmac_f32_e32 v17, v15, v19
	v_mul_f32_e32 v22, v22, v14
	v_fmac_f32_e32 v22, v15, v75
	v_readlane_b32 s2, v6, 57
	v_readlane_b32 s3, v7, 57
	v_add_f32_e32 v12, s1, v10
	v_max_f32_e32 v11, s0, v12
	v_sub_f32_e32 v12, v12, v11
	v_sub_f32_e32 v13, s0, v11
	v_mul_f32_e32 v12, 0x3fb8aa3b, v12
	v_mul_f32_e32 v13, 0x3fb8aa3b, v13
	v_exp_f32_e32 v14, v12
	v_exp_f32_e32 v15, v13
	s_mov_b64 exec, 1
	global_store_dword v4, v10, s[22:23] offset:224
	s_mov_b64 exec, -1
	v_cvt_pk_bf16_f32 v20, v16, v17
	global_store_dword v1, v20, s[24:25]
	global_store_dword v3, v22, s[34:35]
	s_add_u32 s24, s24, 0x2000
	s_addc_u32 s25, s25, 0
	s_add_u32 s34, s34, 0x100
	s_addc_u32 s35, s35, 0
	v_lshlrev_b32_e32 v18, 16, v172
	v_and_b32_e32 v19, 0xffff0000, v172
	v_mul_f32_e32 v16, v16, v14
	v_mul_f32_e32 v17, v17, v14
	v_fmac_f32_e32 v16, v15, v18
	v_fmac_f32_e32 v17, v15, v19
	v_mul_f32_e32 v22, v22, v14
	v_fmac_f32_e32 v22, v15, v48
	v_readlane_b32 s0, v6, 58
	v_readlane_b32 s1, v7, 58
	v_add_f32_e32 v12, s3, v11
	v_max_f32_e32 v10, s2, v12
	v_sub_f32_e32 v12, v12, v10
	v_sub_f32_e32 v13, s2, v10
	v_mul_f32_e32 v12, 0x3fb8aa3b, v12
	v_mul_f32_e32 v13, 0x3fb8aa3b, v13
	v_exp_f32_e32 v14, v12
	v_exp_f32_e32 v15, v13
	s_mov_b64 exec, 1
	global_store_dword v4, v11, s[22:23] offset:228
	s_mov_b64 exec, -1
	v_cvt_pk_bf16_f32 v21, v16, v17
	global_store_dword v1, v21, s[24:25]
	global_store_dword v3, v22, s[34:35]
	s_add_u32 s24, s24, 0x2000
	s_addc_u32 s25, s25, 0
	s_add_u32 s34, s34, 0x100
	s_addc_u32 s35, s35, 0
	v_lshlrev_b32_e32 v18, 16, v173
	v_and_b32_e32 v19, 0xffff0000, v173
	v_mul_f32_e32 v16, v16, v14
	v_mul_f32_e32 v17, v17, v14
	v_fmac_f32_e32 v16, v15, v18
	v_fmac_f32_e32 v17, v15, v19
	v_mul_f32_e32 v22, v22, v14
	v_fmac_f32_e32 v22, v15, v49
	v_readlane_b32 s2, v6, 59
	v_readlane_b32 s3, v7, 59
	v_add_f32_e32 v12, s1, v10
	v_max_f32_e32 v11, s0, v12
	v_sub_f32_e32 v12, v12, v11
	v_sub_f32_e32 v13, s0, v11
	v_mul_f32_e32 v12, 0x3fb8aa3b, v12
	v_mul_f32_e32 v13, 0x3fb8aa3b, v13
	v_exp_f32_e32 v14, v12
	v_exp_f32_e32 v15, v13
	s_mov_b64 exec, 1
	global_store_dword v4, v10, s[22:23] offset:232
	s_mov_b64 exec, -1
	v_cvt_pk_bf16_f32 v20, v16, v17
	global_store_dword v1, v20, s[24:25]
	global_store_dword v3, v22, s[34:35]
	s_add_u32 s24, s24, 0x2000
	s_addc_u32 s25, s25, 0
	s_add_u32 s34, s34, 0x100
	s_addc_u32 s35, s35, 0
	v_lshlrev_b32_e32 v18, 16, v174
	v_and_b32_e32 v19, 0xffff0000, v174
	v_mul_f32_e32 v16, v16, v14
	v_mul_f32_e32 v17, v17, v14
	v_fmac_f32_e32 v16, v15, v18
	v_fmac_f32_e32 v17, v15, v19
	v_mul_f32_e32 v22, v22, v14
	v_fmac_f32_e32 v22, v15, v50
	v_readlane_b32 s0, v6, 60
	v_readlane_b32 s1, v7, 60
	v_add_f32_e32 v12, s3, v11
	v_max_f32_e32 v10, s2, v12
	v_sub_f32_e32 v12, v12, v10
	v_sub_f32_e32 v13, s2, v10
	v_mul_f32_e32 v12, 0x3fb8aa3b, v12
	v_mul_f32_e32 v13, 0x3fb8aa3b, v13
	v_exp_f32_e32 v14, v12
	v_exp_f32_e32 v15, v13
	s_mov_b64 exec, 1
	global_store_dword v4, v11, s[22:23] offset:236
	s_mov_b64 exec, -1
	v_cvt_pk_bf16_f32 v21, v16, v17
	global_store_dword v1, v21, s[24:25]
	global_store_dword v3, v22, s[34:35]
	s_add_u32 s24, s24, 0x2000
	s_addc_u32 s25, s25, 0
	s_add_u32 s34, s34, 0x100
	s_addc_u32 s35, s35, 0
	v_lshlrev_b32_e32 v18, 16, v175
	v_and_b32_e32 v19, 0xffff0000, v175
	v_mul_f32_e32 v16, v16, v14
	v_mul_f32_e32 v17, v17, v14
	v_fmac_f32_e32 v16, v15, v18
	v_fmac_f32_e32 v17, v15, v19
	v_mul_f32_e32 v22, v22, v14
	v_fmac_f32_e32 v22, v15, v51
	v_readlane_b32 s2, v6, 61
	v_readlane_b32 s3, v7, 61
	v_add_f32_e32 v12, s1, v10
	v_max_f32_e32 v11, s0, v12
	v_sub_f32_e32 v12, v12, v11
	v_sub_f32_e32 v13, s0, v11
	v_mul_f32_e32 v12, 0x3fb8aa3b, v12
	v_mul_f32_e32 v13, 0x3fb8aa3b, v13
	v_exp_f32_e32 v14, v12
	v_exp_f32_e32 v15, v13
	s_mov_b64 exec, 1
	global_store_dword v4, v10, s[22:23] offset:240
	s_mov_b64 exec, -1
	v_cvt_pk_bf16_f32 v20, v16, v17
	global_store_dword v1, v20, s[24:25]
	global_store_dword v3, v22, s[34:35]
	s_add_u32 s24, s24, 0x2000
	s_addc_u32 s25, s25, 0
	s_add_u32 s34, s34, 0x100
	s_addc_u32 s35, s35, 0
	v_lshlrev_b32_e32 v18, 16, v198
	v_and_b32_e32 v19, 0xffff0000, v198
	v_mul_f32_e32 v16, v16, v14
	v_mul_f32_e32 v17, v17, v14
	v_fmac_f32_e32 v16, v15, v18
	v_fmac_f32_e32 v17, v15, v19
	v_mul_f32_e32 v22, v22, v14
	v_fmac_f32_e32 v22, v15, v52
	v_readlane_b32 s0, v6, 62
	v_readlane_b32 s1, v7, 62
	v_add_f32_e32 v12, s3, v11
	v_max_f32_e32 v10, s2, v12
	v_sub_f32_e32 v12, v12, v10
	v_sub_f32_e32 v13, s2, v10
	v_mul_f32_e32 v12, 0x3fb8aa3b, v12
	v_mul_f32_e32 v13, 0x3fb8aa3b, v13
	v_exp_f32_e32 v14, v12
	v_exp_f32_e32 v15, v13
	s_mov_b64 exec, 1
	global_store_dword v4, v11, s[22:23] offset:244
	s_mov_b64 exec, -1
	v_cvt_pk_bf16_f32 v21, v16, v17
	global_store_dword v1, v21, s[24:25]
	global_store_dword v3, v22, s[34:35]
	s_add_u32 s24, s24, 0x2000
	s_addc_u32 s25, s25, 0
	s_add_u32 s34, s34, 0x100
	s_addc_u32 s35, s35, 0
	v_lshlrev_b32_e32 v18, 16, v199
	v_and_b32_e32 v19, 0xffff0000, v199
	v_mul_f32_e32 v16, v16, v14
	v_mul_f32_e32 v17, v17, v14
	v_fmac_f32_e32 v16, v15, v18
	v_fmac_f32_e32 v17, v15, v19
	v_mul_f32_e32 v22, v22, v14
	v_fmac_f32_e32 v22, v15, v53
	v_readlane_b32 s2, v6, 63
	v_readlane_b32 s3, v7, 63
	v_add_f32_e32 v12, s1, v10
	v_max_f32_e32 v11, s0, v12
	v_sub_f32_e32 v12, v12, v11
	v_sub_f32_e32 v13, s0, v11
	v_mul_f32_e32 v12, 0x3fb8aa3b, v12
	v_mul_f32_e32 v13, 0x3fb8aa3b, v13
	v_exp_f32_e32 v14, v12
	v_exp_f32_e32 v15, v13
	s_mov_b64 exec, 1
	global_store_dword v4, v10, s[22:23] offset:248
	s_mov_b64 exec, -1
	v_cvt_pk_bf16_f32 v20, v16, v17
	global_store_dword v1, v20, s[24:25]
	global_store_dword v3, v22, s[34:35]
	s_add_u32 s24, s24, 0x2000
	s_addc_u32 s25, s25, 0
	s_add_u32 s34, s34, 0x100
	s_addc_u32 s35, s35, 0
	v_lshlrev_b32_e32 v18, 16, v200
	v_and_b32_e32 v19, 0xffff0000, v200
	v_mul_f32_e32 v16, v16, v14
	v_mul_f32_e32 v17, v17, v14
	v_fmac_f32_e32 v16, v15, v18
	v_fmac_f32_e32 v17, v15, v19
	v_mul_f32_e32 v22, v22, v14
	v_fmac_f32_e32 v22, v15, v54
	v_readlane_b32 s0, v8, 0
	v_readlane_b32 s1, v9, 0
	v_add_f32_e32 v12, s3, v11
	v_max_f32_e32 v10, s2, v12
	v_sub_f32_e32 v12, v12, v10
	v_sub_f32_e32 v13, s2, v10
	v_mul_f32_e32 v12, 0x3fb8aa3b, v12
	v_mul_f32_e32 v13, 0x3fb8aa3b, v13
	v_exp_f32_e32 v14, v12
	v_exp_f32_e32 v15, v13
	s_mov_b64 exec, 1
	global_store_dword v4, v11, s[22:23] offset:252
	s_mov_b64 exec, -1
	v_cvt_pk_bf16_f32 v21, v16, v17
	global_store_dword v1, v21, s[24:25]
	global_store_dword v3, v22, s[34:35]
	s_add_u32 s24, s24, 0x2000
	s_addc_u32 s25, s25, 0
	s_add_u32 s34, s34, 0x100
	s_addc_u32 s35, s35, 0
	v_lshlrev_b32_e32 v18, 16, v201
	v_and_b32_e32 v19, 0xffff0000, v201
	v_mul_f32_e32 v16, v16, v14
	v_mul_f32_e32 v17, v17, v14
	v_fmac_f32_e32 v16, v15, v18
	v_fmac_f32_e32 v17, v15, v19
	v_mul_f32_e32 v22, v22, v14
	v_fmac_f32_e32 v22, v15, v55
	v_readlane_b32 s2, v8, 1
	v_readlane_b32 s3, v9, 1
	v_add_f32_e32 v12, s1, v10
	v_max_f32_e32 v11, s0, v12
	v_sub_f32_e32 v12, v12, v11
	v_sub_f32_e32 v13, s0, v11
	v_mul_f32_e32 v12, 0x3fb8aa3b, v12
	v_mul_f32_e32 v13, 0x3fb8aa3b, v13
	v_exp_f32_e32 v14, v12
	v_exp_f32_e32 v15, v13
	s_mov_b64 exec, 1
	global_store_dword v4, v10, s[22:23] offset:256
	s_mov_b64 exec, -1
	v_cvt_pk_bf16_f32 v20, v16, v17
	global_store_dword v1, v20, s[24:25]
	global_store_dword v3, v22, s[34:35]
	s_add_u32 s24, s24, 0x2000
	s_addc_u32 s25, s25, 0
	s_add_u32 s34, s34, 0x100
	s_addc_u32 s35, s35, 0
	v_lshlrev_b32_e32 v18, 16, v202
	v_and_b32_e32 v19, 0xffff0000, v202
	v_mul_f32_e32 v16, v16, v14
	v_mul_f32_e32 v17, v17, v14
	v_fmac_f32_e32 v16, v15, v18
	v_fmac_f32_e32 v17, v15, v19
	v_mul_f32_e32 v22, v22, v14
	v_fmac_f32_e32 v22, v15, v36
	s_mov_b64 exec, 1
	global_store_dword v4, v11, s[22:23] offset:260
	s_mov_b64 exec, -1
	v_cvt_pk_bf16_f32 v21, v16, v17
	global_store_dword v1, v21, s[24:25]
	global_store_dword v3, v22, s[34:35]
	s_branch .Lscan_next
.Lscan_type0:
	s_load_dwordx2 s[2:3], s[54:55], 0x58
	s_lshr_b32 s0, s31, 1
	s_and_b32 s1, s31, 7
	s_and_b32 s0, s0, 8
	s_or_b32 s1, s0, s1
	s_lshl_b32 s1, s1, 2
	v_mov_b32_e32 v6, s1
	s_waitcnt lgkmcnt(0)
	global_load_dword v6, v6, s[2:3]
	s_mov_b32 s0, 0x3fb8aa3b
	s_mov_b32 s1, 0xc2ce8ed0
	s_waitcnt vmcnt(0)
	v_mul_f32_e32 v6, 0x43000000, v6
	v_mul_f32_e32 v7, 0x3fb8aa3b, v6
	v_fma_f32 v8, v6, s0, -v7
	v_rndne_f32_e32 v9, v7
	v_fmac_f32_e32 v8, 0x32a5705f, v6
	v_sub_f32_e32 v7, v7, v9
	v_add_f32_e32 v7, v7, v8
	v_cvt_i32_f32_e32 v9, v9
	v_exp_f32_e32 v7, v7
	v_cmp_ngt_f32_e32 vcc, s1, v6
	s_mov_b32 s1, 0x42b17218
	v_ldexp_f32 v7, v7, v9
	v_cndmask_b32_e32 v7, 0, v7, vcc
	v_cmp_nlt_f32_e32 vcc, s1, v6
	s_nop 1
	v_cndmask_b32_e32 v14, v162, v7, vcc
	v_cvt_pk_bf16_f32 v20, v16, v17
	global_store_dword v1, v20, s[24:25]
	s_add_u32 s24, s24, 0x2000
	s_addc_u32 s25, s25, 0
	v_lshlrev_b32_e32 v18, 16, v110
	v_and_b32_e32 v19, 0xffff0000, v110
	v_mul_f32_e32 v16, v16, v14
	v_mul_f32_e32 v17, v17, v14
	v_add_f32_e32 v16, v16, v18
	v_add_f32_e32 v17, v17, v19
	v_cvt_pk_bf16_f32 v21, v16, v17
	global_store_dword v1, v21, s[24:25]
	s_add_u32 s24, s24, 0x2000
	s_addc_u32 s25, s25, 0
	v_lshlrev_b32_e32 v18, 16, v111
	v_and_b32_e32 v19, 0xffff0000, v111
	v_mul_f32_e32 v16, v16, v14
	v_mul_f32_e32 v17, v17, v14
	v_add_f32_e32 v16, v16, v18
	v_add_f32_e32 v17, v17, v19
	v_cvt_pk_bf16_f32 v20, v16, v17
	global_store_dword v1, v20, s[24:25]
	s_add_u32 s24, s24, 0x2000
	s_addc_u32 s25, s25, 0
	v_lshlrev_b32_e32 v18, 16, v112
	v_and_b32_e32 v19, 0xffff0000, v112
	v_mul_f32_e32 v16, v16, v14
	v_mul_f32_e32 v17, v17, v14
	v_add_f32_e32 v16, v16, v18
	v_add_f32_e32 v17, v17, v19
	v_cvt_pk_bf16_f32 v21, v16, v17
	global_store_dword v1, v21, s[24:25]
	s_add_u32 s24, s24, 0x2000
	s_addc_u32 s25, s25, 0
	v_lshlrev_b32_e32 v18, 16, v113
	v_and_b32_e32 v19, 0xffff0000, v113
	v_mul_f32_e32 v16, v16, v14
	v_mul_f32_e32 v17, v17, v14
	v_add_f32_e32 v16, v16, v18
	v_add_f32_e32 v17, v17, v19
	v_cvt_pk_bf16_f32 v20, v16, v17
	global_store_dword v1, v20, s[24:25]
	s_add_u32 s24, s24, 0x2000
	s_addc_u32 s25, s25, 0
	v_lshlrev_b32_e32 v18, 16, v114
	v_and_b32_e32 v19, 0xffff0000, v114
	v_mul_f32_e32 v16, v16, v14
	v_mul_f32_e32 v17, v17, v14
	v_add_f32_e32 v16, v16, v18
	v_add_f32_e32 v17, v17, v19
	v_cvt_pk_bf16_f32 v21, v16, v17
	global_store_dword v1, v21, s[24:25]
	s_add_u32 s24, s24, 0x2000
	s_addc_u32 s25, s25, 0
	v_lshlrev_b32_e32 v18, 16, v115
	v_and_b32_e32 v19, 0xffff0000, v115
	v_mul_f32_e32 v16, v16, v14
	v_mul_f32_e32 v17, v17, v14
	v_add_f32_e32 v16, v16, v18
	v_add_f32_e32 v17, v17, v19
	v_cvt_pk_bf16_f32 v20, v16, v17
	global_store_dword v1, v20, s[24:25]
	s_add_u32 s24, s24, 0x2000
	s_addc_u32 s25, s25, 0
	v_lshlrev_b32_e32 v18, 16, v116
	v_and_b32_e32 v19, 0xffff0000, v116
	v_mul_f32_e32 v16, v16, v14
	v_mul_f32_e32 v17, v17, v14
	v_add_f32_e32 v16, v16, v18
	v_add_f32_e32 v17, v17, v19
	v_cvt_pk_bf16_f32 v21, v16, v17
	global_store_dword v1, v21, s[24:25]
	s_add_u32 s24, s24, 0x2000
	s_addc_u32 s25, s25, 0
	v_lshlrev_b32_e32 v18, 16, v117
	v_and_b32_e32 v19, 0xffff0000, v117
	v_mul_f32_e32 v16, v16, v14
	v_mul_f32_e32 v17, v17, v14
	v_add_f32_e32 v16, v16, v18
	v_add_f32_e32 v17, v17, v19
	v_cvt_pk_bf16_f32 v20, v16, v17
	global_store_dword v1, v20, s[24:25]
	s_add_u32 s24, s24, 0x2000
	s_addc_u32 s25, s25, 0
	v_lshlrev_b32_e32 v18, 16, v118
	v_and_b32_e32 v19, 0xffff0000, v118
	v_mul_f32_e32 v16, v16, v14
	v_mul_f32_e32 v17, v17, v14
	v_add_f32_e32 v16, v16, v18
	v_add_f32_e32 v17, v17, v19
	v_cvt_pk_bf16_f32 v21, v16, v17
	global_store_dword v1, v21, s[24:25]
	s_add_u32 s24, s24, 0x2000
	s_addc_u32 s25, s25, 0
	v_lshlrev_b32_e32 v18, 16, v119
	v_and_b32_e32 v19, 0xffff0000, v119
	v_mul_f32_e32 v16, v16, v14
	v_mul_f32_e32 v17, v17, v14
	v_add_f32_e32 v16, v16, v18
	v_add_f32_e32 v17, v17, v19
	v_cvt_pk_bf16_f32 v20, v16, v17
	global_store_dword v1, v20, s[24:25]
	s_add_u32 s24, s24, 0x2000
	s_addc_u32 s25, s25, 0
	v_lshlrev_b32_e32 v18, 16, v120
	v_and_b32_e32 v19, 0xffff0000, v120
	v_mul_f32_e32 v16, v16, v14
	v_mul_f32_e32 v17, v17, v14
	v_add_f32_e32 v16, v16, v18
	v_add_f32_e32 v17, v17, v19
	v_cvt_pk_bf16_f32 v21, v16, v17
	global_store_dword v1, v21, s[24:25]
	s_add_u32 s24, s24, 0x2000
	s_addc_u32 s25, s25, 0
	v_lshlrev_b32_e32 v18, 16, v121
	v_and_b32_e32 v19, 0xffff0000, v121
	v_mul_f32_e32 v16, v16, v14
	v_mul_f32_e32 v17, v17, v14
	v_add_f32_e32 v16, v16, v18
	v_add_f32_e32 v17, v17, v19
	v_cvt_pk_bf16_f32 v20, v16, v17
	global_store_dword v1, v20, s[24:25]
	s_add_u32 s24, s24, 0x2000
	s_addc_u32 s25, s25, 0
	v_lshlrev_b32_e32 v18, 16, v122
	v_and_b32_e32 v19, 0xffff0000, v122
	v_mul_f32_e32 v16, v16, v14
	v_mul_f32_e32 v17, v17, v14
	v_add_f32_e32 v16, v16, v18
	v_add_f32_e32 v17, v17, v19
	v_cvt_pk_bf16_f32 v21, v16, v17
	global_store_dword v1, v21, s[24:25]
	s_add_u32 s24, s24, 0x2000
	s_addc_u32 s25, s25, 0
	v_lshlrev_b32_e32 v18, 16, v123
	v_and_b32_e32 v19, 0xffff0000, v123
	v_mul_f32_e32 v16, v16, v14
	v_mul_f32_e32 v17, v17, v14
	v_add_f32_e32 v16, v16, v18
	v_add_f32_e32 v17, v17, v19
	v_cvt_pk_bf16_f32 v20, v16, v17
	global_store_dword v1, v20, s[24:25]
	s_add_u32 s24, s24, 0x2000
	s_addc_u32 s25, s25, 0
	v_lshlrev_b32_e32 v18, 16, v124
	v_and_b32_e32 v19, 0xffff0000, v124
	v_mul_f32_e32 v16, v16, v14
	v_mul_f32_e32 v17, v17, v14
	v_add_f32_e32 v16, v16, v18
	v_add_f32_e32 v17, v17, v19
	v_cvt_pk_bf16_f32 v21, v16, v17
	global_store_dword v1, v21, s[24:25]
	s_add_u32 s24, s24, 0x2000
	s_addc_u32 s25, s25, 0
	v_lshlrev_b32_e32 v18, 16, v125
	v_and_b32_e32 v19, 0xffff0000, v125
	v_mul_f32_e32 v16, v16, v14
	v_mul_f32_e32 v17, v17, v14
	v_add_f32_e32 v16, v16, v18
	v_add_f32_e32 v17, v17, v19
	v_cvt_pk_bf16_f32 v20, v16, v17
	global_store_dword v1, v20, s[24:25]
	s_add_u32 s24, s24, 0x2000
	s_addc_u32 s25, s25, 0
	v_lshlrev_b32_e32 v18, 16, v126
	v_and_b32_e32 v19, 0xffff0000, v126
	v_mul_f32_e32 v16, v16, v14
	v_mul_f32_e32 v17, v17, v14
	v_add_f32_e32 v16, v16, v18
	v_add_f32_e32 v17, v17, v19
	v_cvt_pk_bf16_f32 v21, v16, v17
	global_store_dword v1, v21, s[24:25]
	s_add_u32 s24, s24, 0x2000
	s_addc_u32 s25, s25, 0
	v_lshlrev_b32_e32 v18, 16, v127
	v_and_b32_e32 v19, 0xffff0000, v127
	v_mul_f32_e32 v16, v16, v14
	v_mul_f32_e32 v17, v17, v14
	v_add_f32_e32 v16, v16, v18
	v_add_f32_e32 v17, v17, v19
	v_cvt_pk_bf16_f32 v20, v16, v17
	global_store_dword v1, v20, s[24:25]
	s_add_u32 s24, s24, 0x2000
	s_addc_u32 s25, s25, 0
	v_lshlrev_b32_e32 v18, 16, v131
	v_and_b32_e32 v19, 0xffff0000, v131
	v_mul_f32_e32 v16, v16, v14
	v_mul_f32_e32 v17, v17, v14
	v_add_f32_e32 v16, v16, v18
	v_add_f32_e32 v17, v17, v19
	v_cvt_pk_bf16_f32 v21, v16, v17
	global_store_dword v1, v21, s[24:25]
	s_add_u32 s24, s24, 0x2000
	s_addc_u32 s25, s25, 0
	v_lshlrev_b32_e32 v18, 16, v132
	v_and_b32_e32 v19, 0xffff0000, v132
	v_mul_f32_e32 v16, v16, v14
	v_mul_f32_e32 v17, v17, v14
	v_add_f32_e32 v16, v16, v18
	v_add_f32_e32 v17, v17, v19
	v_cvt_pk_bf16_f32 v20, v16, v17
	global_store_dword v1, v20, s[24:25]
	s_add_u32 s24, s24, 0x2000
	s_addc_u32 s25, s25, 0
	v_lshlrev_b32_e32 v18, 16, v133
	v_and_b32_e32 v19, 0xffff0000, v133
	v_mul_f32_e32 v16, v16, v14
	v_mul_f32_e32 v17, v17, v14
	v_add_f32_e32 v16, v16, v18
	v_add_f32_e32 v17, v17, v19
	v_cvt_pk_bf16_f32 v21, v16, v17
	global_store_dword v1, v21, s[24:25]
	s_add_u32 s24, s24, 0x2000
	s_addc_u32 s25, s25, 0
	v_lshlrev_b32_e32 v18, 16, v134
	v_and_b32_e32 v19, 0xffff0000, v134
	v_mul_f32_e32 v16, v16, v14
	v_mul_f32_e32 v17, v17, v14
	v_add_f32_e32 v16, v16, v18
	v_add_f32_e32 v17, v17, v19
	v_cvt_pk_bf16_f32 v20, v16, v17
	global_store_dword v1, v20, s[24:25]
	s_add_u32 s24, s24, 0x2000
	s_addc_u32 s25, s25, 0
	v_lshlrev_b32_e32 v18, 16, v135
	v_and_b32_e32 v19, 0xffff0000, v135
	v_mul_f32_e32 v16, v16, v14
	v_mul_f32_e32 v17, v17, v14
	v_add_f32_e32 v16, v16, v18
	v_add_f32_e32 v17, v17, v19
	v_cvt_pk_bf16_f32 v21, v16, v17
	global_store_dword v1, v21, s[24:25]
	s_add_u32 s24, s24, 0x2000
	s_addc_u32 s25, s25, 0
	v_lshlrev_b32_e32 v18, 16, v136
	v_and_b32_e32 v19, 0xffff0000, v136
	v_mul_f32_e32 v16, v16, v14
	v_mul_f32_e32 v17, v17, v14
	v_add_f32_e32 v16, v16, v18
	v_add_f32_e32 v17, v17, v19
	v_cvt_pk_bf16_f32 v20, v16, v17
	global_store_dword v1, v20, s[24:25]
	s_add_u32 s24, s24, 0x2000
	s_addc_u32 s25, s25, 0
	v_lshlrev_b32_e32 v18, 16, v137
	v_and_b32_e32 v19, 0xffff0000, v137
	v_mul_f32_e32 v16, v16, v14
	v_mul_f32_e32 v17, v17, v14
	v_add_f32_e32 v16, v16, v18
	v_add_f32_e32 v17, v17, v19
	v_cvt_pk_bf16_f32 v21, v16, v17
	global_store_dword v1, v21, s[24:25]
	s_add_u32 s24, s24, 0x2000
	s_addc_u32 s25, s25, 0
	v_lshlrev_b32_e32 v18, 16, v138
	v_and_b32_e32 v19, 0xffff0000, v138
	v_mul_f32_e32 v16, v16, v14
	v_mul_f32_e32 v17, v17, v14
	v_add_f32_e32 v16, v16, v18
	v_add_f32_e32 v17, v17, v19
	v_cvt_pk_bf16_f32 v20, v16, v17
	global_store_dword v1, v20, s[24:25]
	s_add_u32 s24, s24, 0x2000
	s_addc_u32 s25, s25, 0
	v_lshlrev_b32_e32 v18, 16, v139
	v_and_b32_e32 v19, 0xffff0000, v139
	v_mul_f32_e32 v16, v16, v14
	v_mul_f32_e32 v17, v17, v14
	v_add_f32_e32 v16, v16, v18
	v_add_f32_e32 v17, v17, v19
	v_cvt_pk_bf16_f32 v21, v16, v17
	global_store_dword v1, v21, s[24:25]
	s_add_u32 s24, s24, 0x2000
	s_addc_u32 s25, s25, 0
	v_lshlrev_b32_e32 v18, 16, v140
	v_and_b32_e32 v19, 0xffff0000, v140
	v_mul_f32_e32 v16, v16, v14
	v_mul_f32_e32 v17, v17, v14
	v_add_f32_e32 v16, v16, v18
	v_add_f32_e32 v17, v17, v19
	v_cvt_pk_bf16_f32 v20, v16, v17
	global_store_dword v1, v20, s[24:25]
	s_add_u32 s24, s24, 0x2000
	s_addc_u32 s25, s25, 0
	v_lshlrev_b32_e32 v18, 16, v141
	v_and_b32_e32 v19, 0xffff0000, v141
	v_mul_f32_e32 v16, v16, v14
	v_mul_f32_e32 v17, v17, v14
	v_add_f32_e32 v16, v16, v18
	v_add_f32_e32 v17, v17, v19
	v_cvt_pk_bf16_f32 v21, v16, v17
	global_store_dword v1, v21, s[24:25]
	s_add_u32 s24, s24, 0x2000
	s_addc_u32 s25, s25, 0
	v_lshlrev_b32_e32 v18, 16, v142
	v_and_b32_e32 v19, 0xffff0000, v142
	v_mul_f32_e32 v16, v16, v14
	v_mul_f32_e32 v17, v17, v14
	v_add_f32_e32 v16, v16, v18
	v_add_f32_e32 v17, v17, v19
	v_cvt_pk_bf16_f32 v20, v16, v17
	global_store_dword v1, v20, s[24:25]
	s_add_u32 s24, s24, 0x2000
	s_addc_u32 s25, s25, 0
	v_lshlrev_b32_e32 v18, 16, v143
	v_and_b32_e32 v19, 0xffff0000, v143
	v_mul_f32_e32 v16, v16, v14
	v_mul_f32_e32 v17, v17, v14
	v_add_f32_e32 v16, v16, v18
	v_add_f32_e32 v17, v17, v19
	v_cvt_pk_bf16_f32 v21, v16, v17
	global_store_dword v1, v21, s[24:25]
	s_add_u32 s24, s24, 0x2000
	s_addc_u32 s25, s25, 0
	v_lshlrev_b32_e32 v18, 16, v144
	v_and_b32_e32 v19, 0xffff0000, v144
	v_mul_f32_e32 v16, v16, v14
	v_mul_f32_e32 v17, v17, v14
	v_add_f32_e32 v16, v16, v18
	v_add_f32_e32 v17, v17, v19
	v_cvt_pk_bf16_f32 v20, v16, v17
	global_store_dword v1, v20, s[24:25]
	s_add_u32 s24, s24, 0x2000
	s_addc_u32 s25, s25, 0
	v_lshlrev_b32_e32 v18, 16, v145
	v_and_b32_e32 v19, 0xffff0000, v145
	v_mul_f32_e32 v16, v16, v14
	v_mul_f32_e32 v17, v17, v14
	v_add_f32_e32 v16, v16, v18
	v_add_f32_e32 v17, v17, v19
	v_cvt_pk_bf16_f32 v21, v16, v17
	global_store_dword v1, v21, s[24:25]
	s_add_u32 s24, s24, 0x2000
	s_addc_u32 s25, s25, 0
	v_lshlrev_b32_e32 v18, 16, v146
	v_and_b32_e32 v19, 0xffff0000, v146
	v_mul_f32_e32 v16, v16, v14
	v_mul_f32_e32 v17, v17, v14
	v_add_f32_e32 v16, v16, v18
	v_add_f32_e32 v17, v17, v19
	v_cvt_pk_bf16_f32 v20, v16, v17
	global_store_dword v1, v20, s[24:25]
	s_add_u32 s24, s24, 0x2000
	s_addc_u32 s25, s25, 0
	v_lshlrev_b32_e32 v18, 16, v147
	v_and_b32_e32 v19, 0xffff0000, v147
	v_mul_f32_e32 v16, v16, v14
	v_mul_f32_e32 v17, v17, v14
	v_add_f32_e32 v16, v16, v18
	v_add_f32_e32 v17, v17, v19
	v_cvt_pk_bf16_f32 v21, v16, v17
	global_store_dword v1, v21, s[24:25]
	s_add_u32 s24, s24, 0x2000
	s_addc_u32 s25, s25, 0
	v_lshlrev_b32_e32 v18, 16, v148
	v_and_b32_e32 v19, 0xffff0000, v148
	v_mul_f32_e32 v16, v16, v14
	v_mul_f32_e32 v17, v17, v14
	v_add_f32_e32 v16, v16, v18
	v_add_f32_e32 v17, v17, v19
	v_cvt_pk_bf16_f32 v20, v16, v17
	global_store_dword v1, v20, s[24:25]
	s_add_u32 s24, s24, 0x2000
	s_addc_u32 s25, s25, 0
	v_lshlrev_b32_e32 v18, 16, v149
	v_and_b32_e32 v19, 0xffff0000, v149
	v_mul_f32_e32 v16, v16, v14
	v_mul_f32_e32 v17, v17, v14
	v_add_f32_e32 v16, v16, v18
	v_add_f32_e32 v17, v17, v19
	v_cvt_pk_bf16_f32 v21, v16, v17
	global_store_dword v1, v21, s[24:25]
	s_add_u32 s24, s24, 0x2000
	s_addc_u32 s25, s25, 0
	v_lshlrev_b32_e32 v18, 16, v150
	v_and_b32_e32 v19, 0xffff0000, v150
	v_mul_f32_e32 v16, v16, v14
	v_mul_f32_e32 v17, v17, v14
	v_add_f32_e32 v16, v16, v18
	v_add_f32_e32 v17, v17, v19
	v_cvt_pk_bf16_f32 v20, v16, v17
	global_store_dword v1, v20, s[24:25]
	s_add_u32 s24, s24, 0x2000
	s_addc_u32 s25, s25, 0
	v_lshlrev_b32_e32 v18, 16, v151
	v_and_b32_e32 v19, 0xffff0000, v151
	v_mul_f32_e32 v16, v16, v14
	v_mul_f32_e32 v17, v17, v14
	v_add_f32_e32 v16, v16, v18
	v_add_f32_e32 v17, v17, v19
	v_cvt_pk_bf16_f32 v21, v16, v17
	global_store_dword v1, v21, s[24:25]
	s_add_u32 s24, s24, 0x2000
	s_addc_u32 s25, s25, 0
	v_lshlrev_b32_e32 v18, 16, v152
	v_and_b32_e32 v19, 0xffff0000, v152
	v_mul_f32_e32 v16, v16, v14
	v_mul_f32_e32 v17, v17, v14
	v_add_f32_e32 v16, v16, v18
	v_add_f32_e32 v17, v17, v19
	v_cvt_pk_bf16_f32 v20, v16, v17
	global_store_dword v1, v20, s[24:25]
	s_add_u32 s24, s24, 0x2000
	s_addc_u32 s25, s25, 0
	v_lshlrev_b32_e32 v18, 16, v153
	v_and_b32_e32 v19, 0xffff0000, v153
	v_mul_f32_e32 v16, v16, v14
	v_mul_f32_e32 v17, v17, v14
	v_add_f32_e32 v16, v16, v18
	v_add_f32_e32 v17, v17, v19
	v_cvt_pk_bf16_f32 v21, v16, v17
	global_store_dword v1, v21, s[24:25]
	s_add_u32 s24, s24, 0x2000
	s_addc_u32 s25, s25, 0
	v_lshlrev_b32_e32 v18, 16, v154
	v_and_b32_e32 v19, 0xffff0000, v154
	v_mul_f32_e32 v16, v16, v14
	v_mul_f32_e32 v17, v17, v14
	v_add_f32_e32 v16, v16, v18
	v_add_f32_e32 v17, v17, v19
	v_cvt_pk_bf16_f32 v20, v16, v17
	global_store_dword v1, v20, s[24:25]
	s_add_u32 s24, s24, 0x2000
	s_addc_u32 s25, s25, 0
	v_lshlrev_b32_e32 v18, 16, v155
	v_and_b32_e32 v19, 0xffff0000, v155
	v_mul_f32_e32 v16, v16, v14
	v_mul_f32_e32 v17, v17, v14
	v_add_f32_e32 v16, v16, v18
	v_add_f32_e32 v17, v17, v19
	v_cvt_pk_bf16_f32 v21, v16, v17
	global_store_dword v1, v21, s[24:25]
	s_add_u32 s24, s24, 0x2000
	s_addc_u32 s25, s25, 0
	v_lshlrev_b32_e32 v18, 16, v156
	v_and_b32_e32 v19, 0xffff0000, v156
	v_mul_f32_e32 v16, v16, v14
	v_mul_f32_e32 v17, v17, v14
	v_add_f32_e32 v16, v16, v18
	v_add_f32_e32 v17, v17, v19
	v_cvt_pk_bf16_f32 v20, v16, v17
	global_store_dword v1, v20, s[24:25]
	s_add_u32 s24, s24, 0x2000
	s_addc_u32 s25, s25, 0
	v_lshlrev_b32_e32 v18, 16, v157
	v_and_b32_e32 v19, 0xffff0000, v157
	v_mul_f32_e32 v16, v16, v14
	v_mul_f32_e32 v17, v17, v14
	v_add_f32_e32 v16, v16, v18
	v_add_f32_e32 v17, v17, v19
	v_cvt_pk_bf16_f32 v21, v16, v17
	global_store_dword v1, v21, s[24:25]
	s_add_u32 s24, s24, 0x2000
	s_addc_u32 s25, s25, 0
	v_lshlrev_b32_e32 v18, 16, v158
	v_and_b32_e32 v19, 0xffff0000, v158
	v_mul_f32_e32 v16, v16, v14
	v_mul_f32_e32 v17, v17, v14
	v_add_f32_e32 v16, v16, v18
	v_add_f32_e32 v17, v17, v19
	v_cvt_pk_bf16_f32 v20, v16, v17
	global_store_dword v1, v20, s[24:25]
	s_add_u32 s24, s24, 0x2000
	s_addc_u32 s25, s25, 0
	v_lshlrev_b32_e32 v18, 16, v159
	v_and_b32_e32 v19, 0xffff0000, v159
	v_mul_f32_e32 v16, v16, v14
	v_mul_f32_e32 v17, v17, v14
	v_add_f32_e32 v16, v16, v18
	v_add_f32_e32 v17, v17, v19
	v_cvt_pk_bf16_f32 v21, v16, v17
	global_store_dword v1, v21, s[24:25]
	s_add_u32 s24, s24, 0x2000
	s_addc_u32 s25, s25, 0
	v_lshlrev_b32_e32 v18, 16, v160
	v_and_b32_e32 v19, 0xffff0000, v160
	v_mul_f32_e32 v16, v16, v14
	v_mul_f32_e32 v17, v17, v14
	v_add_f32_e32 v16, v16, v18
	v_add_f32_e32 v17, v17, v19
	v_cvt_pk_bf16_f32 v20, v16, v17
	global_store_dword v1, v20, s[24:25]
	s_add_u32 s24, s24, 0x2000
	s_addc_u32 s25, s25, 0
	v_lshlrev_b32_e32 v18, 16, v164
	v_and_b32_e32 v19, 0xffff0000, v164
	v_mul_f32_e32 v16, v16, v14
	v_mul_f32_e32 v17, v17, v14
	v_add_f32_e32 v16, v16, v18
	v_add_f32_e32 v17, v17, v19
	v_cvt_pk_bf16_f32 v21, v16, v17
	global_store_dword v1, v21, s[24:25]
	s_add_u32 s24, s24, 0x2000
	s_addc_u32 s25, s25, 0
	v_lshlrev_b32_e32 v18, 16, v165
	v_and_b32_e32 v19, 0xffff0000, v165
	v_mul_f32_e32 v16, v16, v14
	v_mul_f32_e32 v17, v17, v14
	v_add_f32_e32 v16, v16, v18
	v_add_f32_e32 v17, v17, v19
	v_cvt_pk_bf16_f32 v20, v16, v17
	global_store_dword v1, v20, s[24:25]
	s_add_u32 s24, s24, 0x2000
	s_addc_u32 s25, s25, 0
	v_lshlrev_b32_e32 v18, 16, v166
	v_and_b32_e32 v19, 0xffff0000, v166
	v_mul_f32_e32 v16, v16, v14
	v_mul_f32_e32 v17, v17, v14
	v_add_f32_e32 v16, v16, v18
	v_add_f32_e32 v17, v17, v19
	v_cvt_pk_bf16_f32 v21, v16, v17
	global_store_dword v1, v21, s[24:25]
	s_add_u32 s24, s24, 0x2000
	s_addc_u32 s25, s25, 0
	v_lshlrev_b32_e32 v18, 16, v167
	v_and_b32_e32 v19, 0xffff0000, v167
	v_mul_f32_e32 v16, v16, v14
	v_mul_f32_e32 v17, v17, v14
	v_add_f32_e32 v16, v16, v18
	v_add_f32_e32 v17, v17, v19
	v_cvt_pk_bf16_f32 v20, v16, v17
	global_store_dword v1, v20, s[24:25]
	s_add_u32 s24, s24, 0x2000
	s_addc_u32 s25, s25, 0
	v_lshlrev_b32_e32 v18, 16, v168
	v_and_b32_e32 v19, 0xffff0000, v168
	v_mul_f32_e32 v16, v16, v14
	v_mul_f32_e32 v17, v17, v14
	v_add_f32_e32 v16, v16, v18
	v_add_f32_e32 v17, v17, v19
	v_cvt_pk_bf16_f32 v21, v16, v17
	global_store_dword v1, v21, s[24:25]
	s_add_u32 s24, s24, 0x2000
	s_addc_u32 s25, s25, 0
	v_lshlrev_b32_e32 v18, 16, v169
	v_and_b32_e32 v19, 0xffff0000, v169
	v_mul_f32_e32 v16, v16, v14
	v_mul_f32_e32 v17, v17, v14
	v_add_f32_e32 v16, v16, v18
	v_add_f32_e32 v17, v17, v19
	v_cvt_pk_bf16_f32 v20, v16, v17
	global_store_dword v1, v20, s[24:25]
	s_add_u32 s24, s24, 0x2000
	s_addc_u32 s25, s25, 0
	v_lshlrev_b32_e32 v18, 16, v170
	v_and_b32_e32 v19, 0xffff0000, v170
	v_mul_f32_e32 v16, v16, v14
	v_mul_f32_e32 v17, v17, v14
	v_add_f32_e32 v16, v16, v18
	v_add_f32_e32 v17, v17, v19
	v_cvt_pk_bf16_f32 v21, v16, v17
	global_store_dword v1, v21, s[24:25]
	s_add_u32 s24, s24, 0x2000
	s_addc_u32 s25, s25, 0
	v_lshlrev_b32_e32 v18, 16, v171
	v_and_b32_e32 v19, 0xffff0000, v171
	v_mul_f32_e32 v16, v16, v14
	v_mul_f32_e32 v17, v17, v14
	v_add_f32_e32 v16, v16, v18
	v_add_f32_e32 v17, v17, v19
	v_cvt_pk_bf16_f32 v20, v16, v17
	global_store_dword v1, v20, s[24:25]
	s_add_u32 s24, s24, 0x2000
	s_addc_u32 s25, s25, 0
	v_lshlrev_b32_e32 v18, 16, v172
	v_and_b32_e32 v19, 0xffff0000, v172
	v_mul_f32_e32 v16, v16, v14
	v_mul_f32_e32 v17, v17, v14
	v_add_f32_e32 v16, v16, v18
	v_add_f32_e32 v17, v17, v19
	v_cvt_pk_bf16_f32 v21, v16, v17
	global_store_dword v1, v21, s[24:25]
	s_add_u32 s24, s24, 0x2000
	s_addc_u32 s25, s25, 0
	v_lshlrev_b32_e32 v18, 16, v173
	v_and_b32_e32 v19, 0xffff0000, v173
	v_mul_f32_e32 v16, v16, v14
	v_mul_f32_e32 v17, v17, v14
	v_add_f32_e32 v16, v16, v18
	v_add_f32_e32 v17, v17, v19
	v_cvt_pk_bf16_f32 v20, v16, v17
	global_store_dword v1, v20, s[24:25]
	s_add_u32 s24, s24, 0x2000
	s_addc_u32 s25, s25, 0
	v_lshlrev_b32_e32 v18, 16, v174
	v_and_b32_e32 v19, 0xffff0000, v174
	v_mul_f32_e32 v16, v16, v14
	v_mul_f32_e32 v17, v17, v14
	v_add_f32_e32 v16, v16, v18
	v_add_f32_e32 v17, v17, v19
	v_cvt_pk_bf16_f32 v21, v16, v17
	global_store_dword v1, v21, s[24:25]
	s_add_u32 s24, s24, 0x2000
	s_addc_u32 s25, s25, 0
	v_lshlrev_b32_e32 v18, 16, v175
	v_and_b32_e32 v19, 0xffff0000, v175
	v_mul_f32_e32 v16, v16, v14
	v_mul_f32_e32 v17, v17, v14
	v_add_f32_e32 v16, v16, v18
	v_add_f32_e32 v17, v17, v19
	v_cvt_pk_bf16_f32 v20, v16, v17
	global_store_dword v1, v20, s[24:25]
	s_add_u32 s24, s24, 0x2000
	s_addc_u32 s25, s25, 0
	v_lshlrev_b32_e32 v18, 16, v198
	v_and_b32_e32 v19, 0xffff0000, v198
	v_mul_f32_e32 v16, v16, v14
	v_mul_f32_e32 v17, v17, v14
	v_add_f32_e32 v16, v16, v18
	v_add_f32_e32 v17, v17, v19
	v_cvt_pk_bf16_f32 v21, v16, v17
	global_store_dword v1, v21, s[24:25]
	s_add_u32 s24, s24, 0x2000
	s_addc_u32 s25, s25, 0
	v_lshlrev_b32_e32 v18, 16, v199
	v_and_b32_e32 v19, 0xffff0000, v199
	v_mul_f32_e32 v16, v16, v14
	v_mul_f32_e32 v17, v17, v14
	v_add_f32_e32 v16, v16, v18
	v_add_f32_e32 v17, v17, v19
	v_cvt_pk_bf16_f32 v20, v16, v17
	global_store_dword v1, v20, s[24:25]
	s_add_u32 s24, s24, 0x2000
	s_addc_u32 s25, s25, 0
	v_lshlrev_b32_e32 v18, 16, v200
	v_and_b32_e32 v19, 0xffff0000, v200
	v_mul_f32_e32 v16, v16, v14
	v_mul_f32_e32 v17, v17, v14
	v_add_f32_e32 v16, v16, v18
	v_add_f32_e32 v17, v17, v19
	v_cvt_pk_bf16_f32 v21, v16, v17
	global_store_dword v1, v21, s[24:25]
	s_add_u32 s24, s24, 0x2000
	s_addc_u32 s25, s25, 0
	v_lshlrev_b32_e32 v18, 16, v201
	v_and_b32_e32 v19, 0xffff0000, v201
	v_mul_f32_e32 v16, v16, v14
	v_mul_f32_e32 v17, v17, v14
	v_add_f32_e32 v16, v16, v18
	v_add_f32_e32 v17, v17, v19
	v_cvt_pk_bf16_f32 v20, v16, v17
	global_store_dword v1, v20, s[24:25]
	s_add_u32 s24, s24, 0x2000
	s_addc_u32 s25, s25, 0
	v_lshlrev_b32_e32 v18, 16, v202
	v_and_b32_e32 v19, 0xffff0000, v202
	v_mul_f32_e32 v16, v16, v14
	v_mul_f32_e32 v17, v17, v14
	v_add_f32_e32 v16, v16, v18
	v_add_f32_e32 v17, v17, v19
	v_cvt_pk_bf16_f32 v21, v16, v17
	global_store_dword v1, v21, s[24:25]
.Lscan_next:
	s_add_i32 s28, s28, s29
	s_branch .Lscan_loop
.Lscan_done:
.LBB0_953:
	s_and_b64 vcc, exec, s[20:21]
	s_cbranch_vccz .LBB0_995
	s_cmp_gt_i32 s66, 1
	s_mov_b64 s[18:19], -1
	s_cbranch_scc0 .LBB0_995
	s_cmp_gt_i32 s66, 2
	s_mov_b64 s[4:5], -1
	s_cbranch_scc0 .LBB0_1282
	v_readlane_b32 s0, v255, 8
	s_cmpk_gt_i32 s0, 0x41f
	s_cbranch_scc1 .LBB0_1068
	s_add_u32 s14, s46, 0xb7b8600
	s_addc_u32 s15, s47, 0
	s_add_u32 s18, s46, 0x30a4000
	s_addc_u32 s19, s47, 0
	s_add_u32 s20, s46, 0xb9c8600
	s_addc_u32 s21, s47, 0
	s_add_u32 s22, s46, 0x32a4000
	s_addc_u32 s23, s47, 0
	s_add_u32 s24, s46, 0x33ac000
	v_readlane_b32 s34, v255, 8
	s_addc_u32 s25, s47, 0
	s_lshl_b32 s0, s34, 1
	s_add_i32 s30, s65, s0
	v_readlane_b32 s0, v255, 9
	s_lshl_b32 s31, s0, 1
	s_branch .LBB0_959
